# kl3b: K-loops saddr DMA + ds_reads first + prio raised before M-entry barrier, no redundant waits; loop heads 64B-aligned
# baseline (speedup 1.0000x reference)
; template <class Epi, class Sched, bool ALIGN_EPI = false, bool SP2 = false>
; __device__ __forceinline__ void gemm_phase(PG8_LAS unsigned char* lds, const Gemm g, const Sched& S, const Epi& E) {
;     ...
;         const bool has_next = S.next(ui + 1, nxt);
;         const char* nA = has_next ? (const char*)g.A + (size_t)nxt.pm * tstep : cA; const char* nB = has_next ? (const char*)g.Bt + (size_t)nxt.pn * tstep : cB;
;         for (int t = 0; t < nt; t += 2) {
;             const bool last = (t == nt - 2);
;             const char* a1 = cA + (size_t)(t + 1) * kstep;
;             const char* a2 = last ? nA : cA + (size_t)(t + 2) * kstep; const char* b2 = last ? nB : cB + (size_t)(t + 2) * kstep;
;             const char* a3 = a2 + kstep; const char* b3 = b2 + kstep;
;     ...
; #pragma unroll
;         for (int a = 0; a < 2; ++a)
; #pragma unroll
;             for (int b = 0; b < 2; ++b)
; #pragma unroll
;                 for (int m = 0; m < 4; ++m)
; #pragma unroll
;                     for (int n = 0; n < 2; ++n) acc[a][b][m][n] = (f32x4){0.f, 0.f, 0.f, 0.f};
;         cur = nxt; cA = nA; cB = nB; ++ui; relax = Epi::LOADS_BEFORE_STORES && !Epi::AFTER_DRAIN && SP2;
.LBB0_147:
	s_ashr_i32 s21, s20, 31
	s_lshl_b64 s[24:25], s[20:21], 19
	s_add_u32 s24, s39, s24
	s_addc_u32 s25, s38, s25
	s_and_b64 s[26:27], s[22:23], exec
	s_cselect_b32 s21, s25, s1
	s_cselect_b32 s34, s24, s0
	s_ashr_i32 s19, s18, 31
	s_lshl_b64 s[26:27], s[18:19], 19
	s_add_u32 s26, s48, s26
	s_addc_u32 s27, s50, s27
	s_and_b64 s[30:31], s[22:23], exec
	s_cselect_b32 s19, s27, s29
	s_cselect_b32 s41, s26, s28
	s_add_u32 s30, s0, 0x40080
	s_addc_u32 s31, s1, 0
	s_add_u32 s58, s28, 0x100
	v_mov_b32_e32 v0, 0
	s_addc_u32 s59, s29, 0
	s_mov_b32 s60, -2
	s_mov_b64 vcc, 0
	v_mov_b32_e32 v1, v0
	v_mov_b32_e32 v2, v0
	v_mov_b32_e32 v3, v0
	v_mov_b32_e32 v4, v0
	v_mov_b32_e32 v5, v0
	v_mov_b32_e32 v6, v0
	v_mov_b32_e32 v7, v0
	v_mov_b32_e32 v16, v0
	v_mov_b32_e32 v17, v0
	v_mov_b32_e32 v18, v0
	v_mov_b32_e32 v19, v0
	v_mov_b32_e32 v20, v0
	v_mov_b32_e32 v21, v0
	v_mov_b32_e32 v22, v0
	v_mov_b32_e32 v23, v0
	v_mov_b32_e32 v32, v0
	v_mov_b32_e32 v33, v0
	v_mov_b32_e32 v34, v0
	v_mov_b32_e32 v35, v0
	v_mov_b32_e32 v36, v0
	v_mov_b32_e32 v37, v0
	v_mov_b32_e32 v38, v0
	v_mov_b32_e32 v39, v0
	v_mov_b32_e32 v48, v0
	v_mov_b32_e32 v49, v0
	v_mov_b32_e32 v50, v0
	v_mov_b32_e32 v51, v0
	v_mov_b32_e32 v52, v0
	v_mov_b32_e32 v53, v0
	v_mov_b32_e32 v54, v0
	v_mov_b32_e32 v55, v0
	v_mov_b32_e32 v8, v0
	v_mov_b32_e32 v9, v0
	v_mov_b32_e32 v10, v0
	v_mov_b32_e32 v11, v0
	v_mov_b32_e32 v12, v0
	v_mov_b32_e32 v13, v0
	v_mov_b32_e32 v14, v0
	v_mov_b32_e32 v15, v0
	v_mov_b32_e32 v24, v0
	v_mov_b32_e32 v25, v0
	v_mov_b32_e32 v26, v0
	v_mov_b32_e32 v27, v0
	v_mov_b32_e32 v28, v0
	v_mov_b32_e32 v29, v0
	v_mov_b32_e32 v30, v0
	v_mov_b32_e32 v31, v0
	v_mov_b32_e32 v40, v0
	v_mov_b32_e32 v41, v0
	v_mov_b32_e32 v42, v0
	v_mov_b32_e32 v43, v0
	v_mov_b32_e32 v44, v0
	v_mov_b32_e32 v45, v0
	v_mov_b32_e32 v46, v0
	v_mov_b32_e32 v47, v0
	v_mov_b32_e32 v56, v0
	v_mov_b32_e32 v57, v0
	v_mov_b32_e32 v58, v0
	v_mov_b32_e32 v59, v0
	v_mov_b32_e32 v60, v0
	v_mov_b32_e32 v61, v0
	v_mov_b32_e32 v62, v0
	v_mov_b32_e32 v63, v0
	v_mov_b32_e32 v64, v0
	v_mov_b32_e32 v65, v0
	v_mov_b32_e32 v66, v0
	v_mov_b32_e32 v67, v0
	v_mov_b32_e32 v68, v0
	v_mov_b32_e32 v69, v0
	v_mov_b32_e32 v70, v0
	v_mov_b32_e32 v71, v0
	v_mov_b32_e32 v80, v0
	v_mov_b32_e32 v81, v0
	v_mov_b32_e32 v82, v0
	v_mov_b32_e32 v83, v0
	v_mov_b32_e32 v84, v0
	v_mov_b32_e32 v85, v0
	v_mov_b32_e32 v86, v0
	v_mov_b32_e32 v87, v0
	v_mov_b32_e32 v96, v0
	v_mov_b32_e32 v97, v0
	v_mov_b32_e32 v98, v0
	v_mov_b32_e32 v99, v0
	v_mov_b32_e32 v100, v0
	v_mov_b32_e32 v101, v0
	v_mov_b32_e32 v102, v0
	v_mov_b32_e32 v103, v0
	v_mov_b32_e32 v112, v0
	v_mov_b32_e32 v113, v0
	v_mov_b32_e32 v114, v0
	v_mov_b32_e32 v115, v0
	v_mov_b32_e32 v116, v0
	v_mov_b32_e32 v117, v0
	v_mov_b32_e32 v118, v0
	v_mov_b32_e32 v119, v0
	v_mov_b32_e32 v72, v0
	v_mov_b32_e32 v73, v0
	v_mov_b32_e32 v74, v0
	v_mov_b32_e32 v75, v0
	v_mov_b32_e32 v76, v0
	v_mov_b32_e32 v77, v0
	v_mov_b32_e32 v78, v0
	v_mov_b32_e32 v79, v0
	v_mov_b32_e32 v88, v0
	v_mov_b32_e32 v89, v0
	v_mov_b32_e32 v90, v0
	v_mov_b32_e32 v91, v0
	v_mov_b32_e32 v92, v0
	v_mov_b32_e32 v93, v0
	v_mov_b32_e32 v94, v0
	v_mov_b32_e32 v95, v0
	v_mov_b32_e32 v104, v0
	v_mov_b32_e32 v105, v0
	v_mov_b32_e32 v106, v0
	v_mov_b32_e32 v107, v0
	v_mov_b32_e32 v108, v0
	v_mov_b32_e32 v109, v0
	v_mov_b32_e32 v110, v0
	v_mov_b32_e32 v111, v0
	v_mov_b32_e32 v120, v0
	v_mov_b32_e32 v121, v0
	v_mov_b32_e32 v122, v0
	v_mov_b32_e32 v123, v0
	v_mov_b32_e32 v124, v0
	v_mov_b32_e32 v125, v0
	v_mov_b32_e32 v126, v0
	v_mov_b32_e32 v127, v0
	v_lshl_add_u64 v[128:129], s[30:31], 0, v[140:141]
	v_lshl_add_u64 v[130:131], s[30:31], 0, v[142:143]
	.p2align	6

; #define PG8_STAGE(bufoff, gbase, voff) do { _Pragma("unroll") for (int _i = 0; _i < 2; ++_i) \
;         __builtin_amdgcn_global_load_lds((const unsigned*)((const char*)(gbase) + (voff)[_i]), (PG8_LAS unsigned*)(lds + (bufoff) + ldsw + _i * 8192), 16, 0, 0); } while (0)
; #define PG8_LDA(dst, b, h) do { _Pragma("unroll") for (int m = 0; m < 4; ++m) _Pragma("unroll") for (int k = 0; k < 2; ++k) dst[m][k] = *(const PG8_LAS bf16x8*)(lds + PG8_SA(b, h) + aoff + m * 2048 + k * 1024); } while (0)
; #define PG8_LDB(dst, b, h) do { _Pragma("unroll") for (int n = 0; n < 2; ++n) _Pragma("unroll") for (int k = 0; k < 2; ++k) dst[n][k] = *(const PG8_LAS bf16x8*)(lds + PG8_SB(b, h) + boff + n * 2048 + k * 1024); } while (0)
; #define PG8_MMA(ai, bj, At, Bt) do { __builtin_amdgcn_s_setprio(1); _Pragma("unroll") for (int m = 0; m < 4; ++m) _Pragma("unroll") for (int n = 0; n < 2; ++n) _Pragma("unroll") for (int k = 0; k < 2; ++k) \
;         acc[ai][bj][m][n] = __builtin_amdgcn_mfma_f32_16x16x32_bf16(Bt[n][k], At[m][k], acc[ai][bj][m][n], 0, 0, 0); __builtin_amdgcn_s_setprio(0); } while (0)
; #define PG8_WAIT_L(n) asm volatile("s_waitcnt lgkmcnt(" #n ")" ::: "memory")
; #define PG8_WAIT_V8_UNLESS(flag) asm volatile("s_cmp_lg_i32 %0, 0\n\ts_cbranch_scc1 .Lpg8rx%=\n\ts_waitcnt vmcnt(8)\n.Lpg8rx%=:" :: "s"(__builtin_amdgcn_readfirstlane(flag)) : "scc", "memory")
; #define PG8_BAR __builtin_amdgcn_s_barrier()
; #define PG8_SCHED __builtin_amdgcn_sched_barrier(0)
; template <class Epi, class Sched, bool ALIGN_EPI = false, bool SP2 = false>
; __device__ __forceinline__ void gemm_phase(PG8_LAS unsigned char* lds, const Gemm g, const Sched& S, const Epi& E) {
;     ...
;             PG8_STAGE(PG8_SA(1, 1), a1 + hstep, voffA); PG8_SCHED; PG8_LDB(B0, 0, 0); PG8_LDB(B1, 0, 1); PG8_SCHED; PG8_LDA(At, 0, 0);
;             PG8_WAIT_V8_UNLESS(rx); PG8_WAIT_L(0); PG8_BAR; PG8_MMA(0, 0, At, B0); PG8_MMA(0, 1, At, B1); PG8_BAR; PG8_SCHED;
;             PG8_STAGE(PG8_SB(0, 0), b2, voffB); PG8_STAGE(PG8_SB(0, 1), b2 + hstep, voffB); PG8_STAGE(PG8_SA(0, 0), a2, voffA); PG8_SCHED; PG8_LDA(At, 0, 1);
;             PG8_WAIT_V8_UNLESS(rx); PG8_WAIT_L(0); PG8_BAR; PG8_MMA(1, 0, At, B0); PG8_MMA(1, 1, At, B1); PG8_BAR; PG8_SCHED;
.Lpg8rx0:
	s_waitcnt lgkmcnt(0)
	s_setprio 1
	s_barrier
	v_mfma_f32_16x16x32_bf16 v[124:127], v[144:147], v[178:181], v[124:127]
	v_mfma_f32_16x16x32_bf16 v[120:123], v[152:155], v[178:181], v[120:123]
	v_mfma_f32_16x16x32_bf16 v[108:111], v[144:147], v[186:189], v[108:111]
	v_mfma_f32_16x16x32_bf16 v[104:107], v[152:155], v[186:189], v[104:107]
	v_mfma_f32_16x16x32_bf16 v[92:95], v[144:147], v[208:211], v[92:95]
	v_mfma_f32_16x16x32_bf16 v[88:91], v[152:155], v[208:211], v[88:91]
	v_mfma_f32_16x16x32_bf16 v[76:79], v[144:147], v[216:219], v[76:79]
	v_mfma_f32_16x16x32_bf16 v[72:75], v[152:155], v[216:219], v[72:75]
	v_mfma_f32_16x16x32_bf16 v[124:127], v[148:151], v[182:185], v[124:127]
	v_mfma_f32_16x16x32_bf16 v[120:123], v[156:159], v[182:185], v[120:123]
	v_mfma_f32_16x16x32_bf16 v[108:111], v[148:151], v[204:207], v[108:111]
	v_mfma_f32_16x16x32_bf16 v[104:107], v[156:159], v[204:207], v[104:107]
	v_mfma_f32_16x16x32_bf16 v[92:95], v[148:151], v[212:215], v[92:95]
	v_mfma_f32_16x16x32_bf16 v[88:91], v[156:159], v[212:215], v[88:91]
	v_mfma_f32_16x16x32_bf16 v[76:79], v[148:151], v[220:223], v[76:79]
	v_mfma_f32_16x16x32_bf16 v[72:75], v[156:159], v[220:223], v[72:75]
	v_mfma_f32_16x16x32_bf16 v[116:119], v[160:163], v[178:181], v[116:119]
	v_mfma_f32_16x16x32_bf16 v[112:115], v[168:171], v[178:181], v[112:115]
	v_mfma_f32_16x16x32_bf16 v[100:103], v[160:163], v[186:189], v[100:103]
	v_mfma_f32_16x16x32_bf16 v[96:99], v[168:171], v[186:189], v[96:99]
	v_mfma_f32_16x16x32_bf16 v[84:87], v[160:163], v[208:211], v[84:87]
	v_mfma_f32_16x16x32_bf16 v[80:83], v[168:171], v[208:211], v[80:83]
	v_mfma_f32_16x16x32_bf16 v[68:71], v[160:163], v[216:219], v[68:71]
	v_mfma_f32_16x16x32_bf16 v[64:67], v[168:171], v[216:219], v[64:67]
	v_mfma_f32_16x16x32_bf16 v[116:119], v[164:167], v[182:185], v[116:119]
	v_mfma_f32_16x16x32_bf16 v[112:115], v[174:177], v[182:185], v[112:115]
	v_mfma_f32_16x16x32_bf16 v[100:103], v[164:167], v[204:207], v[100:103]
	v_mfma_f32_16x16x32_bf16 v[96:99], v[174:177], v[204:207], v[96:99]
	v_mfma_f32_16x16x32_bf16 v[84:87], v[164:167], v[212:215], v[84:87]
	v_mfma_f32_16x16x32_bf16 v[80:83], v[174:177], v[212:215], v[80:83]
	v_mfma_f32_16x16x32_bf16 v[68:71], v[164:167], v[220:223], v[68:71]
	v_mfma_f32_16x16x32_bf16 v[64:67], v[174:177], v[220:223], v[64:67]
	s_setprio 0
	s_barrier
	ds_read_b128 v[178:181], v173 offset:16384
	ds_read_b128 v[182:185], v173 offset:17408
	ds_read_b128 v[186:189], v173 offset:18432
	ds_read_b128 v[204:207], v173 offset:19456
	ds_read_b128 v[208:211], v173 offset:20480
	ds_read_b128 v[212:215], v173 offset:21504
	ds_read_b128 v[216:219], v173 offset:22528
	ds_read_b128 v[220:223], v173 offset:23552
	s_add_u32 s66, s28, 0x40000
	s_addc_u32 s67, s29, 0
	s_add_i32 m0, s61, s46
	s_nop 0
	global_load_lds_dwordx4 v134, s[28:29]
	s_add_i32 m0, m0, 0x2000
	s_nop 0
	global_load_lds_dwordx4 v138, s[28:29]
	s_add_i32 m0, s65, s46
	s_nop 0
	global_load_lds_dwordx4 v134, s[66:67]
	s_add_i32 m0, m0, 0x2000
	s_nop 0
	global_load_lds_dwordx4 v138, s[66:67]
	s_mov_b32 m0, s9
	s_nop 0
	global_load_lds_dwordx4 v132, s[30:31]
	s_mov_b32 m0, s51
	s_nop 0
	global_load_lds_dwordx4 v136, s[30:31]
	s_cmp_lg_i32 s70, 0
	s_cbranch_scc1 .Lpg8rx1
	s_waitcnt vmcnt(8)
.Lpg8rx1:
	s_waitcnt lgkmcnt(0)
	s_setprio 1
	s_barrier
	v_mfma_f32_16x16x32_bf16 v[60:63], v[144:147], v[178:181], v[60:63]
	v_mfma_f32_16x16x32_bf16 v[56:59], v[152:155], v[178:181], v[56:59]
	v_mfma_f32_16x16x32_bf16 v[44:47], v[144:147], v[186:189], v[44:47]
	v_mfma_f32_16x16x32_bf16 v[40:43], v[152:155], v[186:189], v[40:43]
	v_mfma_f32_16x16x32_bf16 v[28:31], v[144:147], v[208:211], v[28:31]
	v_mfma_f32_16x16x32_bf16 v[24:27], v[152:155], v[208:211], v[24:27]
	v_mfma_f32_16x16x32_bf16 v[12:15], v[144:147], v[216:219], v[12:15]
	v_mfma_f32_16x16x32_bf16 v[8:11], v[152:155], v[216:219], v[8:11]
	v_mfma_f32_16x16x32_bf16 v[60:63], v[148:151], v[182:185], v[60:63]
	v_mfma_f32_16x16x32_bf16 v[56:59], v[156:159], v[182:185], v[56:59]
	v_mfma_f32_16x16x32_bf16 v[44:47], v[148:151], v[204:207], v[44:47]
	v_mfma_f32_16x16x32_bf16 v[40:43], v[156:159], v[204:207], v[40:43]
	v_mfma_f32_16x16x32_bf16 v[28:31], v[148:151], v[212:215], v[28:31]
	v_mfma_f32_16x16x32_bf16 v[24:27], v[156:159], v[212:215], v[24:27]
	v_mfma_f32_16x16x32_bf16 v[12:15], v[148:151], v[220:223], v[12:15]
	v_mfma_f32_16x16x32_bf16 v[8:11], v[156:159], v[220:223], v[8:11]
	v_mfma_f32_16x16x32_bf16 v[52:55], v[160:163], v[178:181], v[52:55]
	v_mfma_f32_16x16x32_bf16 v[48:51], v[168:171], v[178:181], v[48:51]
	v_mfma_f32_16x16x32_bf16 v[36:39], v[160:163], v[186:189], v[36:39]
	v_mfma_f32_16x16x32_bf16 v[32:35], v[168:171], v[186:189], v[32:35]
	v_mfma_f32_16x16x32_bf16 v[20:23], v[160:163], v[208:211], v[20:23]
	v_mfma_f32_16x16x32_bf16 v[16:19], v[168:171], v[208:211], v[16:19]
	v_mfma_f32_16x16x32_bf16 v[4:7], v[160:163], v[216:219], v[4:7]
	v_mfma_f32_16x16x32_bf16 v[0:3], v[168:171], v[216:219], v[0:3]
	v_mfma_f32_16x16x32_bf16 v[52:55], v[164:167], v[182:185], v[52:55]
	v_mfma_f32_16x16x32_bf16 v[48:51], v[174:177], v[182:185], v[48:51]
	v_mfma_f32_16x16x32_bf16 v[36:39], v[164:167], v[204:207], v[36:39]
	v_mfma_f32_16x16x32_bf16 v[32:35], v[174:177], v[204:207], v[32:35]
	v_mfma_f32_16x16x32_bf16 v[20:23], v[164:167], v[212:215], v[20:23]
	v_mfma_f32_16x16x32_bf16 v[16:19], v[174:177], v[212:215], v[16:19]
	v_mfma_f32_16x16x32_bf16 v[4:7], v[164:167], v[220:223], v[4:7]
	v_mfma_f32_16x16x32_bf16 v[0:3], v[174:177], v[220:223], v[0:3]
	s_setprio 0
	s_barrier
; #define PG8_STAGE(bufoff, gbase, voff) do { _Pragma("unroll") for (int _i = 0; _i < 2; ++_i) \
;         __builtin_amdgcn_global_load_lds((const unsigned*)((const char*)(gbase) + (voff)[_i]), (PG8_LAS unsigned*)(lds + (bufoff) + ldsw + _i * 8192), 16, 0, 0); } while (0)
; #define PG8_LDA(dst, b, h) do { _Pragma("unroll") for (int m = 0; m < 4; ++m) _Pragma("unroll") for (int k = 0; k < 2; ++k) dst[m][k] = *(const PG8_LAS bf16x8*)(lds + PG8_SA(b, h) + aoff + m * 2048 + k * 1024); } while (0)
; #define PG8_LDB(dst, b, h) do { _Pragma("unroll") for (int n = 0; n < 2; ++n) _Pragma("unroll") for (int k = 0; k < 2; ++k) dst[n][k] = *(const PG8_LAS bf16x8*)(lds + PG8_SB(b, h) + boff + n * 2048 + k * 1024); } while (0)
; #define PG8_MMA(ai, bj, At, Bt) do { __builtin_amdgcn_s_setprio(1); _Pragma("unroll") for (int m = 0; m < 4; ++m) _Pragma("unroll") for (int n = 0; n < 2; ++n) _Pragma("unroll") for (int k = 0; k < 2; ++k) \
;         acc[ai][bj][m][n] = __builtin_amdgcn_mfma_f32_16x16x32_bf16(Bt[n][k], At[m][k], acc[ai][bj][m][n], 0, 0, 0); __builtin_amdgcn_s_setprio(0); } while (0)
; #define PG8_WAIT_V(n) asm volatile("s_waitcnt vmcnt(" #n ")" ::: "memory")
; #define PG8_WAIT_L(n) asm volatile("s_waitcnt lgkmcnt(" #n ")" ::: "memory")
; #define PG8_BAR __builtin_amdgcn_s_barrier()
; #define PG8_SCHED __builtin_amdgcn_sched_barrier(0)
; template <class Epi, class Sched, bool ALIGN_EPI = false, bool SP2 = false>
; __device__ __forceinline__ void gemm_phase(PG8_LAS unsigned char* lds, const Gemm g, const Sched& S, const Epi& E) {
;     ...
;             PG8_STAGE(PG8_SA(0, 1), a2 + hstep, voffA); PG8_SCHED; PG8_LDB(B0, 1, 0); PG8_LDB(B1, 1, 1); PG8_SCHED; PG8_LDA(At, 1, 0);
;             PG8_WAIT_V(8); PG8_WAIT_L(0); PG8_BAR; PG8_MMA(0, 0, At, B0); PG8_MMA(0, 1, At, B1); PG8_BAR; PG8_SCHED;
;             PG8_STAGE(PG8_SB(1, 0), b3, voffB); PG8_STAGE(PG8_SB(1, 1), b3 + hstep, voffB); PG8_STAGE(PG8_SA(1, 0), a3, voffA); PG8_SCHED; PG8_LDA(At, 1, 1);
;             PG8_WAIT_V(8); PG8_WAIT_L(0); PG8_BAR; PG8_MMA(1, 0, At, B0); PG8_MMA(1, 1, At, B1); PG8_BAR; PG8_SCHED;
;     ...
;         if constexpr (ALIGN_EPI) { if (wr == 0) PG8_BAR; }
	s_mov_b64 s[98:99], s[30:31]
	s_add_u32 s100, s30, 0x40000
	s_addc_u32 s101, s31, 0
	s_add_i32 s30, 0, 0x18000
	s_add_i32 s31, 0, 0x1c000
	v_add_u32_e32 v156, s30, v172
	v_add_u32_e32 v174, s31, v172
	ds_read_b128 v[144:147], v156
	ds_read_b128 v[148:151], v156 offset:1024
	ds_read_b128 v[152:155], v156 offset:2048
	ds_read_b128 v[156:159], v156 offset:3072
	ds_read_b128 v[160:163], v174
	ds_read_b128 v[164:167], v174 offset:1024
	ds_read_b128 v[168:171], v174 offset:2048
	ds_read_b128 v[174:177], v174 offset:3072
	ds_read_b128 v[178:181], v173 offset:32768
	ds_read_b128 v[182:185], v173 offset:33792
	ds_read_b128 v[186:189], v173 offset:34816
	ds_read_b128 v[204:207], v173 offset:35840
	ds_read_b128 v[208:211], v173 offset:36864
	ds_read_b128 v[212:215], v173 offset:37888
	ds_read_b128 v[216:219], v173 offset:38912
	ds_read_b128 v[220:223], v173 offset:39936
	s_mov_b32 m0, s52
	s_nop 0
	global_load_lds_dwordx4 v132, s[100:101]
	s_mov_b32 m0, s53
	s_nop 0
	global_load_lds_dwordx4 v136, s[100:101]
	s_waitcnt vmcnt(8)
	s_waitcnt lgkmcnt(0)
	s_setprio 1
	s_barrier
	v_mfma_f32_16x16x32_bf16 v[124:127], v[144:147], v[178:181], v[124:127]
	v_mfma_f32_16x16x32_bf16 v[120:123], v[152:155], v[178:181], v[120:123]
	v_mfma_f32_16x16x32_bf16 v[108:111], v[144:147], v[186:189], v[108:111]
	v_mfma_f32_16x16x32_bf16 v[104:107], v[152:155], v[186:189], v[104:107]
	v_mfma_f32_16x16x32_bf16 v[92:95], v[144:147], v[208:211], v[92:95]
	v_mfma_f32_16x16x32_bf16 v[88:91], v[152:155], v[208:211], v[88:91]
	v_mfma_f32_16x16x32_bf16 v[76:79], v[144:147], v[216:219], v[76:79]
	v_mfma_f32_16x16x32_bf16 v[72:75], v[152:155], v[216:219], v[72:75]
	v_mfma_f32_16x16x32_bf16 v[124:127], v[148:151], v[182:185], v[124:127]
	v_mfma_f32_16x16x32_bf16 v[120:123], v[156:159], v[182:185], v[120:123]
	v_mfma_f32_16x16x32_bf16 v[108:111], v[148:151], v[204:207], v[108:111]
	v_mfma_f32_16x16x32_bf16 v[104:107], v[156:159], v[204:207], v[104:107]
	v_mfma_f32_16x16x32_bf16 v[92:95], v[148:151], v[212:215], v[92:95]
	v_mfma_f32_16x16x32_bf16 v[88:91], v[156:159], v[212:215], v[88:91]
	v_mfma_f32_16x16x32_bf16 v[76:79], v[148:151], v[220:223], v[76:79]
	v_mfma_f32_16x16x32_bf16 v[72:75], v[156:159], v[220:223], v[72:75]
	v_mfma_f32_16x16x32_bf16 v[116:119], v[160:163], v[178:181], v[116:119]
	v_mfma_f32_16x16x32_bf16 v[112:115], v[168:171], v[178:181], v[112:115]
	v_mfma_f32_16x16x32_bf16 v[100:103], v[160:163], v[186:189], v[100:103]
	v_mfma_f32_16x16x32_bf16 v[96:99], v[168:171], v[186:189], v[96:99]
	v_mfma_f32_16x16x32_bf16 v[84:87], v[160:163], v[208:211], v[84:87]
	v_mfma_f32_16x16x32_bf16 v[80:83], v[168:171], v[208:211], v[80:83]
	v_mfma_f32_16x16x32_bf16 v[68:71], v[160:163], v[216:219], v[68:71]
	v_mfma_f32_16x16x32_bf16 v[64:67], v[168:171], v[216:219], v[64:67]
	v_mfma_f32_16x16x32_bf16 v[116:119], v[164:167], v[182:185], v[116:119]
	v_mfma_f32_16x16x32_bf16 v[112:115], v[174:177], v[182:185], v[112:115]
	v_mfma_f32_16x16x32_bf16 v[100:103], v[164:167], v[204:207], v[100:103]
	v_mfma_f32_16x16x32_bf16 v[96:99], v[174:177], v[204:207], v[96:99]
	v_mfma_f32_16x16x32_bf16 v[84:87], v[164:167], v[212:215], v[84:87]
	v_mfma_f32_16x16x32_bf16 v[80:83], v[174:177], v[212:215], v[80:83]
	v_mfma_f32_16x16x32_bf16 v[68:71], v[164:167], v[220:223], v[68:71]
	v_mfma_f32_16x16x32_bf16 v[64:67], v[174:177], v[220:223], v[64:67]
	s_setprio 0
	s_barrier
	ds_read_b128 v[178:181], v173 offset:49152
	ds_read_b128 v[182:185], v173 offset:50176
	ds_read_b128 v[186:189], v173 offset:51200
	ds_read_b128 v[204:207], v173 offset:52224
	ds_read_b128 v[208:211], v173 offset:53248
	ds_read_b128 v[212:215], v173 offset:54272
	ds_read_b128 v[216:219], v173 offset:55296
	ds_read_b128 v[220:223], v173 offset:56320
	s_add_u32 s100, s28, 0x80
	s_addc_u32 s101, s29, 0
	s_add_u32 s28, s28, 0x40080
	s_addc_u32 s29, s29, 0
	s_add_u32 s98, s98, 0x80
	s_addc_u32 s99, s99, 0
	s_add_i32 m0, s30, s46
	s_nop 0
	global_load_lds_dwordx4 v134, s[100:101]
	s_add_i32 m0, m0, 0x2000
	s_nop 0
	global_load_lds_dwordx4 v138, s[100:101]
	s_add_i32 m0, s31, s46
	s_nop 0
	global_load_lds_dwordx4 v134, s[28:29]
	s_add_i32 m0, m0, 0x2000
	s_nop 0
	global_load_lds_dwordx4 v138, s[28:29]
	s_mov_b32 m0, s54
	s_nop 0
	global_load_lds_dwordx4 v132, s[98:99]
	s_mov_b32 m0, s55
	s_nop 0
	global_load_lds_dwordx4 v136, s[98:99]
	s_waitcnt vmcnt(8)
	s_waitcnt lgkmcnt(0)
	s_setprio 1
	s_barrier
	v_mfma_f32_16x16x32_bf16 v[60:63], v[144:147], v[178:181], v[60:63]
	v_mfma_f32_16x16x32_bf16 v[56:59], v[152:155], v[178:181], v[56:59]
	v_mfma_f32_16x16x32_bf16 v[44:47], v[144:147], v[186:189], v[44:47]
	v_mfma_f32_16x16x32_bf16 v[40:43], v[152:155], v[186:189], v[40:43]
	v_mfma_f32_16x16x32_bf16 v[28:31], v[144:147], v[208:211], v[28:31]
	v_mfma_f32_16x16x32_bf16 v[24:27], v[152:155], v[208:211], v[24:27]
	v_mfma_f32_16x16x32_bf16 v[12:15], v[144:147], v[216:219], v[12:15]
	v_mfma_f32_16x16x32_bf16 v[8:11], v[152:155], v[216:219], v[8:11]
	v_mfma_f32_16x16x32_bf16 v[60:63], v[148:151], v[182:185], v[60:63]
	v_mfma_f32_16x16x32_bf16 v[56:59], v[156:159], v[182:185], v[56:59]
	v_mfma_f32_16x16x32_bf16 v[44:47], v[148:151], v[204:207], v[44:47]
	v_mfma_f32_16x16x32_bf16 v[40:43], v[156:159], v[204:207], v[40:43]
	v_mfma_f32_16x16x32_bf16 v[28:31], v[148:151], v[212:215], v[28:31]
	v_mfma_f32_16x16x32_bf16 v[24:27], v[156:159], v[212:215], v[24:27]
	v_mfma_f32_16x16x32_bf16 v[12:15], v[148:151], v[220:223], v[12:15]
	v_mfma_f32_16x16x32_bf16 v[8:11], v[156:159], v[220:223], v[8:11]
	v_mfma_f32_16x16x32_bf16 v[52:55], v[160:163], v[178:181], v[52:55]
	v_mfma_f32_16x16x32_bf16 v[48:51], v[168:171], v[178:181], v[48:51]
	v_mfma_f32_16x16x32_bf16 v[36:39], v[160:163], v[186:189], v[36:39]
	v_mfma_f32_16x16x32_bf16 v[32:35], v[168:171], v[186:189], v[32:35]
	v_mfma_f32_16x16x32_bf16 v[20:23], v[160:163], v[208:211], v[20:23]
	v_mfma_f32_16x16x32_bf16 v[16:19], v[168:171], v[208:211], v[16:19]
	v_mfma_f32_16x16x32_bf16 v[4:7], v[160:163], v[216:219], v[4:7]
	v_mfma_f32_16x16x32_bf16 v[0:3], v[168:171], v[216:219], v[0:3]
	v_mfma_f32_16x16x32_bf16 v[52:55], v[164:167], v[182:185], v[52:55]
	v_mfma_f32_16x16x32_bf16 v[48:51], v[174:177], v[182:185], v[48:51]
	v_mfma_f32_16x16x32_bf16 v[36:39], v[164:167], v[204:207], v[36:39]
	v_mfma_f32_16x16x32_bf16 v[32:35], v[174:177], v[204:207], v[32:35]
	v_mfma_f32_16x16x32_bf16 v[20:23], v[164:167], v[212:215], v[20:23]
	v_mfma_f32_16x16x32_bf16 v[16:19], v[174:177], v[212:215], v[16:19]
	v_mfma_f32_16x16x32_bf16 v[4:7], v[164:167], v[220:223], v[4:7]
	v_mfma_f32_16x16x32_bf16 v[0:3], v[174:177], v[220:223], v[0:3]
	s_setprio 0
	s_barrier
	s_add_i32 s60, s60, 2
	s_add_u32 vcc_lo, vcc_lo, 0x100
	s_addc_u32 vcc_hi, vcc_hi, 0
	s_cmp_gt_u32 s60, 13
	s_cbranch_scc0 .LBB0_148
	.p2align	6
	s_and_b64 vcc, exec, s[62:63]
	s_cbranch_vccz .LBB0_151
	s_barrier

; #define WAIT_BAR(N) asm volatile("s_waitcnt vmcnt(" #N ") lgkmcnt(0)\n\ts_barrier":::"memory")
;   #define DMA_K(t,slot) glds16(ksrc+(long)(t)*KVBLK*PQ,(unsigned)__builtin_amdgcn_readfirstlane(kdst+(slot)))
;   #define DMA_V(t,slot) glds16(vsrc+(long)(t)*KVBLK*PQ,(unsigned)__builtin_amdgcn_readfirstlane(vdst+(slot)))
;   #define CMASK(P0,P1,t) do{int jb_=(t)-(NT-4); if(jb_>=0)cmask(P0,P1,jb_,qrel,hi);}while(0)
;   #define START(P0,P1) do{ const float rm=rowmax(P0,P1); resc=false; \
;     { const float dl=rm; mhat=fadd_s(mhat,dl); \
;       _Pragma("unroll") for(int r=0;r<16;++r){P0[r]=fsub_s(P0[r],dl);P1[r]=fsub_s(P1[r],dl);} \
;       _Pragma("unroll") for(int r=0;r<16;++r)negm[r]=-mhat; asm volatile("":"+v"(negm)); } \
;     _Pragma("unroll") for(int r=0;r<16;++r)P0[r]=__builtin_amdgcn_exp2f(P0[r]); }while(0)
;   #define ROT() do{sl_prev=sl_cur;sl_cur=sl_next;sl_next=(sl_next==(NSLOT-1)*SLOTB)?0:sl_next+SLOTB;}while(0)
;   #define CMASK(P0,P1,t) do{}while(0)
;   #define CMASK(P0,P1,t) do{int jb_=(t)-(NT-4); if(jb_>=0)cmask(P0,P1,jb_,qrel,hi);}while(0)
; #define WAIT_BAR(N) asm volatile("s_waitcnt vmcnt(" #N ") lgkmcnt(0)\n\ts_barrier":::"memory")
;   #define DMA_K(t,slot) glds16(ksrc+(long)(t)*4096,(unsigned)__builtin_amdgcn_readfirstlane(kdst+(slot)))
;   #define DMA_V(t,slot) do{ glds16(vsrc+(long)(t)*8192,(unsigned)__builtin_amdgcn_readfirstlane(vdst+2*(slot))); glds16(vsrc+(long)(t)*8192+4096,(unsigned)__builtin_amdgcn_readfirstlane(vdst+2*(slot)+8192)); }while(0)
;   #define QLD(d) (*(const __attribute__((address_space(3))) bf16x8*)(qp+(d)*1024))
;   #define CMASK(P0,P1,t) do{}while(0)
; template<int THRL> __device__ __forceinline__ void attn_unit128(int qb,const bf16*Qh,const bf16*__restrict__ Kh,const bf16*__restrict__ Vh,bf16*Oh,char*shm){
;     ...
;   f32x16 pA0,pA1,pB0,pB1;
;   int sl_prev=0,sl_cur=0,sl_next=KSLOT;
;     ...
;   DMA_K(2,2*KSLOT);
;   WAIT_BAR(1);
;   { bf16x8 q4[4];
;     #pragma unroll
;     for(int d0=0;d0<4;++d0)q4[d0]=QLD(d0);
;     qkt(pA0,pA1,Kbase,q4,zero16,r32,hi); }
;   asm volatile("s_nop 15\n\ts_nop 7":"+v"(pA0),"+v"(pA1));CMASK(pA0,pA1,0);
;   START(pA0,pA1);
;   _Pragma("unroll") for(int r=0;r<16;++r)pA1[r]=__builtin_amdgcn_exp2f(pA1[r]);
;   WAIT_BAR(0);
;   DMA_K(3,0);DMA_V(1,KSLOT);
;   ROT();
;   kload8(kf,kp0+sl_cur);
;   WAIT_BAR(3);
;   s16x4 vlo[16],vhi[16]; u32x4 pw0,pw1,pw2,pw3;
.LBB0_367:
	v_lshlrev_b32_e32 v35, 1, v34
	v_lshlrev_b32_e32 v215, 3, v34
	v_lshlrev_b32_e32 v34, 4, v34
	v_and_b32_e32 v218, 32, v35
	v_and_b32_e32 v34, 0xc0, v34
	v_and_b32_e32 v219, 24, v215
	v_lshl_or_b32 v217, v186, 8, v34
	v_add_u32_e32 v34, 0, v218
	v_add3_u32 v224, v34, v219, v217
	v_max3_f32 v34, v0, v1, v16
	v_max3_f32 v35, v2, v3, v17
	s_and_b32 s1, s1, 0x3fffffc0
	v_max3_f32 v34, v34, v18, v19
	v_max3_f32 v35, v35, v6, v7
	s_lshl_b32 s1, s1, 2
	v_max3_f32 v34, v34, v4, v5
	v_max3_f32 v35, v35, v22, v23
	s_add_i32 s34, s1, 0
	v_max3_f32 v34, v34, v20, v21
	v_max3_f32 v35, v35, v10, v11
	s_add_i32 s34, s34, 0x12000
	v_max3_f32 v34, v34, v8, v9
	v_max3_f32 v35, v35, v26, v27
	s_waitcnt vmcnt(0) lgkmcnt(0)
	s_barrier
	s_cmp_lg_u32 0, -1
	v_max3_f32 v34, v34, v24, v25
	v_max3_f32 v35, v35, v14, v15
	s_mov_b32 s72, 1
	v_max3_f32 v34, v34, v12, v13
	v_max3_f32 v35, v35, v30, v31
	s_mov_b32 s28, 0
	v_max3_f32 v34, v34, v28, v29
	v_lshlrev_b32_e32 v225, 4, v186
	v_max_f32_e32 v34, v34, v35
	v_lshl_add_u32 v216, v213, 2, s34
	v_mov_b32_e32 v35, v34
	s_nop 1
	v_permlane32_swap_b32_e32 v34, v35
	v_max_f32_e32 v34, v34, v35
	s_nop 0
	v_sub_f32_e32 v0, v0, v34
	v_sub_f32_e32 v1, v1, v34
	v_sub_f32_e32 v16, v16, v34
	v_sub_f32_e32 v17, v17, v34
	v_sub_f32_e32 v2, v2, v34
	v_sub_f32_e32 v18, v18, v34
	s_nop 0
	v_exp_f32_e32 v80, v0
	v_exp_f32_e32 v81, v1
	v_lshl_add_u64 v[0:1], v[180:181], 0, s[88:89]
	s_mov_b32 s1, m0
	s_mov_b32 m0, s42
	s_nop 0
	global_load_lds_dwordx4 v[0:1], off
	s_mov_b32 m0, s1
	s_cselect_b32 s1, 0, 0
	s_add_i32 s0, s1, s0
	v_lshl_add_u64 v[0:1], v[32:33], 0, s[86:87]
	s_add_i32 s1, s0, 0xa000
	s_mov_b32 s19, m0
	s_mov_b32 m0, s1
	s_nop 0
	global_load_lds_dwordx4 v[0:1], off
	s_mov_b32 m0, s19
	v_lshl_add_u64 v[0:1], v[32:33], 0, s[88:89]
	s_add_i32 s0, s0, 0xc000
	s_mov_b32 s1, m0
	s_mov_b32 m0, s0
	s_nop 0
	global_load_lds_dwordx4 v[0:1], off
	s_mov_b32 m0, s1
	ds_read_b128 v[168:171], v223 offset:8192
	ds_read_b128 v[160:163], v223 offset:8704
	ds_read_b128 v[172:175], v223 offset:10240
	ds_read_b128 v[156:159], v223 offset:10752
	ds_read_b128 v[164:167], v223 offset:12288
	ds_read_b128 v[148:151], v223 offset:12800
	ds_read_b128 v[152:155], v223 offset:14336
	ds_read_b128 v[144:147], v223 offset:14848
	v_sub_f32_e32 v3, v3, v34
	v_sub_f32_e32 v19, v19, v34
	v_sub_f32_e32 v4, v4, v34
	v_sub_f32_e32 v20, v20, v34
	v_sub_f32_e32 v5, v5, v34
	v_sub_f32_e32 v21, v21, v34
	v_sub_f32_e32 v6, v6, v34
	v_sub_f32_e32 v22, v22, v34
	v_sub_f32_e32 v7, v7, v34
	v_sub_f32_e32 v23, v23, v34
	v_sub_f32_e32 v8, v8, v34
	v_sub_f32_e32 v24, v24, v34
	v_sub_f32_e32 v9, v9, v34
	v_sub_f32_e32 v25, v25, v34
	v_sub_f32_e32 v10, v10, v34
	v_sub_f32_e32 v26, v26, v34
	v_sub_f32_e32 v11, v11, v34
	v_sub_f32_e32 v27, v27, v34
	v_sub_f32_e32 v12, v12, v34
	v_sub_f32_e32 v28, v28, v34
	v_sub_f32_e32 v13, v13, v34
	v_sub_f32_e32 v29, v29, v34
	v_sub_f32_e32 v14, v14, v34
	v_sub_f32_e32 v30, v30, v34
	v_sub_f32_e32 v15, v15, v34
	v_sub_f32_e32 v31, v31, v34
	v_exp_f32_e32 v82, v2
	v_exp_f32_e32 v83, v3
	v_exp_f32_e32 v84, v4
	v_exp_f32_e32 v85, v5
	v_exp_f32_e32 v86, v6
	v_exp_f32_e32 v87, v7
	v_exp_f32_e32 v88, v8
	v_exp_f32_e32 v89, v9
	v_exp_f32_e32 v90, v10
	v_exp_f32_e32 v91, v11
	v_exp_f32_e32 v92, v12
	v_exp_f32_e32 v93, v13
	v_exp_f32_e32 v94, v14
	v_exp_f32_e32 v95, v15
	v_exp_f32_e32 v64, v16
	v_exp_f32_e32 v65, v17
	v_exp_f32_e32 v66, v18
	v_exp_f32_e32 v67, v19
	v_exp_f32_e32 v68, v20
	v_exp_f32_e32 v69, v21
	v_exp_f32_e32 v70, v22
	v_exp_f32_e32 v71, v23
	v_exp_f32_e32 v72, v24
	v_exp_f32_e32 v73, v25
	v_exp_f32_e32 v74, v26
	v_exp_f32_e32 v75, v27
	v_exp_f32_e32 v76, v28
	v_exp_f32_e32 v77, v29
	v_exp_f32_e32 v78, v30
	v_exp_f32_e32 v79, v31
	s_waitcnt vmcnt(3) lgkmcnt(0)
	s_barrier
	s_andn2_b64 vcc, exec, s[16:17]
	v_cmp_gt_u32_e64 s[0:1], 32, v212
	v_add_f32_e32 v220, v195, v34
	s_cbranch_vccnz .LBB0_383
	s_add_u32 s20, s59, s24
	s_addc_u32 s21, s60, s25
	v_mov_b32_e32 v32, v195
	v_mov_b32_e32 v33, v195
	v_mov_b32_e32 v46, v195
	v_mov_b32_e32 v47, v195
	v_lshl_add_u64 v[182:183], s[20:21], 0, v[194:195]
	s_mov_b64 s[20:21], 0xa000
	v_mov_b32_e32 v34, v195
	v_mov_b32_e32 v35, v195
	v_mov_b32_e32 v36, v195
	v_mov_b32_e32 v37, v195
	v_mov_b32_e32 v38, v195
	v_mov_b32_e32 v39, v195
	v_mov_b32_e32 v40, v195
	v_mov_b32_e32 v41, v195
	v_mov_b32_e32 v42, v195
	v_mov_b32_e32 v43, v195
	v_mov_b32_e32 v44, v195
	v_mov_b32_e32 v45, v195
	v_mov_b64_e32 v[62:63], v[46:47]
	v_mov_b64_e32 v[16:17], v[32:33]
	v_mov_b64_e32 v[0:1], v[32:33]
	v_lshl_add_u64 v[184:185], v[180:181], 0, s[20:21]
	s_mov_b32 s20, 0
	s_movk_i32 s28, 0x4000
	s_movk_i32 s29, 0x2000
	v_mov_b32_e32 v226, 0
	s_mov_b32 s19, 6
	v_mov_b64_e32 v[60:61], v[44:45]
	v_mov_b64_e32 v[58:59], v[42:43]
	v_mov_b64_e32 v[56:57], v[40:41]
	v_mov_b64_e32 v[54:55], v[38:39]
	v_mov_b64_e32 v[52:53], v[36:37]
	v_mov_b64_e32 v[50:51], v[34:35]
	v_mov_b64_e32 v[48:49], v[32:33]
	v_mov_b64_e32 v[18:19], v[34:35]
	v_mov_b64_e32 v[20:21], v[36:37]
	v_mov_b64_e32 v[22:23], v[38:39]
	v_mov_b64_e32 v[24:25], v[40:41]
	v_mov_b64_e32 v[26:27], v[42:43]
	v_mov_b64_e32 v[28:29], v[44:45]
	v_mov_b64_e32 v[30:31], v[46:47]
	v_mov_b64_e32 v[2:3], v[34:35]
	v_mov_b64_e32 v[4:5], v[36:37]
	v_mov_b64_e32 v[6:7], v[38:39]
	v_mov_b64_e32 v[8:9], v[40:41]
	v_mov_b64_e32 v[10:11], v[42:43]
	v_mov_b64_e32 v[12:13], v[44:45]
	v_mov_b64_e32 v[14:15], v[46:47]
	.p2align	6
	s_nop 0
	s_nop 0

;   #define RESC() do{ if(resc){ asm volatile("s_waitcnt lgkmcnt(0)":::"memory"); \
;       _Pragma("unroll") for(int d_=0;d_<2;++d_) _Pragma("unroll") for(int r=0;r<16;++r)o[d_][r]*=wsf[crow(r,hi)]; } }while(0)
;   #define ROT() do{sl_prev=sl_cur;sl_cur=sl_next;sl_next=(sl_next==(NSLOT-1)*SLOTB)?0:sl_next+SLOTB;}while(0)
;   #define ENDW(tt) do{ if((tt)+3<NT){WAIT_BAR(2);} else if((tt)+2<NT){WAIT_BAR(1);} else {WAIT_BAR(0);} }while(0)
;   #define RESC() do{ if(resc){ asm volatile("s_waitcnt lgkmcnt(0)":::"memory"); \
;       _Pragma("unroll") for(int d_=0;d_<4;++d_) _Pragma("unroll") for(int r=0;r<16;++r)o[d_][r]*=wsf[crow(r,hi)]; } }while(0)
;   #define ROT() do{sl_prev=sl_cur;sl_cur=sl_next;sl_next=(sl_next==(NSLOT-1)*KSLOT)?0:sl_next+KSLOT;}while(0)
;   #define ENDW(tt) do{ if((tt)+3<NT){WAIT_BAR(3);} else if((tt)+2<NT){WAIT_BAR(2);} else {WAIT_BAR(0);} }while(0)
; template<int THRL> __device__ __forceinline__ void attn_unit128(int qb,const bf16*Qh,const bf16*__restrict__ Kh,const bf16*__restrict__ Vh,bf16*Oh,char*shm){
;     ...
;   for(;t+1<NT;t+=2){
;     STEP(pB0,pB1,pA0,pA1,t,(t+3<NT),(t+1<NT),(t+1<NT));       ENDW(t);   RESC(); ROT();
;     STEP(pA0,pA1,pB0,pB1,t+1,(t+4<NT),(t+2<NT),(t+2<NT));     ENDW(t+1); RESC(); ROT();
.LBB0_394:
.LBB0_395:
	s_lshl_b32 s22, s72, 6
	s_add_i32 s22, s48, s22
	v_add_u32_e32 v227, s22, v214
	s_add_i32 s30, s72, 2
	s_lshl_b64 s[22:23], s[72:73], 14
	s_add_u32 s24, s61, s24
	s_addc_u32 s25, s70, s25
	s_add_u32 s22, s24, s22
	s_addc_u32 s23, s25, s23
	v_lshl_add_u64 v[190:191], s[22:23], 0, v[194:195]
	s_lshl_b64 s[22:23], s[72:73], 13
	v_lshl_add_u64 v[96:97], v[180:181], 0, s[22:23]
	v_cmp_gt_u32_e64 s[0:1], 32, v212
	v_lshl_add_u64 v[204:205], v[96:97], 0, s[94:95]
	.p2align	6

; #define FIN(k) ((const float*)ptab(F.tab, (k)))
; __device__ __forceinline__ void lru_item(Frame& F, int l, int item) {
;     ...
;         for (int n = 0; n < 2; ++n) { const int ch = l * RW + g * 64 + hf * 32 + 16 * n + r; ba[n] = FIN(I_BGA)[ch]; bx[n] = FIN(I_BGX)[ch];
;             const float z = -FIN(I_LRULAM)[ch]; sp8[n] = 8.f * (fmaxf(z, 0.f) + log1pf(__expf(-fabsf(z)))); }
.LBB0_466:
	s_waitcnt vmcnt(3)
	v_max_f32_e64 v39, -v38, -v38
	v_mul_f32_e64 v38, |v38|, s46
	v_max_f32_e32 v41, 0, v39
	v_exp_f32_e32 v39, v38
	s_ashr_i32 s13, s12, 31
	s_lshl_b64 s[14:15], s[12:13], 15
	v_mov_b32_e32 v38, 1.0
	v_add_f32_e32 v50, 1.0, v39
	v_add_f32_e32 v40, -1.0, v50
	v_sub_f32_e32 v42, v40, v50
	v_add_f32_e32 v42, 1.0, v42
	v_sub_f32_e32 v40, v39, v40
	v_add_f32_e32 v51, v40, v42
	s_waitcnt vmcnt(0)
	v_max_f32_e64 v40, -v35, -v35
	v_mul_f32_e64 v35, |v35|, s46
	v_exp_f32_e32 v35, v35
	v_cvt_f64_f32_e32 v[42:43], v50
	v_frexp_exp_i32_f64_e32 v53, v[42:43]
	v_frexp_mant_f32_e32 v52, v50
	v_add_f32_e32 v61, 1.0, v35
	v_add_f32_e32 v42, -1.0, v61
	v_sub_f32_e32 v43, v42, v61
	v_add_f32_e32 v43, 1.0, v43
	v_sub_f32_e32 v42, v35, v42
	v_add_f32_e32 v62, v42, v43
	v_frexp_mant_f32_e32 v63, v61
	v_cvt_f64_f32_e32 v[42:43], v61
	v_cmp_gt_f32_e32 vcc, s48, v52
	v_frexp_exp_i32_f64_e32 v42, v[42:43]
	v_cmp_gt_f32_e64 s[0:1], s48, v63
	v_subbrev_co_u32_e32 v81, vcc, 0, v53, vcc
	s_nop 0
	v_subbrev_co_u32_e64 v80, s[0:1], 0, v42, s[0:1]
	v_sub_u32_e32 v42, 0, v81
	v_ldexp_f32 v43, v50, v42
	v_sub_u32_e32 v50, 0, v80
	v_ldexp_f32 v51, v51, v42
	v_ldexp_f32 v42, v61, v50
	v_pk_add_f32 v[52:53], v[42:43], 1.0 op_sel_hi:[1,0]
	v_ldexp_f32 v50, v62, v50
	v_pk_add_f32 v[62:63], v[52:53], -1.0 op_sel_hi:[1,0]
	v_pk_add_f32 v[68:69], v[42:43], -1.0 op_sel_hi:[1,0]
	v_pk_add_f32 v[62:63], v[42:43], v[62:63] neg_lo:[0,1] neg_hi:[0,1]
	v_pk_add_f32 v[70:71], v[68:69], 1.0 op_sel_hi:[1,0]
	v_pk_add_f32 v[62:63], v[50:51], v[62:63]
	v_pk_add_f32 v[42:43], v[42:43], v[70:71] neg_lo:[0,1] neg_hi:[0,1]
	v_pk_add_f32 v[64:65], v[52:53], v[62:63]
	v_pk_add_f32 v[42:43], v[50:51], v[42:43]
	v_rcp_f32_e32 v67, v65
	v_rcp_f32_e32 v66, v64
	v_pk_add_f32 v[50:51], v[68:69], v[42:43]
	v_pk_add_f32 v[52:53], v[64:65], v[52:53] neg_lo:[0,1] neg_hi:[0,1]
	v_pk_add_f32 v[68:69], v[50:51], v[68:69] neg_lo:[0,1] neg_hi:[0,1]
	v_pk_mul_f32 v[70:71], v[50:51], v[66:67]
	v_pk_add_f32 v[52:53], v[62:63], v[52:53] neg_lo:[0,1] neg_hi:[0,1]
	v_pk_mul_f32 v[62:63], v[64:65], v[70:71]
	v_pk_add_f32 v[42:43], v[42:43], v[68:69] neg_lo:[0,1] neg_hi:[0,1]
	v_pk_fma_f32 v[68:69], v[70:71], v[64:65], v[62:63] neg_lo:[0,0,1] neg_hi:[0,0,1]
	s_mov_b32 s0, 0x3e9b6dac
	v_pk_fma_f32 v[68:69], v[70:71], v[52:53], v[68:69]
	v_max_f32_e32 v40, 0, v40
	v_pk_add_f32 v[72:73], v[62:63], v[68:69]
	v_lshlrev_b32_e32 v194, 4, v32
	v_pk_add_f32 v[74:75], v[50:51], v[72:73] neg_lo:[0,1] neg_hi:[0,1]
	v_pk_add_f32 v[62:63], v[72:73], v[62:63] neg_lo:[0,1] neg_hi:[0,1]
	v_pk_add_f32 v[50:51], v[50:51], v[74:75] neg_lo:[0,1] neg_hi:[0,1]
	s_mov_b32 s13, 0
	v_pk_add_f32 v[50:51], v[50:51], v[72:73] neg_lo:[0,1] neg_hi:[0,1]
	s_nop 0
	v_pk_add_f32 v[42:43], v[42:43], v[50:51]
	v_pk_add_f32 v[50:51], v[62:63], v[68:69] neg_lo:[0,1] neg_hi:[0,1]
	s_nop 0
	v_pk_add_f32 v[42:43], v[50:51], v[42:43]
	s_nop 0
	v_pk_add_f32 v[50:51], v[74:75], v[42:43]
	s_nop 0
	v_pk_mul_f32 v[62:63], v[66:67], v[50:51]
	v_mov_b32_e32 v73, v51
	v_pk_mul_f32 v[68:69], v[64:65], v[62:63]
	v_pk_add_f32 v[74:75], v[74:75], v[50:51] neg_lo:[0,1] neg_hi:[0,1]
	v_pk_fma_f32 v[64:65], v[62:63], v[64:65], v[68:69] neg_lo:[0,0,1] neg_hi:[0,0,1]
	v_mov_b32_e32 v78, v69
	v_pk_fma_f32 v[52:53], v[62:63], v[52:53], v[64:65]
	v_pk_add_f32 v[42:43], v[42:43], v[74:75]
	v_pk_add_f32 v[64:65], v[68:69], v[52:53]
	s_nop 0
	v_pk_add_f32 v[76:77], v[50:51], v[64:65] neg_lo:[0,1] neg_hi:[0,1]
	v_mov_b32_e32 v72, v65
	v_mov_b32_e32 v79, v77
	v_pk_add_f32 v[72:73], v[72:73], v[78:79] neg_lo:[0,1] neg_hi:[0,1]
	v_mov_b32_e32 v78, v53
	v_mov_b32_e32 v79, v65
	v_pk_add_f32 v[50:51], v[50:51], v[76:77] neg_lo:[0,1] neg_hi:[0,1]
	v_pk_add_f32 v[72:73], v[72:73], v[78:79] neg_lo:[0,1] neg_hi:[0,1]
	v_pk_add_f32 v[50:51], v[50:51], v[64:65] neg_lo:[0,1] neg_hi:[0,1]
	v_pk_add_f32 v[68:69], v[64:65], v[68:69] neg_lo:[0,1] neg_hi:[0,1]
	v_mov_b32_e32 v51, v73
	v_pk_add_f32 v[42:43], v[42:43], v[50:51]
	v_pk_add_f32 v[50:51], v[68:69], v[52:53] neg_lo:[0,1] neg_hi:[0,1]
	v_pk_add_f32 v[78:79], v[70:71], v[62:63]
	v_mov_b32_e32 v51, v72
	v_pk_add_f32 v[42:43], v[50:51], v[42:43]
	v_pk_add_f32 v[50:51], v[78:79], v[70:71] neg_lo:[0,1] neg_hi:[0,1]
	v_pk_add_f32 v[42:43], v[76:77], v[42:43]
	v_pk_add_f32 v[50:51], v[62:63], v[50:51] neg_lo:[0,1] neg_hi:[0,1]
	v_pk_mul_f32 v[42:43], v[66:67], v[42:43]
	v_cvt_f32_i32_e32 v67, v81
	v_pk_add_f32 v[42:43], v[50:51], v[42:43]
	v_cvt_f32_i32_e32 v66, v80
	v_pk_add_f32 v[50:51], v[78:79], v[42:43]
	v_mul_u32_u24_e32 v80, 0x440, v33
	v_pk_mul_f32 v[62:63], v[50:51], v[50:51]
	v_pk_add_f32 v[52:53], v[50:51], v[78:79] neg_lo:[0,1] neg_hi:[0,1]
	v_pk_fma_f32 v[64:65], v[62:63], s[0:1], v[198:199] op_sel_hi:[1,0,0]
	s_mov_b32 s0, 0x3f2aaada
	v_pk_add_f32 v[42:43], v[42:43], v[52:53] neg_lo:[0,1] neg_hi:[0,1]
	v_ldexp_f32 v53, v51, 1
	v_pk_fma_f32 v[64:65], v[62:63], v[64:65], s[0:1] op_sel_hi:[1,1,0]
	v_ldexp_f32 v52, v50, 1
	v_pk_mul_f32 v[50:51], v[50:51], v[62:63]
	s_mov_b32 s0, 0x3f317218
	v_pk_mul_f32 v[50:51], v[50:51], v[64:65]
	v_pk_mul_f32 v[68:69], v[66:67], s[0:1] op_sel_hi:[1,0]
	v_pk_add_f32 v[62:63], v[52:53], v[50:51]
	v_ldexp_f32 v43, v43, 1
	v_pk_add_f32 v[52:53], v[62:63], v[52:53] neg_lo:[0,1] neg_hi:[0,1]
	v_pk_fma_f32 v[70:71], v[66:67], s[0:1], v[68:69] op_sel_hi:[1,0,1] neg_lo:[0,0,1] neg_hi:[0,0,1]
	s_mov_b32 s0, 0xb102e308
	v_ldexp_f32 v42, v42, 1
	v_pk_add_f32 v[50:51], v[50:51], v[52:53] neg_lo:[0,1] neg_hi:[0,1]
	v_pk_fma_f32 v[66:67], v[66:67], s[0:1], v[70:71] op_sel_hi:[1,0,1]
	v_pk_add_f32 v[42:43], v[42:43], v[50:51]
	v_pk_add_f32 v[70:71], v[68:69], v[66:67]
; __device__ __forceinline__ float bf2f(unsigned short v) { return __uint_as_float((unsigned)v << 16); }
; #define FIN(k) ((const float*)ptab(F.tab, (k)))
; __device__ __forceinline__ void lru_item(Frame& F, int l, int item) {
;     ...
;             const float z = -FIN(I_LRULAM)[ch]; sp8[n] = 8.f * (fmaxf(z, 0.f) + log1pf(__expf(-fabsf(z)))); }
;         const bf16* xcol = pj + 3 * AW + cch;
;         float h3 = 0.f, h2 = 0.f, h1 = 0.f;
;         if (t0 != 0) { h3 = bf2f(xcol[(size_t)(t0 - 3) * INW]); h2 = bf2f(xcol[(size_t)(t0 - 2) * INW]); h1 = bf2f(xcol[(size_t)(t0 - 1) * INW]); }
;         float hrun[2] = {0.f, 0.f}, Arun[2] = {1.f, 1.f};
;         unsigned short xq[16], xn[16];
; #pragma unroll
;         for (int tt = 0; tt < 16; ++tt) { xq[tt] = xcol[(size_t)(t0 + tt) * INW]; xn[tt] = xcol[(size_t)(t0 + 16 + tt) * INW]; }
	v_pk_add_f32 v[50:51], v[62:63], v[42:43]
	v_pk_add_f32 v[68:69], v[70:71], v[68:69] neg_lo:[0,1] neg_hi:[0,1]
	v_pk_add_f32 v[52:53], v[50:51], v[62:63] neg_lo:[0,1] neg_hi:[0,1]
	v_pk_add_f32 v[66:67], v[66:67], v[68:69] neg_lo:[0,1] neg_hi:[0,1]
	v_pk_add_f32 v[42:43], v[42:43], v[52:53] neg_lo:[0,1] neg_hi:[0,1]
	v_mov_b32_e32 v72, v51
	v_pk_add_f32 v[52:53], v[66:67], v[42:43]
	v_mov_b32_e32 v73, v71
	v_pk_add_f32 v[62:63], v[52:53], v[66:67] neg_lo:[0,1] neg_hi:[0,1]
	s_mov_b32 s0, 0x7f800000
	v_pk_add_f32 v[64:65], v[52:53], v[62:63] neg_lo:[0,1] neg_hi:[0,1]
	v_pk_add_f32 v[42:43], v[42:43], v[62:63] neg_lo:[0,1] neg_hi:[0,1]
	v_pk_add_f32 v[62:63], v[70:71], v[50:51]
	v_pk_add_f32 v[64:65], v[66:67], v[64:65] neg_lo:[0,1] neg_hi:[0,1]
	v_pk_add_f32 v[66:67], v[62:63], v[70:71] neg_lo:[0,1] neg_hi:[0,1]
	v_mov_b32_e32 v51, v70
	v_pk_add_f32 v[68:69], v[62:63], v[66:67] neg_lo:[0,1] neg_hi:[0,1]
	v_mov_b32_e32 v74, v67
	v_mov_b32_e32 v75, v69
	v_mov_b32_e32 v67, v68
	v_pk_add_f32 v[72:73], v[72:73], v[74:75] neg_lo:[0,1] neg_hi:[0,1]
	v_pk_add_f32 v[50:51], v[50:51], v[66:67] neg_lo:[0,1] neg_hi:[0,1]
	v_pk_add_f32 v[72:73], v[72:73], v[72:73] op_sel_hi:[0,1]
	v_pk_add_f32 v[50:51], v[50:51], v[50:51] op_sel:[0,1] op_sel_hi:[1,0]
	v_pk_add_f32 v[42:43], v[42:43], v[64:65]
	v_mov_b32_e32 v51, v53
	v_mov_b32_e32 v53, v73
	v_pk_add_f32 v[50:51], v[50:51], v[52:53]
	v_cmp_neq_f32_e32 vcc, s0, v35
	v_pk_add_f32 v[52:53], v[62:63], v[50:51]
	s_nop 0
	v_pk_add_f32 v[62:63], v[52:53], v[62:63] neg_lo:[0,1] neg_hi:[0,1]
	s_nop 0
	v_pk_add_f32 v[50:51], v[50:51], v[62:63] neg_lo:[0,1] neg_hi:[0,1]
	s_nop 0
	v_pk_add_f32 v[42:43], v[42:43], v[50:51]
	s_nop 0
	v_pk_add_f32 v[42:43], v[52:53], v[42:43]
	s_nop 0
	v_cndmask_b32_e32 v42, v245, v42, vcc
	v_cmp_neq_f32_e32 vcc, s0, v39
	s_mov_b32 s0, 0x33800000
	s_nop 0
	v_cndmask_b32_e32 v43, v245, v43, vcc
	v_cmp_ngt_f32_e32 vcc, -1.0, v39
	s_nop 1
	v_cndmask_b32_e32 v43, v246, v43, vcc
	v_cmp_ngt_f32_e32 vcc, -1.0, v35
	s_nop 1
	v_cndmask_b32_e32 v42, v246, v42, vcc
	v_cmp_neq_f32_e32 vcc, -1.0, v35
	s_nop 1
	v_cndmask_b32_e32 v42, v243, v42, vcc
	v_cmp_neq_f32_e32 vcc, -1.0, v39
	s_nop 1
	v_cndmask_b32_e32 v43, v243, v43, vcc
	v_cmp_lt_f32_e64 vcc, |v35|, s0
	v_cmp_lt_f32_e64 s[0:1], |v39|, s0
	s_nop 0
	v_cndmask_b32_e32 v42, v42, v35, vcc
	v_cndmask_b32_e64 v43, v43, v39, s[0:1]
	v_pk_add_f32 v[40:41], v[40:41], v[42:43]
	v_mad_i64_i32 v[42:43], s[28:29], s23, v244, v[36:37]
	s_or_b32 s1, s23, 16
	global_load_ushort v95, v[42:43], off offset:3072
	v_mad_i64_i32 v[42:43], s[28:29], s1, v244, v[36:37]
	s_or_b32 s1, s23, 1
	global_load_ushort v61, v[42:43], off offset:3072
	v_mad_i64_i32 v[42:43], s[28:29], s1, v244, v[36:37]
	s_or_b32 s1, s23, 17
	global_load_ushort v94, v[42:43], off offset:3072
	v_mad_i64_i32 v[42:43], s[28:29], s1, v244, v[36:37]
	s_or_b32 s1, s23, 2
	global_load_ushort v62, v[42:43], off offset:3072
	v_mad_i64_i32 v[42:43], s[28:29], s1, v244, v[36:37]
	s_or_b32 s1, s23, 18
	global_load_ushort v93, v[42:43], off offset:3072
	v_mad_i64_i32 v[42:43], s[28:29], s1, v244, v[36:37]
	s_or_b32 s1, s23, 3
	global_load_ushort v63, v[42:43], off offset:3072
	v_mad_i64_i32 v[42:43], s[28:29], s1, v244, v[36:37]
	s_or_b32 s1, s23, 19
	global_load_ushort v91, v[42:43], off offset:3072
	v_mad_i64_i32 v[42:43], s[28:29], s1, v244, v[36:37]
	s_or_b32 s1, s23, 4
	global_load_ushort v64, v[42:43], off offset:3072
	v_mad_i64_i32 v[42:43], s[28:29], s1, v244, v[36:37]
	s_or_b32 s1, s23, 20
	global_load_ushort v92, v[42:43], off offset:3072
	v_mad_i64_i32 v[42:43], s[28:29], s1, v244, v[36:37]
; __device__ __forceinline__ float bf2f(unsigned short v) { return __uint_as_float((unsigned)v << 16); }
; __device__ __forceinline__ void lru_item(Frame& F, int l, int item) {
;     ...
;         const bf16* xcol = pj + 3 * AW + cch;
;         float h3 = 0.f, h2 = 0.f, h1 = 0.f;
;         if (t0 != 0) { h3 = bf2f(xcol[(size_t)(t0 - 3) * INW]); h2 = bf2f(xcol[(size_t)(t0 - 2) * INW]); h1 = bf2f(xcol[(size_t)(t0 - 1) * INW]); }
;         float hrun[2] = {0.f, 0.f}, Arun[2] = {1.f, 1.f};
;         unsigned short xq[16], xn[16];
; #pragma unroll
;         for (int tt = 0; tt < 16; ++tt) { xq[tt] = xcol[(size_t)(t0 + tt) * INW]; xn[tt] = xcol[(size_t)(t0 + 16 + tt) * INW]; }
; #pragma unroll 1
;         for (int sc = 0; sc < 16; ++sc) {
	s_or_b32 s1, s23, 5
	global_load_ushort v65, v[42:43], off offset:3072
	v_mad_i64_i32 v[42:43], s[28:29], s1, v244, v[36:37]
	s_or_b32 s1, s23, 21
	global_load_ushort v90, v[42:43], off offset:3072
	v_mad_i64_i32 v[42:43], s[28:29], s1, v244, v[36:37]
	s_or_b32 s1, s23, 6
	global_load_ushort v66, v[42:43], off offset:3072
	v_mad_i64_i32 v[42:43], s[28:29], s1, v244, v[36:37]
	s_or_b32 s1, s23, 22
	global_load_ushort v89, v[42:43], off offset:3072
	v_mad_i64_i32 v[42:43], s[28:29], s1, v244, v[36:37]
	s_or_b32 s1, s23, 7
	global_load_ushort v67, v[42:43], off offset:3072
	v_mad_i64_i32 v[42:43], s[28:29], s1, v244, v[36:37]
	s_or_b32 s1, s23, 23
	global_load_ushort v87, v[42:43], off offset:3072
	v_mad_i64_i32 v[42:43], s[28:29], s1, v244, v[36:37]
	s_or_b32 s1, s23, 8
	global_load_ushort v68, v[42:43], off offset:3072
	v_mad_i64_i32 v[42:43], s[28:29], s1, v244, v[36:37]
	s_or_b32 s1, s23, 24
	global_load_ushort v88, v[42:43], off offset:3072
	v_mad_i64_i32 v[42:43], s[28:29], s1, v244, v[36:37]
	s_or_b32 s1, s23, 9
	global_load_ushort v69, v[42:43], off offset:3072
	v_mad_i64_i32 v[42:43], s[28:29], s1, v244, v[36:37]
	s_or_b32 s1, s23, 25
	global_load_ushort v86, v[42:43], off offset:3072
	v_mad_i64_i32 v[42:43], s[28:29], s1, v244, v[36:37]
	s_or_b32 s1, s23, 10
	global_load_ushort v70, v[42:43], off offset:3072
	v_mad_i64_i32 v[42:43], s[28:29], s1, v244, v[36:37]
	s_or_b32 s1, s23, 26
	global_load_ushort v111, v[42:43], off offset:3072
	v_mad_i64_i32 v[42:43], s[28:29], s1, v244, v[36:37]
	s_or_b32 s1, s23, 11
	global_load_ushort v71, v[42:43], off offset:3072
	v_mad_i64_i32 v[42:43], s[28:29], s1, v244, v[36:37]
	s_or_b32 s1, s23, 27
	global_load_ushort v109, v[42:43], off offset:3072
	v_mad_i64_i32 v[42:43], s[28:29], s1, v244, v[36:37]
	s_or_b32 s1, s23, 12
	global_load_ushort v72, v[42:43], off offset:3072
	v_mad_i64_i32 v[42:43], s[28:29], s1, v244, v[36:37]
	s_or_b32 s1, s23, 28
	global_load_ushort v110, v[42:43], off offset:3072
	v_mad_i64_i32 v[42:43], s[28:29], s1, v244, v[36:37]
	s_or_b32 s1, s23, 13
	global_load_ushort v73, v[42:43], off offset:3072
	v_mad_i64_i32 v[42:43], s[28:29], s1, v244, v[36:37]
	s_or_b32 s1, s23, 29
	global_load_ushort v108, v[42:43], off offset:3072
	v_mad_i64_i32 v[42:43], s[28:29], s1, v244, v[36:37]
	s_or_b32 s1, s23, 14
	global_load_ushort v74, v[42:43], off offset:3072
	v_mad_i64_i32 v[42:43], s[28:29], s1, v244, v[36:37]
	s_or_b32 s1, s23, 30
	global_load_ushort v106, v[42:43], off offset:3072
	v_mad_i64_i32 v[42:43], s[28:29], s1, v244, v[36:37]
	s_or_b32 s1, s23, 15
	global_load_ushort v75, v[42:43], off offset:3072
	v_mad_i64_i32 v[42:43], s[28:29], s1, v244, v[36:37]
	s_or_b32 s1, s23, 31
	global_load_ushort v107, v[42:43], off offset:3072
	v_mad_i64_i32 v[42:43], s[28:29], s1, v244, v[36:37]
	global_load_ushort v76, v[42:43], off offset:3072
	s_mul_i32 s0, s12, 0x1100
	s_add_i32 s0, s0, 0
	v_mov_b32_e32 v35, s0
	v_lshl_add_u32 v77, v32, 2, s0
	s_add_i32 s0, s0, s16
	s_movk_i32 s1, 0x110
	v_lshl_add_u32 v79, v44, 2, s0
	s_add_u32 s0, s21, s14
	v_mad_u32_u24 v35, v44, s1, v35
	s_addc_u32 s1, s22, s15
	v_or_b32_e32 v42, v44, v206
	s_add_u32 s0, s27, s0
	v_lshlrev_b32_e32 v39, 5, v33
	v_lshlrev_b32_e32 v50, 2, v42
	s_addc_u32 s1, s26, s1
	v_pk_mul_f32 v[40:41], v[40:41], s[92:93] op_sel_hi:[1,0]
	v_or_b32_e32 v51, 64, v50
	v_or_b32_e32 v52, 0x80, v50
	v_or_b32_e32 v53, 0xc0, v50
	v_lshl_add_u64 v[42:43], s[0:1], 0, v[194:195]
	v_add_u32_e32 v78, v35, v39
	v_add_u32_e32 v79, v79, v80
	s_mov_b32 s16, s23
	v_mov_b32_e32 v35, v34
	v_mov_b32_e32 v39, v38
	.p2align	6

; #define VM_WAIT() asm volatile("s_waitcnt vmcnt(0)" ::: "memory")
; __device__ __forceinline__ void lru_item(Frame& F, int l, int item) {
;     ...
;     {
;         VM_WAIT();
;         float hrun[2] = {hin[0], hin[1]};
;         v4u cur[2], nxt[2]; cur[0] = lb[0]; cur[1] = lb[64]; nxt[0] = lb[128]; nxt[1] = lb[192];
;         unsigned short gq[2][4];
; #pragma unroll
;         for (int n = 0; n < 2; ++n)
; #pragma unroll
;             for (int i = 0; i < 4; ++i) gq[n][i] = gcol[(size_t)(t0 + 4 * q + i) * INW + 16 * n];
; #pragma unroll 1
;         for (int sc = 0; sc < 16; ++sc) {
.LBB0_480:
	s_lshl_b64 s[10:11], s[10:11], 22
	s_add_u32 s10, s6, s10
	s_addc_u32 s11, s7, s11
	s_ashr_i32 s3, s2, 31
	s_lshl_b64 s[6:7], s[2:3], 18
	s_add_u32 s3, s27, s6
	s_addc_u32 s7, s26, s7
	s_add_u32 s6, s3, s14
	s_addc_u32 s7, s7, s15
	v_lshlrev_b32_e32 v194, 4, v32
	v_lshl_add_u64 v[0:1], s[6:7], 0, v[194:195]
	s_mov_b64 s[6:7], 0x7e00000
	s_lshl_b32 s3, s25, 1
	v_lshl_add_u64 v[26:27], v[0:1], 0, s[6:7]
	s_add_u32 s6, s10, s3
	s_addc_u32 s7, s11, 0
	s_lshl_b32 s10, s24, 1
	s_add_u32 s6, s6, s10
	s_addc_u32 s7, s7, 0
	s_add_u32 s3, s8, s3
	s_addc_u32 s9, s9, 0
	s_add_u32 s8, s3, s10
	s_addc_u32 s9, s9, 0
	v_lshlrev_b32_e32 v194, 1, v44
	v_lshlrev_b32_e32 v48, 2, v33
	v_lshl_add_u64 v[2:3], s[8:9], 0, v[194:195]
	s_mov_b64 s[8:9], 0x1000
	s_mov_b32 s3, 0x7e00000
	v_lshl_add_u64 v[28:29], v[2:3], 0, s[8:9]
	v_add_co_u32_e32 v4, vcc, s3, v0
	v_or_b32_e32 v22, s23, v48
	s_waitcnt vmcnt(0)
	s_nop 0
	v_addc_co_u32_e32 v5, vcc, 0, v1, vcc
	v_mad_i64_i32 v[16:17], s[8:9], v22, s45, v[28:29]
	v_or_b32_e32 v18, 1, v22
	v_or_b32_e32 v20, 2, v22
	v_or_b32_e32 v22, 3, v22
	global_load_dwordx4 v[8:11], v[26:27], off offset:1024
	global_load_dwordx4 v[0:3], v[26:27], off offset:2048
	global_load_dwordx4 v[12:15], v[4:5], off
	s_nop 0
	global_load_dwordx4 v[4:7], v[26:27], off offset:3072
	v_mad_i64_i32 v[18:19], s[8:9], v18, s45, v[28:29]
	v_mad_i64_i32 v[20:21], s[8:9], v20, s45, v[28:29]
	v_mad_i64_i32 v[22:23], s[8:9], v22, s45, v[28:29]
	global_load_ushort v34, v[16:17], off
	global_load_ushort v45, v[18:19], off
	global_load_ushort v43, v[20:21], off
	global_load_ushort v41, v[22:23], off
	global_load_ushort v54, v[22:23], off offset:32
	global_load_ushort v55, v[20:21], off offset:32
	global_load_ushort v56, v[18:19], off offset:32
	global_load_ushort v57, v[16:17], off offset:32
	v_lshl_add_u64 v[30:31], s[6:7], 0, v[194:195]
	s_mov_b32 s3, 0
	v_cmp_eq_u32_e32 vcc, 1, v33
	v_cmp_eq_u32_e64 s[40:41], 2, v33
	v_add_u32_e32 v49, s23, v48
	s_mov_b32 s6, 0
	s_mov_b32 s7, 0
	.p2align	6

; template <class Epi, class Sched, bool ALIGN_EPI = false, bool SP2 = false>
; __device__ __forceinline__ void gemm_phase(PG8_LAS unsigned char* lds, const Gemm g, const Sched& S, const Epi& E) {
;     ...
;         const bool has_next = S.next(ui + 1, nxt);
;         const char* nA = has_next ? (const char*)g.A + (size_t)nxt.pm * tstep : cA; const char* nB = has_next ? (const char*)g.Bt + (size_t)nxt.pn * tstep : cB;
;         for (int t = 0; t < nt; t += 2) {
;             const bool last = (t == nt - 2);
;             const char* a1 = cA + (size_t)(t + 1) * kstep;
;             const char* a2 = last ? nA : cA + (size_t)(t + 2) * kstep; const char* b2 = last ? nB : cB + (size_t)(t + 2) * kstep;
;             const char* a3 = a2 + kstep; const char* b3 = b2 + kstep;
;     ...
; #pragma unroll
;         for (int a = 0; a < 2; ++a)
; #pragma unroll
;             for (int b = 0; b < 2; ++b)
; #pragma unroll
;                 for (int m = 0; m < 4; ++m)
; #pragma unroll
;                     for (int n = 0; n < 2; ++n) acc[a][b][m][n] = (f32x4){0.f, 0.f, 0.f, 0.f};
;         cur = nxt; cA = nA; cB = nB; ++ui; relax = Epi::LOADS_BEFORE_STORES && !Epi::AFTER_DRAIN && SP2;
.LBB0_513:
	s_ashr_i32 s19, s18, 31
	s_lshl_b64 s[22:23], s[18:19], 19
	s_add_u32 s22, s4, s22
	s_addc_u32 s23, s5, s23
	s_and_b64 s[24:25], s[20:21], exec
	s_cselect_b32 s19, s23, s1
	s_cselect_b32 s27, s22, s0
	s_ashr_i32 s17, s16, 31
	s_lshl_b64 s[24:25], s[16:17], 19
	s_add_u32 s24, s37, s24
	s_addc_u32 s25, s38, s25
	s_and_b64 s[30:31], s[20:21], exec
	s_cselect_b32 s17, s25, s29
	s_cselect_b32 s55, s24, s28
	s_add_u32 s56, s28, 0x100
	s_addc_u32 s57, s29, 0
	s_add_u32 s28, s0, 0x40080
	s_addc_u32 s29, s1, 0
	v_mov_b32_e32 v0, 0
	v_lshl_add_u64 v[116:117], s[28:29], 0, v[210:211]
	v_lshl_add_u64 v[118:119], s[28:29], 0, v[212:213]
	s_mov_b32 s58, -2
	s_mov_b64 s[62:63], 0
	s_waitcnt lgkmcnt(0)
	v_mov_b32_e32 v1, v0
	v_mov_b32_e32 v2, v0
	v_mov_b32_e32 v3, v0
	v_mov_b32_e32 v4, v0
	v_mov_b32_e32 v5, v0
	v_mov_b32_e32 v6, v0
	v_mov_b32_e32 v7, v0
	v_mov_b32_e32 v16, v0
	v_mov_b32_e32 v17, v0
	v_mov_b32_e32 v18, v0
	v_mov_b32_e32 v19, v0
	v_mov_b32_e32 v20, v0
	v_mov_b32_e32 v21, v0
	v_mov_b32_e32 v22, v0
	v_mov_b32_e32 v23, v0
	v_mov_b32_e32 v32, v0
	v_mov_b32_e32 v33, v0
	v_mov_b32_e32 v34, v0
	v_mov_b32_e32 v35, v0
	v_mov_b32_e32 v36, v0
	v_mov_b32_e32 v37, v0
	v_mov_b32_e32 v38, v0
	v_mov_b32_e32 v39, v0
	v_mov_b32_e32 v48, v0
	v_mov_b32_e32 v49, v0
	v_mov_b32_e32 v50, v0
	v_mov_b32_e32 v51, v0
	v_mov_b32_e32 v52, v0
	v_mov_b32_e32 v53, v0
	v_mov_b32_e32 v54, v0
	v_mov_b32_e32 v55, v0
	v_mov_b32_e32 v8, v0
	v_mov_b32_e32 v9, v0
	v_mov_b32_e32 v10, v0
	v_mov_b32_e32 v11, v0
	v_mov_b32_e32 v12, v0
	v_mov_b32_e32 v13, v0
	v_mov_b32_e32 v14, v0
	v_mov_b32_e32 v15, v0
	v_mov_b32_e32 v24, v0
	v_mov_b32_e32 v25, v0
	v_mov_b32_e32 v26, v0
	v_mov_b32_e32 v27, v0
	v_mov_b32_e32 v28, v0
	v_mov_b32_e32 v29, v0
	v_mov_b32_e32 v30, v0
	v_mov_b32_e32 v31, v0
	v_mov_b32_e32 v40, v0
	v_mov_b32_e32 v41, v0
	v_mov_b32_e32 v42, v0
	v_mov_b32_e32 v43, v0
	v_mov_b32_e32 v44, v0
	v_mov_b32_e32 v45, v0
	v_mov_b32_e32 v46, v0
	v_mov_b32_e32 v47, v0
	v_mov_b32_e32 v56, v0
	v_mov_b32_e32 v57, v0
	v_mov_b32_e32 v58, v0
	v_mov_b32_e32 v59, v0
	v_mov_b32_e32 v60, v0
	v_mov_b32_e32 v61, v0
	v_mov_b32_e32 v62, v0
	v_mov_b32_e32 v63, v0
	v_mov_b32_e32 v64, v0
	v_mov_b32_e32 v65, v0
	v_mov_b32_e32 v66, v0
	v_mov_b32_e32 v67, v0
	v_mov_b32_e32 v68, v0
	v_mov_b32_e32 v69, v0
	v_mov_b32_e32 v70, v0
	v_mov_b32_e32 v71, v0
	v_mov_b32_e32 v80, v0
	v_mov_b32_e32 v81, v0
	v_mov_b32_e32 v82, v0
	v_mov_b32_e32 v83, v0
	v_mov_b32_e32 v84, v0
	v_mov_b32_e32 v85, v0
	v_mov_b32_e32 v86, v0
	v_mov_b32_e32 v87, v0
	v_mov_b32_e32 v96, v0
	v_mov_b32_e32 v97, v0
	v_mov_b32_e32 v98, v0
	v_mov_b32_e32 v99, v0
	v_mov_b32_e32 v100, v0
	v_mov_b32_e32 v101, v0
	v_mov_b32_e32 v102, v0
	v_mov_b32_e32 v103, v0
	v_mov_b32_e32 v112, v0
	v_mov_b32_e32 v113, v0
	v_mov_b32_e32 v114, v0
	v_mov_b32_e32 v115, v0
	v_mov_b32_e32 v124, v0
	v_mov_b32_e32 v125, v0
	v_mov_b32_e32 v126, v0
	v_mov_b32_e32 v127, v0
	v_mov_b32_e32 v72, v0
	v_mov_b32_e32 v73, v0
	v_mov_b32_e32 v74, v0
	v_mov_b32_e32 v75, v0
	v_mov_b32_e32 v76, v0
	v_mov_b32_e32 v77, v0
	v_mov_b32_e32 v78, v0
	v_mov_b32_e32 v79, v0
	v_mov_b32_e32 v88, v0
	v_mov_b32_e32 v89, v0
	v_mov_b32_e32 v90, v0
	v_mov_b32_e32 v91, v0
	v_mov_b32_e32 v92, v0
	v_mov_b32_e32 v93, v0
	v_mov_b32_e32 v94, v0
	v_mov_b32_e32 v95, v0
	v_mov_b32_e32 v104, v0
	v_mov_b32_e32 v105, v0
	v_mov_b32_e32 v106, v0
	v_mov_b32_e32 v107, v0
	v_mov_b32_e32 v108, v0
	v_mov_b32_e32 v109, v0
	v_mov_b32_e32 v110, v0
	v_mov_b32_e32 v111, v0
	v_mov_b32_e32 v148, v0
	v_mov_b32_e32 v149, v0
	v_mov_b32_e32 v150, v0
	v_mov_b32_e32 v151, v0
	v_mov_b32_e32 v152, v0
	v_mov_b32_e32 v153, v0
	v_mov_b32_e32 v154, v0
	v_mov_b32_e32 v155, v0
	.p2align	6

; #define PG8_STAGE(bufoff, gbase, voff) do { _Pragma("unroll") for (int _i = 0; _i < 2; ++_i) \
;         __builtin_amdgcn_global_load_lds((const unsigned*)((const char*)(gbase) + (voff)[_i]), (PG8_LAS unsigned*)(lds + (bufoff) + ldsw + _i * 8192), 16, 0, 0); } while (0)
; #define PG8_LDA(dst, b, h) do { _Pragma("unroll") for (int m = 0; m < 4; ++m) _Pragma("unroll") for (int k = 0; k < 2; ++k) dst[m][k] = *(const PG8_LAS bf16x8*)(lds + PG8_SA(b, h) + aoff + m * 2048 + k * 1024); } while (0)
; #define PG8_LDB(dst, b, h) do { _Pragma("unroll") for (int n = 0; n < 2; ++n) _Pragma("unroll") for (int k = 0; k < 2; ++k) dst[n][k] = *(const PG8_LAS bf16x8*)(lds + PG8_SB(b, h) + boff + n * 2048 + k * 1024); } while (0)
; #define PG8_MMA(ai, bj, At, Bt) do { __builtin_amdgcn_s_setprio(1); _Pragma("unroll") for (int m = 0; m < 4; ++m) _Pragma("unroll") for (int n = 0; n < 2; ++n) _Pragma("unroll") for (int k = 0; k < 2; ++k) \
;         acc[ai][bj][m][n] = __builtin_amdgcn_mfma_f32_16x16x32_bf16(Bt[n][k], At[m][k], acc[ai][bj][m][n], 0, 0, 0); __builtin_amdgcn_s_setprio(0); } while (0)
; #define PG8_WAIT_L(n) asm volatile("s_waitcnt lgkmcnt(" #n ")" ::: "memory")
; #define PG8_WAIT_V8_UNLESS(flag) asm volatile("s_cmp_lg_i32 %0, 0\n\ts_cbranch_scc1 .Lpg8rx%=\n\ts_waitcnt vmcnt(8)\n.Lpg8rx%=:" :: "s"(__builtin_amdgcn_readfirstlane(flag)) : "scc", "memory")
; #define PG8_BAR __builtin_amdgcn_s_barrier()
; #define PG8_SCHED __builtin_amdgcn_sched_barrier(0)
; template <class Epi, class Sched, bool ALIGN_EPI = false, bool SP2 = false>
; __device__ __forceinline__ void gemm_phase(PG8_LAS unsigned char* lds, const Gemm g, const Sched& S, const Epi& E) {
;     ...
;             PG8_STAGE(PG8_SA(1, 1), a1 + hstep, voffA); PG8_SCHED; PG8_LDB(B0, 0, 0); PG8_LDB(B1, 0, 1); PG8_SCHED; PG8_LDA(At, 0, 0);
;             PG8_WAIT_V8_UNLESS(rx); PG8_WAIT_L(0); PG8_BAR; PG8_MMA(0, 0, At, B0); PG8_MMA(0, 1, At, B1); PG8_BAR; PG8_SCHED;
;             PG8_STAGE(PG8_SB(0, 0), b2, voffB); PG8_STAGE(PG8_SB(0, 1), b2 + hstep, voffB); PG8_STAGE(PG8_SA(0, 0), a2, voffA); PG8_SCHED; PG8_LDA(At, 0, 1);
;             PG8_WAIT_V8_UNLESS(rx); PG8_WAIT_L(0); PG8_BAR; PG8_MMA(1, 0, At, B0); PG8_MMA(1, 1, At, B1); PG8_BAR; PG8_SCHED;
.Lpg8rx2:
	s_waitcnt lgkmcnt(0)
	s_setprio 1
	s_barrier
	v_mfma_f32_16x16x32_bf16 v[152:155], v[120:123], v[164:167], v[152:155]
	v_mfma_f32_16x16x32_bf16 v[148:151], v[132:135], v[164:167], v[148:151]
	v_mfma_f32_16x16x32_bf16 v[108:111], v[120:123], v[172:175], v[108:111]
	v_mfma_f32_16x16x32_bf16 v[104:107], v[132:135], v[172:175], v[104:107]
	v_mfma_f32_16x16x32_bf16 v[92:95], v[120:123], v[180:183], v[92:95]
	v_mfma_f32_16x16x32_bf16 v[88:91], v[132:135], v[180:183], v[88:91]
	v_mfma_f32_16x16x32_bf16 v[76:79], v[120:123], v[188:191], v[76:79]
	v_mfma_f32_16x16x32_bf16 v[72:75], v[132:135], v[188:191], v[72:75]
	v_mfma_f32_16x16x32_bf16 v[152:155], v[128:131], v[168:171], v[152:155]
	v_mfma_f32_16x16x32_bf16 v[148:151], v[136:139], v[168:171], v[148:151]
	v_mfma_f32_16x16x32_bf16 v[108:111], v[128:131], v[176:179], v[108:111]
	v_mfma_f32_16x16x32_bf16 v[104:107], v[136:139], v[176:179], v[104:107]
	v_mfma_f32_16x16x32_bf16 v[92:95], v[128:131], v[184:187], v[92:95]
	v_mfma_f32_16x16x32_bf16 v[88:91], v[136:139], v[184:187], v[88:91]
	v_mfma_f32_16x16x32_bf16 v[76:79], v[128:131], v[214:217], v[76:79]
	v_mfma_f32_16x16x32_bf16 v[72:75], v[136:139], v[214:217], v[72:75]
	v_mfma_f32_16x16x32_bf16 v[124:127], v[140:143], v[164:167], v[124:127]
	v_mfma_f32_16x16x32_bf16 v[112:115], v[156:159], v[164:167], v[112:115]
	v_mfma_f32_16x16x32_bf16 v[100:103], v[140:143], v[172:175], v[100:103]
	v_mfma_f32_16x16x32_bf16 v[96:99], v[156:159], v[172:175], v[96:99]
	v_mfma_f32_16x16x32_bf16 v[84:87], v[140:143], v[180:183], v[84:87]
	v_mfma_f32_16x16x32_bf16 v[80:83], v[156:159], v[180:183], v[80:83]
	v_mfma_f32_16x16x32_bf16 v[68:71], v[140:143], v[188:191], v[68:71]
	v_mfma_f32_16x16x32_bf16 v[64:67], v[156:159], v[188:191], v[64:67]
	v_mfma_f32_16x16x32_bf16 v[124:127], v[144:147], v[168:171], v[124:127]
	v_mfma_f32_16x16x32_bf16 v[112:115], v[160:163], v[168:171], v[112:115]
	v_mfma_f32_16x16x32_bf16 v[100:103], v[144:147], v[176:179], v[100:103]
	v_mfma_f32_16x16x32_bf16 v[96:99], v[160:163], v[176:179], v[96:99]
	v_mfma_f32_16x16x32_bf16 v[84:87], v[144:147], v[184:187], v[84:87]
	v_mfma_f32_16x16x32_bf16 v[80:83], v[160:163], v[184:187], v[80:83]
	v_mfma_f32_16x16x32_bf16 v[68:71], v[144:147], v[214:217], v[68:71]
	v_mfma_f32_16x16x32_bf16 v[64:67], v[160:163], v[214:217], v[64:67]
	s_setprio 0
	s_barrier
	ds_read_b128 v[164:167], v248 offset:16384
	ds_read_b128 v[168:171], v248 offset:17408
	ds_read_b128 v[172:175], v248 offset:18432
	ds_read_b128 v[176:179], v248 offset:19456
	ds_read_b128 v[180:183], v248 offset:20480
	ds_read_b128 v[184:187], v248 offset:21504
	ds_read_b128 v[188:191], v248 offset:22528
	ds_read_b128 v[214:217], v248 offset:23552
	s_add_u32 s60, s28, 0x40000
	s_addc_u32 s61, s29, 0
	s_add_i32 m0, s59, s39
	s_nop 0
	global_load_lds_dwordx4 v194, s[28:29]
	s_add_i32 m0, m0, 0x2000
	s_nop 0
	global_load_lds_dwordx4 v208, s[28:29]
	s_add_i32 m0, s65, s39
	s_nop 0
	global_load_lds_dwordx4 v194, s[60:61]
	s_add_i32 m0, m0, 0x2000
	s_nop 0
	global_load_lds_dwordx4 v208, s[60:61]
	s_mov_b32 m0, s41
	s_nop 0
	global_load_lds_dwordx4 v204, s[30:31]
	s_mov_b32 m0, s44
	s_nop 0
	global_load_lds_dwordx4 v206, s[30:31]
	s_cmp_lg_i32 s66, 0
	s_cbranch_scc1 .Lpg8rx3
	s_waitcnt vmcnt(8)
.Lpg8rx3:
	s_waitcnt lgkmcnt(0)
	s_setprio 1
	s_barrier
	v_mfma_f32_16x16x32_bf16 v[60:63], v[120:123], v[164:167], v[60:63]
	v_mfma_f32_16x16x32_bf16 v[56:59], v[132:135], v[164:167], v[56:59]
	v_mfma_f32_16x16x32_bf16 v[44:47], v[120:123], v[172:175], v[44:47]
	v_mfma_f32_16x16x32_bf16 v[40:43], v[132:135], v[172:175], v[40:43]
	v_mfma_f32_16x16x32_bf16 v[28:31], v[120:123], v[180:183], v[28:31]
	v_mfma_f32_16x16x32_bf16 v[24:27], v[132:135], v[180:183], v[24:27]
	v_mfma_f32_16x16x32_bf16 v[12:15], v[120:123], v[188:191], v[12:15]
	v_mfma_f32_16x16x32_bf16 v[8:11], v[132:135], v[188:191], v[8:11]
	v_mfma_f32_16x16x32_bf16 v[60:63], v[128:131], v[168:171], v[60:63]
	v_mfma_f32_16x16x32_bf16 v[56:59], v[136:139], v[168:171], v[56:59]
	v_mfma_f32_16x16x32_bf16 v[44:47], v[128:131], v[176:179], v[44:47]
	v_mfma_f32_16x16x32_bf16 v[40:43], v[136:139], v[176:179], v[40:43]
	v_mfma_f32_16x16x32_bf16 v[28:31], v[128:131], v[184:187], v[28:31]
	v_mfma_f32_16x16x32_bf16 v[24:27], v[136:139], v[184:187], v[24:27]
	v_mfma_f32_16x16x32_bf16 v[12:15], v[128:131], v[214:217], v[12:15]
	v_mfma_f32_16x16x32_bf16 v[8:11], v[136:139], v[214:217], v[8:11]
	v_mfma_f32_16x16x32_bf16 v[52:55], v[140:143], v[164:167], v[52:55]
	v_mfma_f32_16x16x32_bf16 v[48:51], v[156:159], v[164:167], v[48:51]
	v_mfma_f32_16x16x32_bf16 v[36:39], v[140:143], v[172:175], v[36:39]
	v_mfma_f32_16x16x32_bf16 v[32:35], v[156:159], v[172:175], v[32:35]
	v_mfma_f32_16x16x32_bf16 v[20:23], v[140:143], v[180:183], v[20:23]
	v_mfma_f32_16x16x32_bf16 v[16:19], v[156:159], v[180:183], v[16:19]
	v_mfma_f32_16x16x32_bf16 v[4:7], v[140:143], v[188:191], v[4:7]
	v_mfma_f32_16x16x32_bf16 v[0:3], v[156:159], v[188:191], v[0:3]
	v_mfma_f32_16x16x32_bf16 v[52:55], v[144:147], v[168:171], v[52:55]
	v_mfma_f32_16x16x32_bf16 v[48:51], v[160:163], v[168:171], v[48:51]
	v_mfma_f32_16x16x32_bf16 v[36:39], v[144:147], v[176:179], v[36:39]
	v_mfma_f32_16x16x32_bf16 v[32:35], v[160:163], v[176:179], v[32:35]
	v_mfma_f32_16x16x32_bf16 v[20:23], v[144:147], v[184:187], v[20:23]
	v_mfma_f32_16x16x32_bf16 v[16:19], v[160:163], v[184:187], v[16:19]
	v_mfma_f32_16x16x32_bf16 v[4:7], v[144:147], v[214:217], v[4:7]
	v_mfma_f32_16x16x32_bf16 v[0:3], v[160:163], v[214:217], v[0:3]
	s_setprio 0
	s_barrier
; #define PG8_STAGE(bufoff, gbase, voff) do { _Pragma("unroll") for (int _i = 0; _i < 2; ++_i) \
;         __builtin_amdgcn_global_load_lds((const unsigned*)((const char*)(gbase) + (voff)[_i]), (PG8_LAS unsigned*)(lds + (bufoff) + ldsw + _i * 8192), 16, 0, 0); } while (0)
; #define PG8_LDA(dst, b, h) do { _Pragma("unroll") for (int m = 0; m < 4; ++m) _Pragma("unroll") for (int k = 0; k < 2; ++k) dst[m][k] = *(const PG8_LAS bf16x8*)(lds + PG8_SA(b, h) + aoff + m * 2048 + k * 1024); } while (0)
; #define PG8_LDB(dst, b, h) do { _Pragma("unroll") for (int n = 0; n < 2; ++n) _Pragma("unroll") for (int k = 0; k < 2; ++k) dst[n][k] = *(const PG8_LAS bf16x8*)(lds + PG8_SB(b, h) + boff + n * 2048 + k * 1024); } while (0)
; #define PG8_MMA(ai, bj, At, Bt) do { __builtin_amdgcn_s_setprio(1); _Pragma("unroll") for (int m = 0; m < 4; ++m) _Pragma("unroll") for (int n = 0; n < 2; ++n) _Pragma("unroll") for (int k = 0; k < 2; ++k) \
;         acc[ai][bj][m][n] = __builtin_amdgcn_mfma_f32_16x16x32_bf16(Bt[n][k], At[m][k], acc[ai][bj][m][n], 0, 0, 0); __builtin_amdgcn_s_setprio(0); } while (0)
; #define PG8_WAIT_V(n) asm volatile("s_waitcnt vmcnt(" #n ")" ::: "memory")
; #define PG8_WAIT_L(n) asm volatile("s_waitcnt lgkmcnt(" #n ")" ::: "memory")
; #define PG8_BAR __builtin_amdgcn_s_barrier()
; #define PG8_SCHED __builtin_amdgcn_sched_barrier(0)
; template <class Epi, class Sched, bool ALIGN_EPI = false, bool SP2 = false>
; __device__ __forceinline__ void gemm_phase(PG8_LAS unsigned char* lds, const Gemm g, const Sched& S, const Epi& E) {
;     ...
;             PG8_STAGE(PG8_SA(0, 1), a2 + hstep, voffA); PG8_SCHED; PG8_LDB(B0, 1, 0); PG8_LDB(B1, 1, 1); PG8_SCHED; PG8_LDA(At, 1, 0);
;             PG8_WAIT_V(8); PG8_WAIT_L(0); PG8_BAR; PG8_MMA(0, 0, At, B0); PG8_MMA(0, 1, At, B1); PG8_BAR; PG8_SCHED;
;             PG8_STAGE(PG8_SB(1, 0), b3, voffB); PG8_STAGE(PG8_SB(1, 1), b3 + hstep, voffB); PG8_STAGE(PG8_SA(1, 0), a3, voffA); PG8_SCHED; PG8_LDA(At, 1, 1);
;             PG8_WAIT_V(8); PG8_WAIT_L(0); PG8_BAR; PG8_MMA(1, 0, At, B0); PG8_MMA(1, 1, At, B1); PG8_BAR; PG8_SCHED;
;     ...
;         if constexpr (ALIGN_EPI) { if (wr == 0) PG8_BAR; }
	s_mov_b64 s[98:99], s[30:31]
	s_add_u32 s100, s30, 0x40000
	s_addc_u32 s101, s31, 0
	s_add_i32 s30, 0, 0x18000
	s_add_i32 s31, 0, 0x1c000
	v_add_u32_e32 v136, s30, v247
	v_add_u32_e32 v160, s31, v247
	ds_read_b128 v[120:123], v136
	ds_read_b128 v[128:131], v136 offset:1024
	ds_read_b128 v[132:135], v136 offset:2048
	ds_read_b128 v[136:139], v136 offset:3072
	ds_read_b128 v[140:143], v160
	ds_read_b128 v[144:147], v160 offset:1024
	ds_read_b128 v[156:159], v160 offset:2048
	ds_read_b128 v[160:163], v160 offset:3072
	ds_read_b128 v[164:167], v248 offset:32768
	ds_read_b128 v[168:171], v248 offset:33792
	ds_read_b128 v[172:175], v248 offset:34816
	ds_read_b128 v[176:179], v248 offset:35840
	ds_read_b128 v[180:183], v248 offset:36864
	ds_read_b128 v[184:187], v248 offset:37888
	ds_read_b128 v[188:191], v248 offset:38912
	ds_read_b128 v[214:217], v248 offset:39936
	s_mov_b32 m0, s46
	s_nop 0
	global_load_lds_dwordx4 v204, s[100:101]
	s_mov_b32 m0, s48
	s_nop 0
	global_load_lds_dwordx4 v206, s[100:101]
	s_waitcnt vmcnt(8)
	s_waitcnt lgkmcnt(0)
	s_setprio 1
	s_barrier
	v_mfma_f32_16x16x32_bf16 v[152:155], v[120:123], v[164:167], v[152:155]
	v_mfma_f32_16x16x32_bf16 v[148:151], v[132:135], v[164:167], v[148:151]
	v_mfma_f32_16x16x32_bf16 v[108:111], v[120:123], v[172:175], v[108:111]
	v_mfma_f32_16x16x32_bf16 v[104:107], v[132:135], v[172:175], v[104:107]
	v_mfma_f32_16x16x32_bf16 v[92:95], v[120:123], v[180:183], v[92:95]
	v_mfma_f32_16x16x32_bf16 v[88:91], v[132:135], v[180:183], v[88:91]
	v_mfma_f32_16x16x32_bf16 v[76:79], v[120:123], v[188:191], v[76:79]
	v_mfma_f32_16x16x32_bf16 v[72:75], v[132:135], v[188:191], v[72:75]
	v_mfma_f32_16x16x32_bf16 v[152:155], v[128:131], v[168:171], v[152:155]
	v_mfma_f32_16x16x32_bf16 v[148:151], v[136:139], v[168:171], v[148:151]
	v_mfma_f32_16x16x32_bf16 v[108:111], v[128:131], v[176:179], v[108:111]
	v_mfma_f32_16x16x32_bf16 v[104:107], v[136:139], v[176:179], v[104:107]
	v_mfma_f32_16x16x32_bf16 v[92:95], v[128:131], v[184:187], v[92:95]
	v_mfma_f32_16x16x32_bf16 v[88:91], v[136:139], v[184:187], v[88:91]
	v_mfma_f32_16x16x32_bf16 v[76:79], v[128:131], v[214:217], v[76:79]
	v_mfma_f32_16x16x32_bf16 v[72:75], v[136:139], v[214:217], v[72:75]
	v_mfma_f32_16x16x32_bf16 v[124:127], v[140:143], v[164:167], v[124:127]
	v_mfma_f32_16x16x32_bf16 v[112:115], v[156:159], v[164:167], v[112:115]
	v_mfma_f32_16x16x32_bf16 v[100:103], v[140:143], v[172:175], v[100:103]
	v_mfma_f32_16x16x32_bf16 v[96:99], v[156:159], v[172:175], v[96:99]
	v_mfma_f32_16x16x32_bf16 v[84:87], v[140:143], v[180:183], v[84:87]
	v_mfma_f32_16x16x32_bf16 v[80:83], v[156:159], v[180:183], v[80:83]
	v_mfma_f32_16x16x32_bf16 v[68:71], v[140:143], v[188:191], v[68:71]
	v_mfma_f32_16x16x32_bf16 v[64:67], v[156:159], v[188:191], v[64:67]
	v_mfma_f32_16x16x32_bf16 v[124:127], v[144:147], v[168:171], v[124:127]
	v_mfma_f32_16x16x32_bf16 v[112:115], v[160:163], v[168:171], v[112:115]
	v_mfma_f32_16x16x32_bf16 v[100:103], v[144:147], v[176:179], v[100:103]
	v_mfma_f32_16x16x32_bf16 v[96:99], v[160:163], v[176:179], v[96:99]
	v_mfma_f32_16x16x32_bf16 v[84:87], v[144:147], v[184:187], v[84:87]
	v_mfma_f32_16x16x32_bf16 v[80:83], v[160:163], v[184:187], v[80:83]
	v_mfma_f32_16x16x32_bf16 v[68:71], v[144:147], v[214:217], v[68:71]
	v_mfma_f32_16x16x32_bf16 v[64:67], v[160:163], v[214:217], v[64:67]
	s_setprio 0
	s_barrier
	ds_read_b128 v[164:167], v248 offset:49152
	ds_read_b128 v[168:171], v248 offset:50176
	ds_read_b128 v[172:175], v248 offset:51200
	ds_read_b128 v[176:179], v248 offset:52224
	ds_read_b128 v[180:183], v248 offset:53248
	ds_read_b128 v[184:187], v248 offset:54272
	ds_read_b128 v[188:191], v248 offset:55296
	ds_read_b128 v[214:217], v248 offset:56320
	s_add_u32 s100, s28, 0x80
	s_addc_u32 s101, s29, 0
	s_add_u32 s28, s28, 0x40080
	s_addc_u32 s29, s29, 0
	s_add_u32 s98, s98, 0x80
	s_addc_u32 s99, s99, 0
	s_add_i32 m0, s30, s39
	s_nop 0
	global_load_lds_dwordx4 v194, s[100:101]
	s_add_i32 m0, m0, 0x2000
	s_nop 0
	global_load_lds_dwordx4 v208, s[100:101]
	s_add_i32 m0, s31, s39
	s_nop 0
	global_load_lds_dwordx4 v194, s[28:29]
	s_add_i32 m0, m0, 0x2000
	s_nop 0
	global_load_lds_dwordx4 v208, s[28:29]
	s_mov_b32 m0, s50
	s_nop 0
	global_load_lds_dwordx4 v204, s[98:99]
	s_mov_b32 m0, s51
	s_nop 0
	global_load_lds_dwordx4 v206, s[98:99]
	s_waitcnt vmcnt(8)
	s_waitcnt lgkmcnt(0)
	s_setprio 1
	s_barrier
	v_mfma_f32_16x16x32_bf16 v[60:63], v[120:123], v[164:167], v[60:63]
	v_mfma_f32_16x16x32_bf16 v[56:59], v[132:135], v[164:167], v[56:59]
	v_mfma_f32_16x16x32_bf16 v[44:47], v[120:123], v[172:175], v[44:47]
	v_mfma_f32_16x16x32_bf16 v[40:43], v[132:135], v[172:175], v[40:43]
	v_mfma_f32_16x16x32_bf16 v[28:31], v[120:123], v[180:183], v[28:31]
	v_mfma_f32_16x16x32_bf16 v[24:27], v[132:135], v[180:183], v[24:27]
	v_mfma_f32_16x16x32_bf16 v[12:15], v[120:123], v[188:191], v[12:15]
	v_mfma_f32_16x16x32_bf16 v[8:11], v[132:135], v[188:191], v[8:11]
	v_mfma_f32_16x16x32_bf16 v[60:63], v[128:131], v[168:171], v[60:63]
	v_mfma_f32_16x16x32_bf16 v[56:59], v[136:139], v[168:171], v[56:59]
	v_mfma_f32_16x16x32_bf16 v[44:47], v[128:131], v[176:179], v[44:47]
	v_mfma_f32_16x16x32_bf16 v[40:43], v[136:139], v[176:179], v[40:43]
	v_mfma_f32_16x16x32_bf16 v[28:31], v[128:131], v[184:187], v[28:31]
	v_mfma_f32_16x16x32_bf16 v[24:27], v[136:139], v[184:187], v[24:27]
	v_mfma_f32_16x16x32_bf16 v[12:15], v[128:131], v[214:217], v[12:15]
	v_mfma_f32_16x16x32_bf16 v[8:11], v[136:139], v[214:217], v[8:11]
	v_mfma_f32_16x16x32_bf16 v[52:55], v[140:143], v[164:167], v[52:55]
	v_mfma_f32_16x16x32_bf16 v[48:51], v[156:159], v[164:167], v[48:51]
	v_mfma_f32_16x16x32_bf16 v[36:39], v[140:143], v[172:175], v[36:39]
	v_mfma_f32_16x16x32_bf16 v[32:35], v[156:159], v[172:175], v[32:35]
	v_mfma_f32_16x16x32_bf16 v[20:23], v[140:143], v[180:183], v[20:23]
	v_mfma_f32_16x16x32_bf16 v[16:19], v[156:159], v[180:183], v[16:19]
	v_mfma_f32_16x16x32_bf16 v[4:7], v[140:143], v[188:191], v[4:7]
	v_mfma_f32_16x16x32_bf16 v[0:3], v[156:159], v[188:191], v[0:3]
	v_mfma_f32_16x16x32_bf16 v[52:55], v[144:147], v[168:171], v[52:55]
	v_mfma_f32_16x16x32_bf16 v[48:51], v[160:163], v[168:171], v[48:51]
	v_mfma_f32_16x16x32_bf16 v[36:39], v[144:147], v[176:179], v[36:39]
	v_mfma_f32_16x16x32_bf16 v[32:35], v[160:163], v[176:179], v[32:35]
	v_mfma_f32_16x16x32_bf16 v[20:23], v[144:147], v[184:187], v[20:23]
	v_mfma_f32_16x16x32_bf16 v[16:19], v[160:163], v[184:187], v[16:19]
	v_mfma_f32_16x16x32_bf16 v[4:7], v[144:147], v[214:217], v[4:7]
	v_mfma_f32_16x16x32_bf16 v[0:3], v[160:163], v[214:217], v[0:3]
	s_setprio 0
	s_barrier
	s_add_i32 s58, s58, 2
	s_add_u32 s62, s62, 0x100
	s_addc_u32 s63, s63, 0
	s_cmp_gt_u32 s58, 13
	s_cbranch_scc0 .LBB0_514
	.p2align	6
	s_and_b64 vcc, exec, s[14:15]
	s_cbranch_vccz .LBB0_517
	s_barrier

; template <class Epi, class Sched, bool ALIGN_EPI = false, bool SP2 = false>
; __device__ __forceinline__ void gemm_phase(PG8_LAS unsigned char* lds, const Gemm g, const Sched& S, const Epi& E) {
;     ...
;         const bool has_next = S.next(ui + 1, nxt);
;         const char* nA = has_next ? (const char*)g.A + (size_t)nxt.pm * tstep : cA; const char* nB = has_next ? (const char*)g.Bt + (size_t)nxt.pn * tstep : cB;
;         for (int t = 0; t < nt; t += 2) {
;             const bool last = (t == nt - 2);
;             const char* a1 = cA + (size_t)(t + 1) * kstep;
;             const char* a2 = last ? nA : cA + (size_t)(t + 2) * kstep; const char* b2 = last ? nB : cB + (size_t)(t + 2) * kstep;
;             const char* a3 = a2 + kstep; const char* b3 = b2 + kstep;
;     ...
; #pragma unroll
;         for (int a = 0; a < 2; ++a)
; #pragma unroll
;             for (int b = 0; b < 2; ++b)
; #pragma unroll
;                 for (int m = 0; m < 4; ++m)
; #pragma unroll
;                     for (int n = 0; n < 2; ++n) acc[a][b][m][n] = (f32x4){0.f, 0.f, 0.f, 0.f};
;         cur = nxt; cA = nA; cB = nB; ++ui; relax = Epi::LOADS_BEFORE_STORES && !Epi::AFTER_DRAIN && SP2;
.LBB0_610:
	s_ashr_i32 s13, s12, 31
	s_lshl_b64 s[16:17], s[12:13], 19
	s_add_u32 s16, s39, s16
	s_addc_u32 s17, s42, s17
	s_and_b64 s[18:19], s[14:15], exec
	s_cselect_b32 s13, s17, s25
	s_cselect_b32 s54, s16, s24
	s_ashr_i32 s11, s10, 31
	s_lshl_b64 s[18:19], s[10:11], 19
	s_add_u32 s18, s43, s18
	s_addc_u32 s19, s44, s19
	s_and_b64 s[30:31], s[14:15], exec
	s_cselect_b32 s11, s19, s29
	s_cselect_b32 s55, s18, s28
	s_add_u32 s30, s24, 0x40080
	s_addc_u32 s31, s25, 0
	s_add_u32 s56, s28, 0x100
	v_mov_b32_e32 v0, 0
	v_lshl_add_u64 v[128:129], s[30:31], 0, v[160:161]
	v_lshl_add_u64 v[130:131], s[30:31], 0, v[162:163]
	s_addc_u32 s57, s29, 0
	s_mov_b32 s58, -2
	s_mov_b64 s[40:41], 0
	v_mov_b32_e32 v1, v0
	v_mov_b32_e32 v2, v0
	v_mov_b32_e32 v3, v0
	v_mov_b32_e32 v4, v0
	v_mov_b32_e32 v5, v0
	v_mov_b32_e32 v6, v0
	v_mov_b32_e32 v7, v0
	v_mov_b32_e32 v16, v0
	v_mov_b32_e32 v17, v0
	v_mov_b32_e32 v18, v0
	v_mov_b32_e32 v19, v0
	v_mov_b32_e32 v20, v0
	v_mov_b32_e32 v21, v0
	v_mov_b32_e32 v22, v0
	v_mov_b32_e32 v23, v0
	v_mov_b32_e32 v32, v0
	v_mov_b32_e32 v33, v0
	v_mov_b32_e32 v34, v0
	v_mov_b32_e32 v35, v0
	v_mov_b32_e32 v36, v0
	v_mov_b32_e32 v37, v0
	v_mov_b32_e32 v38, v0
	v_mov_b32_e32 v39, v0
	v_mov_b32_e32 v48, v0
	v_mov_b32_e32 v49, v0
	v_mov_b32_e32 v50, v0
	v_mov_b32_e32 v51, v0
	v_mov_b32_e32 v52, v0
	v_mov_b32_e32 v53, v0
	v_mov_b32_e32 v54, v0
	v_mov_b32_e32 v55, v0
	v_mov_b32_e32 v8, v0
	v_mov_b32_e32 v9, v0
	v_mov_b32_e32 v10, v0
	v_mov_b32_e32 v11, v0
	v_mov_b32_e32 v12, v0
	v_mov_b32_e32 v13, v0
	v_mov_b32_e32 v14, v0
	v_mov_b32_e32 v15, v0
	v_mov_b32_e32 v24, v0
	v_mov_b32_e32 v25, v0
	v_mov_b32_e32 v26, v0
	v_mov_b32_e32 v27, v0
	v_mov_b32_e32 v28, v0
	v_mov_b32_e32 v29, v0
	v_mov_b32_e32 v30, v0
	v_mov_b32_e32 v31, v0
	v_mov_b32_e32 v40, v0
	v_mov_b32_e32 v41, v0
	v_mov_b32_e32 v42, v0
	v_mov_b32_e32 v43, v0
	v_mov_b32_e32 v44, v0
	v_mov_b32_e32 v45, v0
	v_mov_b32_e32 v46, v0
	v_mov_b32_e32 v47, v0
	v_mov_b32_e32 v56, v0
	v_mov_b32_e32 v57, v0
	v_mov_b32_e32 v58, v0
	v_mov_b32_e32 v59, v0
	v_mov_b32_e32 v60, v0
	v_mov_b32_e32 v61, v0
	v_mov_b32_e32 v62, v0
	v_mov_b32_e32 v63, v0
	v_mov_b32_e32 v64, v0
	v_mov_b32_e32 v65, v0
	v_mov_b32_e32 v66, v0
	v_mov_b32_e32 v67, v0
	v_mov_b32_e32 v68, v0
	v_mov_b32_e32 v69, v0
	v_mov_b32_e32 v70, v0
	v_mov_b32_e32 v71, v0
	v_mov_b32_e32 v80, v0
	v_mov_b32_e32 v81, v0
	v_mov_b32_e32 v82, v0
	v_mov_b32_e32 v83, v0
	v_mov_b32_e32 v84, v0
	v_mov_b32_e32 v85, v0
	v_mov_b32_e32 v86, v0
	v_mov_b32_e32 v87, v0
	v_mov_b32_e32 v96, v0
	v_mov_b32_e32 v97, v0
	v_mov_b32_e32 v98, v0
	v_mov_b32_e32 v99, v0
	v_mov_b32_e32 v100, v0
	v_mov_b32_e32 v101, v0
	v_mov_b32_e32 v102, v0
	v_mov_b32_e32 v103, v0
	v_mov_b32_e32 v112, v0
	v_mov_b32_e32 v113, v0
	v_mov_b32_e32 v114, v0
	v_mov_b32_e32 v115, v0
	v_mov_b32_e32 v116, v0
	v_mov_b32_e32 v117, v0
	v_mov_b32_e32 v118, v0
	v_mov_b32_e32 v119, v0
	v_mov_b32_e32 v72, v0
	v_mov_b32_e32 v73, v0
	v_mov_b32_e32 v74, v0
	v_mov_b32_e32 v75, v0
	v_mov_b32_e32 v76, v0
	v_mov_b32_e32 v77, v0
	v_mov_b32_e32 v78, v0
	v_mov_b32_e32 v79, v0
	v_mov_b32_e32 v88, v0
	v_mov_b32_e32 v89, v0
	v_mov_b32_e32 v90, v0
	v_mov_b32_e32 v91, v0
	v_mov_b32_e32 v92, v0
	v_mov_b32_e32 v93, v0
	v_mov_b32_e32 v94, v0
	v_mov_b32_e32 v95, v0
	v_mov_b32_e32 v104, v0
	v_mov_b32_e32 v105, v0
	v_mov_b32_e32 v106, v0
	v_mov_b32_e32 v107, v0
	v_mov_b32_e32 v108, v0
	v_mov_b32_e32 v109, v0
	v_mov_b32_e32 v110, v0
	v_mov_b32_e32 v111, v0
	v_mov_b32_e32 v120, v0
	v_mov_b32_e32 v121, v0
	v_mov_b32_e32 v122, v0
	v_mov_b32_e32 v123, v0
	v_mov_b32_e32 v124, v0
	v_mov_b32_e32 v125, v0
	v_mov_b32_e32 v126, v0
	v_mov_b32_e32 v127, v0
	.p2align	6
	s_nop 0
	s_nop 0

; #define PG8_STAGE(bufoff, gbase, voff) do { _Pragma("unroll") for (int _i = 0; _i < 2; ++_i) \
;         __builtin_amdgcn_global_load_lds((const unsigned*)((const char*)(gbase) + (voff)[_i]), (PG8_LAS unsigned*)(lds + (bufoff) + ldsw + _i * 8192), 16, 0, 0); } while (0)
; #define PG8_LDA(dst, b, h) do { _Pragma("unroll") for (int m = 0; m < 4; ++m) _Pragma("unroll") for (int k = 0; k < 2; ++k) dst[m][k] = *(const PG8_LAS bf16x8*)(lds + PG8_SA(b, h) + aoff + m * 2048 + k * 1024); } while (0)
; #define PG8_LDB(dst, b, h) do { _Pragma("unroll") for (int n = 0; n < 2; ++n) _Pragma("unroll") for (int k = 0; k < 2; ++k) dst[n][k] = *(const PG8_LAS bf16x8*)(lds + PG8_SB(b, h) + boff + n * 2048 + k * 1024); } while (0)
; #define PG8_MMA(ai, bj, At, Bt) do { __builtin_amdgcn_s_setprio(1); _Pragma("unroll") for (int m = 0; m < 4; ++m) _Pragma("unroll") for (int n = 0; n < 2; ++n) _Pragma("unroll") for (int k = 0; k < 2; ++k) \
;         acc[ai][bj][m][n] = __builtin_amdgcn_mfma_f32_16x16x32_bf16(Bt[n][k], At[m][k], acc[ai][bj][m][n], 0, 0, 0); __builtin_amdgcn_s_setprio(0); } while (0)
; #define PG8_WAIT_L(n) asm volatile("s_waitcnt lgkmcnt(" #n ")" ::: "memory")
; #define PG8_WAIT_V8_UNLESS(flag) asm volatile("s_cmp_lg_i32 %0, 0\n\ts_cbranch_scc1 .Lpg8rx%=\n\ts_waitcnt vmcnt(8)\n.Lpg8rx%=:" :: "s"(__builtin_amdgcn_readfirstlane(flag)) : "scc", "memory")
; #define PG8_BAR __builtin_amdgcn_s_barrier()
; #define PG8_SCHED __builtin_amdgcn_sched_barrier(0)
; template <class Epi, class Sched, bool ALIGN_EPI = false, bool SP2 = false>
; __device__ __forceinline__ void gemm_phase(PG8_LAS unsigned char* lds, const Gemm g, const Sched& S, const Epi& E) {
;     ...
;             PG8_STAGE(PG8_SA(1, 1), a1 + hstep, voffA); PG8_SCHED; PG8_LDB(B0, 0, 0); PG8_LDB(B1, 0, 1); PG8_SCHED; PG8_LDA(At, 0, 0);
;             PG8_WAIT_V8_UNLESS(rx); PG8_WAIT_L(0); PG8_BAR; PG8_MMA(0, 0, At, B0); PG8_MMA(0, 1, At, B1); PG8_BAR; PG8_SCHED;
;             PG8_STAGE(PG8_SB(0, 0), b2, voffB); PG8_STAGE(PG8_SB(0, 1), b2 + hstep, voffB); PG8_STAGE(PG8_SA(0, 0), a2, voffA); PG8_SCHED; PG8_LDA(At, 0, 1);
;             PG8_WAIT_V8_UNLESS(rx); PG8_WAIT_L(0); PG8_BAR; PG8_MMA(1, 0, At, B0); PG8_MMA(1, 1, At, B1); PG8_BAR; PG8_SCHED;
.Lpg8rx4:
	s_waitcnt lgkmcnt(0)
	s_setprio 1
	s_barrier
	v_mfma_f32_16x16x32_bf16 v[124:127], v[132:135], v[176:179], v[124:127]
	v_mfma_f32_16x16x32_bf16 v[120:123], v[140:143], v[176:179], v[120:123]
	v_mfma_f32_16x16x32_bf16 v[108:111], v[132:135], v[204:207], v[108:111]
	v_mfma_f32_16x16x32_bf16 v[104:107], v[140:143], v[204:207], v[104:107]
	v_mfma_f32_16x16x32_bf16 v[92:95], v[132:135], v[212:215], v[92:95]
	v_mfma_f32_16x16x32_bf16 v[88:91], v[140:143], v[212:215], v[88:91]
	v_mfma_f32_16x16x32_bf16 v[76:79], v[132:135], v[220:223], v[76:79]
	v_mfma_f32_16x16x32_bf16 v[72:75], v[140:143], v[220:223], v[72:75]
	v_mfma_f32_16x16x32_bf16 v[124:127], v[136:139], v[186:189], v[124:127]
	v_mfma_f32_16x16x32_bf16 v[120:123], v[144:147], v[186:189], v[120:123]
	v_mfma_f32_16x16x32_bf16 v[108:111], v[136:139], v[208:211], v[108:111]
	v_mfma_f32_16x16x32_bf16 v[104:107], v[144:147], v[208:211], v[104:107]
	v_mfma_f32_16x16x32_bf16 v[92:95], v[136:139], v[216:219], v[92:95]
	v_mfma_f32_16x16x32_bf16 v[88:91], v[144:147], v[216:219], v[88:91]
	v_mfma_f32_16x16x32_bf16 v[76:79], v[136:139], v[224:227], v[76:79]
	v_mfma_f32_16x16x32_bf16 v[72:75], v[144:147], v[224:227], v[72:75]
	v_mfma_f32_16x16x32_bf16 v[116:119], v[148:151], v[176:179], v[116:119]
	v_mfma_f32_16x16x32_bf16 v[112:115], v[168:171], v[176:179], v[112:115]
	v_mfma_f32_16x16x32_bf16 v[100:103], v[148:151], v[204:207], v[100:103]
	v_mfma_f32_16x16x32_bf16 v[96:99], v[168:171], v[204:207], v[96:99]
	v_mfma_f32_16x16x32_bf16 v[84:87], v[148:151], v[212:215], v[84:87]
	v_mfma_f32_16x16x32_bf16 v[80:83], v[168:171], v[212:215], v[80:83]
	v_mfma_f32_16x16x32_bf16 v[68:71], v[148:151], v[220:223], v[68:71]
	v_mfma_f32_16x16x32_bf16 v[64:67], v[168:171], v[220:223], v[64:67]
	v_mfma_f32_16x16x32_bf16 v[116:119], v[164:167], v[186:189], v[116:119]
	v_mfma_f32_16x16x32_bf16 v[112:115], v[172:175], v[186:189], v[112:115]
	v_mfma_f32_16x16x32_bf16 v[100:103], v[164:167], v[208:211], v[100:103]
	v_mfma_f32_16x16x32_bf16 v[96:99], v[172:175], v[208:211], v[96:99]
	v_mfma_f32_16x16x32_bf16 v[84:87], v[164:167], v[216:219], v[84:87]
	v_mfma_f32_16x16x32_bf16 v[80:83], v[172:175], v[216:219], v[80:83]
	v_mfma_f32_16x16x32_bf16 v[68:71], v[164:167], v[224:227], v[68:71]
	v_mfma_f32_16x16x32_bf16 v[64:67], v[172:175], v[224:227], v[64:67]
	s_setprio 0
	s_barrier
	ds_read_b128 v[176:179], v185 offset:16384
	ds_read_b128 v[186:189], v185 offset:17408
	ds_read_b128 v[204:207], v185 offset:18432
	ds_read_b128 v[208:211], v185 offset:19456
	ds_read_b128 v[212:215], v185 offset:20480
	ds_read_b128 v[216:219], v185 offset:21504
	ds_read_b128 v[220:223], v185 offset:22528
	ds_read_b128 v[224:227], v185 offset:23552
	s_add_u32 s60, s28, 0x40000
	s_addc_u32 s61, s29, 0
	s_add_i32 m0, s59, s38
	s_nop 0
	global_load_lds_dwordx4 v154, s[28:29]
	s_add_i32 m0, m0, 0x2000
	s_nop 0
	global_load_lds_dwordx4 v158, s[28:29]
	s_add_i32 m0, s62, s38
	s_nop 0
	global_load_lds_dwordx4 v154, s[60:61]
	s_add_i32 m0, m0, 0x2000
	s_nop 0
	global_load_lds_dwordx4 v158, s[60:61]
	s_mov_b32 m0, s21
	s_nop 0
	global_load_lds_dwordx4 v152, s[30:31]
	s_mov_b32 m0, s23
	s_nop 0
	global_load_lds_dwordx4 v156, s[30:31]
	s_cmp_lg_i32 s63, 0
	s_cbranch_scc1 .Lpg8rx5
	s_waitcnt vmcnt(8)
.Lpg8rx5:
	s_waitcnt lgkmcnt(0)
	s_setprio 1
	s_barrier
	v_mfma_f32_16x16x32_bf16 v[60:63], v[132:135], v[176:179], v[60:63]
	v_mfma_f32_16x16x32_bf16 v[56:59], v[140:143], v[176:179], v[56:59]
	v_mfma_f32_16x16x32_bf16 v[44:47], v[132:135], v[204:207], v[44:47]
	v_mfma_f32_16x16x32_bf16 v[40:43], v[140:143], v[204:207], v[40:43]
	v_mfma_f32_16x16x32_bf16 v[28:31], v[132:135], v[212:215], v[28:31]
	v_mfma_f32_16x16x32_bf16 v[24:27], v[140:143], v[212:215], v[24:27]
	v_mfma_f32_16x16x32_bf16 v[12:15], v[132:135], v[220:223], v[12:15]
	v_mfma_f32_16x16x32_bf16 v[8:11], v[140:143], v[220:223], v[8:11]
	v_mfma_f32_16x16x32_bf16 v[60:63], v[136:139], v[186:189], v[60:63]
	v_mfma_f32_16x16x32_bf16 v[56:59], v[144:147], v[186:189], v[56:59]
	v_mfma_f32_16x16x32_bf16 v[44:47], v[136:139], v[208:211], v[44:47]
	v_mfma_f32_16x16x32_bf16 v[40:43], v[144:147], v[208:211], v[40:43]
	v_mfma_f32_16x16x32_bf16 v[28:31], v[136:139], v[216:219], v[28:31]
	v_mfma_f32_16x16x32_bf16 v[24:27], v[144:147], v[216:219], v[24:27]
	v_mfma_f32_16x16x32_bf16 v[12:15], v[136:139], v[224:227], v[12:15]
	v_mfma_f32_16x16x32_bf16 v[8:11], v[144:147], v[224:227], v[8:11]
	v_mfma_f32_16x16x32_bf16 v[52:55], v[148:151], v[176:179], v[52:55]
	v_mfma_f32_16x16x32_bf16 v[48:51], v[168:171], v[176:179], v[48:51]
	v_mfma_f32_16x16x32_bf16 v[36:39], v[148:151], v[204:207], v[36:39]
	v_mfma_f32_16x16x32_bf16 v[32:35], v[168:171], v[204:207], v[32:35]
	v_mfma_f32_16x16x32_bf16 v[20:23], v[148:151], v[212:215], v[20:23]
	v_mfma_f32_16x16x32_bf16 v[16:19], v[168:171], v[212:215], v[16:19]
	v_mfma_f32_16x16x32_bf16 v[4:7], v[148:151], v[220:223], v[4:7]
	v_mfma_f32_16x16x32_bf16 v[0:3], v[168:171], v[220:223], v[0:3]
	v_mfma_f32_16x16x32_bf16 v[52:55], v[164:167], v[186:189], v[52:55]
	v_mfma_f32_16x16x32_bf16 v[48:51], v[172:175], v[186:189], v[48:51]
	v_mfma_f32_16x16x32_bf16 v[36:39], v[164:167], v[208:211], v[36:39]
	v_mfma_f32_16x16x32_bf16 v[32:35], v[172:175], v[208:211], v[32:35]
	v_mfma_f32_16x16x32_bf16 v[20:23], v[164:167], v[216:219], v[20:23]
	v_mfma_f32_16x16x32_bf16 v[16:19], v[172:175], v[216:219], v[16:19]
	v_mfma_f32_16x16x32_bf16 v[4:7], v[164:167], v[224:227], v[4:7]
	v_mfma_f32_16x16x32_bf16 v[0:3], v[172:175], v[224:227], v[0:3]
	s_setprio 0
	s_barrier
; #define PG8_STAGE(bufoff, gbase, voff) do { _Pragma("unroll") for (int _i = 0; _i < 2; ++_i) \
;         __builtin_amdgcn_global_load_lds((const unsigned*)((const char*)(gbase) + (voff)[_i]), (PG8_LAS unsigned*)(lds + (bufoff) + ldsw + _i * 8192), 16, 0, 0); } while (0)
; #define PG8_LDA(dst, b, h) do { _Pragma("unroll") for (int m = 0; m < 4; ++m) _Pragma("unroll") for (int k = 0; k < 2; ++k) dst[m][k] = *(const PG8_LAS bf16x8*)(lds + PG8_SA(b, h) + aoff + m * 2048 + k * 1024); } while (0)
; #define PG8_LDB(dst, b, h) do { _Pragma("unroll") for (int n = 0; n < 2; ++n) _Pragma("unroll") for (int k = 0; k < 2; ++k) dst[n][k] = *(const PG8_LAS bf16x8*)(lds + PG8_SB(b, h) + boff + n * 2048 + k * 1024); } while (0)
; #define PG8_MMA(ai, bj, At, Bt) do { __builtin_amdgcn_s_setprio(1); _Pragma("unroll") for (int m = 0; m < 4; ++m) _Pragma("unroll") for (int n = 0; n < 2; ++n) _Pragma("unroll") for (int k = 0; k < 2; ++k) \
;         acc[ai][bj][m][n] = __builtin_amdgcn_mfma_f32_16x16x32_bf16(Bt[n][k], At[m][k], acc[ai][bj][m][n], 0, 0, 0); __builtin_amdgcn_s_setprio(0); } while (0)
; #define PG8_WAIT_V(n) asm volatile("s_waitcnt vmcnt(" #n ")" ::: "memory")
; #define PG8_WAIT_L(n) asm volatile("s_waitcnt lgkmcnt(" #n ")" ::: "memory")
; #define PG8_BAR __builtin_amdgcn_s_barrier()
; #define PG8_SCHED __builtin_amdgcn_sched_barrier(0)
; template <class Epi, class Sched, bool ALIGN_EPI = false, bool SP2 = false>
; __device__ __forceinline__ void gemm_phase(PG8_LAS unsigned char* lds, const Gemm g, const Sched& S, const Epi& E) {
;     ...
;             PG8_STAGE(PG8_SA(0, 1), a2 + hstep, voffA); PG8_SCHED; PG8_LDB(B0, 1, 0); PG8_LDB(B1, 1, 1); PG8_SCHED; PG8_LDA(At, 1, 0);
;             PG8_WAIT_V(8); PG8_WAIT_L(0); PG8_BAR; PG8_MMA(0, 0, At, B0); PG8_MMA(0, 1, At, B1); PG8_BAR; PG8_SCHED;
;             PG8_STAGE(PG8_SB(1, 0), b3, voffB); PG8_STAGE(PG8_SB(1, 1), b3 + hstep, voffB); PG8_STAGE(PG8_SA(1, 0), a3, voffA); PG8_SCHED; PG8_LDA(At, 1, 1);
;             PG8_WAIT_V(8); PG8_WAIT_L(0); PG8_BAR; PG8_MMA(1, 0, At, B0); PG8_MMA(1, 1, At, B1); PG8_BAR; PG8_SCHED;
;     ...
;         if constexpr (ALIGN_EPI) { if (wr == 0) PG8_BAR; }
	s_mov_b64 s[98:99], s[30:31]
	s_add_u32 s100, s30, 0x40000
	s_addc_u32 s101, s31, 0
	s_add_i32 s30, 0, 0x18000
	s_add_i32 s31, 0, 0x1c000
	v_add_u32_e32 v144, s30, v183
	v_add_u32_e32 v172, s31, v183
	ds_read_b128 v[132:135], v144
	ds_read_b128 v[136:139], v144 offset:1024
	ds_read_b128 v[140:143], v144 offset:2048
	ds_read_b128 v[144:147], v144 offset:3072
	ds_read_b128 v[148:151], v172
	ds_read_b128 v[164:167], v172 offset:1024
	ds_read_b128 v[168:171], v172 offset:2048
	ds_read_b128 v[172:175], v172 offset:3072
	ds_read_b128 v[176:179], v185 offset:32768
	ds_read_b128 v[186:189], v185 offset:33792
	ds_read_b128 v[204:207], v185 offset:34816
	ds_read_b128 v[208:211], v185 offset:35840
	ds_read_b128 v[212:215], v185 offset:36864
	ds_read_b128 v[216:219], v185 offset:37888
	ds_read_b128 v[220:223], v185 offset:38912
	ds_read_b128 v[224:227], v185 offset:39936
	s_mov_b32 m0, s46
	s_nop 0
	global_load_lds_dwordx4 v152, s[100:101]
	s_mov_b32 m0, s48
	s_nop 0
	global_load_lds_dwordx4 v156, s[100:101]
	s_waitcnt vmcnt(8)
	s_waitcnt lgkmcnt(0)
	s_setprio 1
	s_barrier
	v_mfma_f32_16x16x32_bf16 v[124:127], v[132:135], v[176:179], v[124:127]
	v_mfma_f32_16x16x32_bf16 v[120:123], v[140:143], v[176:179], v[120:123]
	v_mfma_f32_16x16x32_bf16 v[108:111], v[132:135], v[204:207], v[108:111]
	v_mfma_f32_16x16x32_bf16 v[104:107], v[140:143], v[204:207], v[104:107]
	v_mfma_f32_16x16x32_bf16 v[92:95], v[132:135], v[212:215], v[92:95]
	v_mfma_f32_16x16x32_bf16 v[88:91], v[140:143], v[212:215], v[88:91]
	v_mfma_f32_16x16x32_bf16 v[76:79], v[132:135], v[220:223], v[76:79]
	v_mfma_f32_16x16x32_bf16 v[72:75], v[140:143], v[220:223], v[72:75]
	v_mfma_f32_16x16x32_bf16 v[124:127], v[136:139], v[186:189], v[124:127]
	v_mfma_f32_16x16x32_bf16 v[120:123], v[144:147], v[186:189], v[120:123]
	v_mfma_f32_16x16x32_bf16 v[108:111], v[136:139], v[208:211], v[108:111]
	v_mfma_f32_16x16x32_bf16 v[104:107], v[144:147], v[208:211], v[104:107]
	v_mfma_f32_16x16x32_bf16 v[92:95], v[136:139], v[216:219], v[92:95]
	v_mfma_f32_16x16x32_bf16 v[88:91], v[144:147], v[216:219], v[88:91]
	v_mfma_f32_16x16x32_bf16 v[76:79], v[136:139], v[224:227], v[76:79]
	v_mfma_f32_16x16x32_bf16 v[72:75], v[144:147], v[224:227], v[72:75]
	v_mfma_f32_16x16x32_bf16 v[116:119], v[148:151], v[176:179], v[116:119]
	v_mfma_f32_16x16x32_bf16 v[112:115], v[168:171], v[176:179], v[112:115]
	v_mfma_f32_16x16x32_bf16 v[100:103], v[148:151], v[204:207], v[100:103]
	v_mfma_f32_16x16x32_bf16 v[96:99], v[168:171], v[204:207], v[96:99]
	v_mfma_f32_16x16x32_bf16 v[84:87], v[148:151], v[212:215], v[84:87]
	v_mfma_f32_16x16x32_bf16 v[80:83], v[168:171], v[212:215], v[80:83]
	v_mfma_f32_16x16x32_bf16 v[68:71], v[148:151], v[220:223], v[68:71]
	v_mfma_f32_16x16x32_bf16 v[64:67], v[168:171], v[220:223], v[64:67]
	v_mfma_f32_16x16x32_bf16 v[116:119], v[164:167], v[186:189], v[116:119]
	v_mfma_f32_16x16x32_bf16 v[112:115], v[172:175], v[186:189], v[112:115]
	v_mfma_f32_16x16x32_bf16 v[100:103], v[164:167], v[208:211], v[100:103]
	v_mfma_f32_16x16x32_bf16 v[96:99], v[172:175], v[208:211], v[96:99]
	v_mfma_f32_16x16x32_bf16 v[84:87], v[164:167], v[216:219], v[84:87]
	v_mfma_f32_16x16x32_bf16 v[80:83], v[172:175], v[216:219], v[80:83]
	v_mfma_f32_16x16x32_bf16 v[68:71], v[164:167], v[224:227], v[68:71]
	v_mfma_f32_16x16x32_bf16 v[64:67], v[172:175], v[224:227], v[64:67]
	s_setprio 0
	s_barrier
	ds_read_b128 v[176:179], v185 offset:49152
	ds_read_b128 v[186:189], v185 offset:50176
	ds_read_b128 v[204:207], v185 offset:51200
	ds_read_b128 v[208:211], v185 offset:52224
	ds_read_b128 v[212:215], v185 offset:53248
	ds_read_b128 v[216:219], v185 offset:54272
	ds_read_b128 v[220:223], v185 offset:55296
	ds_read_b128 v[224:227], v185 offset:56320
	s_add_u32 s100, s28, 0x80
	s_addc_u32 s101, s29, 0
	s_add_u32 s28, s28, 0x40080
	s_addc_u32 s29, s29, 0
	s_add_u32 s98, s98, 0x80
	s_addc_u32 s99, s99, 0
	s_add_i32 m0, s30, s38
	s_nop 0
	global_load_lds_dwordx4 v154, s[100:101]
	s_add_i32 m0, m0, 0x2000
	s_nop 0
	global_load_lds_dwordx4 v158, s[100:101]
	s_add_i32 m0, s31, s38
	s_nop 0
	global_load_lds_dwordx4 v154, s[28:29]
	s_add_i32 m0, m0, 0x2000
	s_nop 0
	global_load_lds_dwordx4 v158, s[28:29]
	s_mov_b32 m0, s50
	s_nop 0
	global_load_lds_dwordx4 v152, s[98:99]
	s_mov_b32 m0, s51
	s_nop 0
	global_load_lds_dwordx4 v156, s[98:99]
	s_waitcnt vmcnt(8)
	s_waitcnt lgkmcnt(0)
	s_setprio 1
	s_barrier
	v_mfma_f32_16x16x32_bf16 v[60:63], v[132:135], v[176:179], v[60:63]
	v_mfma_f32_16x16x32_bf16 v[56:59], v[140:143], v[176:179], v[56:59]
	v_mfma_f32_16x16x32_bf16 v[44:47], v[132:135], v[204:207], v[44:47]
	v_mfma_f32_16x16x32_bf16 v[40:43], v[140:143], v[204:207], v[40:43]
	v_mfma_f32_16x16x32_bf16 v[28:31], v[132:135], v[212:215], v[28:31]
	v_mfma_f32_16x16x32_bf16 v[24:27], v[140:143], v[212:215], v[24:27]
	v_mfma_f32_16x16x32_bf16 v[12:15], v[132:135], v[220:223], v[12:15]
	v_mfma_f32_16x16x32_bf16 v[8:11], v[140:143], v[220:223], v[8:11]
	v_mfma_f32_16x16x32_bf16 v[60:63], v[136:139], v[186:189], v[60:63]
	v_mfma_f32_16x16x32_bf16 v[56:59], v[144:147], v[186:189], v[56:59]
	v_mfma_f32_16x16x32_bf16 v[44:47], v[136:139], v[208:211], v[44:47]
	v_mfma_f32_16x16x32_bf16 v[40:43], v[144:147], v[208:211], v[40:43]
	v_mfma_f32_16x16x32_bf16 v[28:31], v[136:139], v[216:219], v[28:31]
	v_mfma_f32_16x16x32_bf16 v[24:27], v[144:147], v[216:219], v[24:27]
	v_mfma_f32_16x16x32_bf16 v[12:15], v[136:139], v[224:227], v[12:15]
	v_mfma_f32_16x16x32_bf16 v[8:11], v[144:147], v[224:227], v[8:11]
	v_mfma_f32_16x16x32_bf16 v[52:55], v[148:151], v[176:179], v[52:55]
	v_mfma_f32_16x16x32_bf16 v[48:51], v[168:171], v[176:179], v[48:51]
	v_mfma_f32_16x16x32_bf16 v[36:39], v[148:151], v[204:207], v[36:39]
	v_mfma_f32_16x16x32_bf16 v[32:35], v[168:171], v[204:207], v[32:35]
	v_mfma_f32_16x16x32_bf16 v[20:23], v[148:151], v[212:215], v[20:23]
	v_mfma_f32_16x16x32_bf16 v[16:19], v[168:171], v[212:215], v[16:19]
	v_mfma_f32_16x16x32_bf16 v[4:7], v[148:151], v[220:223], v[4:7]
	v_mfma_f32_16x16x32_bf16 v[0:3], v[168:171], v[220:223], v[0:3]
	v_mfma_f32_16x16x32_bf16 v[52:55], v[164:167], v[186:189], v[52:55]
	v_mfma_f32_16x16x32_bf16 v[48:51], v[172:175], v[186:189], v[48:51]
	v_mfma_f32_16x16x32_bf16 v[36:39], v[164:167], v[208:211], v[36:39]
	v_mfma_f32_16x16x32_bf16 v[32:35], v[172:175], v[208:211], v[32:35]
	v_mfma_f32_16x16x32_bf16 v[20:23], v[164:167], v[216:219], v[20:23]
	v_mfma_f32_16x16x32_bf16 v[16:19], v[172:175], v[216:219], v[16:19]
	v_mfma_f32_16x16x32_bf16 v[4:7], v[164:167], v[224:227], v[4:7]
	v_mfma_f32_16x16x32_bf16 v[0:3], v[172:175], v[224:227], v[0:3]
	s_setprio 0
	s_barrier
	s_add_i32 s58, s58, 2
	s_add_u32 s40, s40, 0x100
	s_addc_u32 s41, s41, 0
	s_cmp_gt_u32 s58, 13
	s_cbranch_scc0 .LBB0_611
	.p2align	6
	s_and_b64 vcc, exec, s[8:9]
	s_cbranch_vccz .LBB0_614
	s_barrier

; template <class Epi, class Sched, bool ALIGN_EPI = false, bool SP2 = false>
; __device__ __forceinline__ void gemm_phase(PG8_LAS unsigned char* lds, const Gemm g, const Sched& S, const Epi& E) {
;     ...
;         const bool has_next = S.next(ui + 1, nxt);
;         const char* nA = has_next ? (const char*)g.A + (size_t)nxt.pm * tstep : cA; const char* nB = has_next ? (const char*)g.Bt + (size_t)nxt.pn * tstep : cB;
;         for (int t = 0; t < nt; t += 2) {
;             const bool last = (t == nt - 2);
;             const char* a1 = cA + (size_t)(t + 1) * kstep;
;             const char* a2 = last ? nA : cA + (size_t)(t + 2) * kstep; const char* b2 = last ? nB : cB + (size_t)(t + 2) * kstep;
;             const char* a3 = a2 + kstep; const char* b3 = b2 + kstep;
;     ...
; #pragma unroll
;         for (int a = 0; a < 2; ++a)
; #pragma unroll
;             for (int b = 0; b < 2; ++b)
; #pragma unroll
;                 for (int m = 0; m < 4; ++m)
; #pragma unroll
;                     for (int n = 0; n < 2; ++n) acc[a][b][m][n] = (f32x4){0.f, 0.f, 0.f, 0.f};
;         cur = nxt; cA = nA; cB = nB; ++ui; relax = Epi::LOADS_BEFORE_STORES && !Epi::AFTER_DRAIN && SP2;
.LBB0_964:
	s_ashr_i32 s15, s14, 31
	s_lshl_b64 s[18:19], s[14:15], 21
	s_add_u32 s18, s2, s18
	s_addc_u32 s19, s3, s19
	s_and_b64 s[20:21], s[16:17], exec
	s_cselect_b32 s15, s19, s1
	s_cselect_b32 s23, s18, s0
	s_ashr_i32 s13, s12, 31
	s_lshl_b64 s[20:21], s[12:13], 21
	s_add_u32 s20, s37, s20
	s_addc_u32 s21, s38, s21
	s_and_b64 s[30:31], s[16:17], exec
	s_cselect_b32 s13, s21, s29
	s_cselect_b32 s53, s20, s28
	s_add_u32 s54, s28, 0x100
	s_addc_u32 s55, s29, 0
	s_add_u32 s28, s0, 0x100080
	s_addc_u32 s29, s1, 0
	v_mov_b32_e32 v0, 0
	v_lshl_add_u64 v[116:117], s[28:29], 0, v[210:211]
	v_lshl_add_u64 v[118:119], s[28:29], 0, v[212:213]
	s_mov_b32 s56, -2
	s_mov_b64 s[40:41], 0
	s_waitcnt lgkmcnt(0)
	v_mov_b32_e32 v1, v0
	v_mov_b32_e32 v2, v0
	v_mov_b32_e32 v3, v0
	v_mov_b32_e32 v4, v0
	v_mov_b32_e32 v5, v0
	v_mov_b32_e32 v6, v0
	v_mov_b32_e32 v7, v0
	v_mov_b32_e32 v16, v0
	v_mov_b32_e32 v17, v0
	v_mov_b32_e32 v18, v0
	v_mov_b32_e32 v19, v0
	v_mov_b32_e32 v20, v0
	v_mov_b32_e32 v21, v0
	v_mov_b32_e32 v22, v0
	v_mov_b32_e32 v23, v0
	v_mov_b32_e32 v32, v0
	v_mov_b32_e32 v33, v0
	v_mov_b32_e32 v34, v0
	v_mov_b32_e32 v35, v0
	v_mov_b32_e32 v36, v0
	v_mov_b32_e32 v37, v0
	v_mov_b32_e32 v38, v0
	v_mov_b32_e32 v39, v0
	v_mov_b32_e32 v48, v0
	v_mov_b32_e32 v49, v0
	v_mov_b32_e32 v50, v0
	v_mov_b32_e32 v51, v0
	v_mov_b32_e32 v52, v0
	v_mov_b32_e32 v53, v0
	v_mov_b32_e32 v54, v0
	v_mov_b32_e32 v55, v0
	v_mov_b32_e32 v8, v0
	v_mov_b32_e32 v9, v0
	v_mov_b32_e32 v10, v0
	v_mov_b32_e32 v11, v0
	v_mov_b32_e32 v12, v0
	v_mov_b32_e32 v13, v0
	v_mov_b32_e32 v14, v0
	v_mov_b32_e32 v15, v0
	v_mov_b32_e32 v24, v0
	v_mov_b32_e32 v25, v0
	v_mov_b32_e32 v26, v0
	v_mov_b32_e32 v27, v0
	v_mov_b32_e32 v28, v0
	v_mov_b32_e32 v29, v0
	v_mov_b32_e32 v30, v0
	v_mov_b32_e32 v31, v0
	v_mov_b32_e32 v40, v0
	v_mov_b32_e32 v41, v0
	v_mov_b32_e32 v42, v0
	v_mov_b32_e32 v43, v0
	v_mov_b32_e32 v44, v0
	v_mov_b32_e32 v45, v0
	v_mov_b32_e32 v46, v0
	v_mov_b32_e32 v47, v0
	v_mov_b32_e32 v56, v0
	v_mov_b32_e32 v57, v0
	v_mov_b32_e32 v58, v0
	v_mov_b32_e32 v59, v0
	v_mov_b32_e32 v60, v0
	v_mov_b32_e32 v61, v0
	v_mov_b32_e32 v62, v0
	v_mov_b32_e32 v63, v0
	v_mov_b32_e32 v64, v0
	v_mov_b32_e32 v65, v0
	v_mov_b32_e32 v66, v0
	v_mov_b32_e32 v67, v0
	v_mov_b32_e32 v68, v0
	v_mov_b32_e32 v69, v0
	v_mov_b32_e32 v70, v0
	v_mov_b32_e32 v71, v0
	v_mov_b32_e32 v80, v0
	v_mov_b32_e32 v81, v0
	v_mov_b32_e32 v82, v0
	v_mov_b32_e32 v83, v0
	v_mov_b32_e32 v84, v0
	v_mov_b32_e32 v85, v0
	v_mov_b32_e32 v86, v0
	v_mov_b32_e32 v87, v0
	v_mov_b32_e32 v96, v0
	v_mov_b32_e32 v97, v0
	v_mov_b32_e32 v98, v0
	v_mov_b32_e32 v99, v0
	v_mov_b32_e32 v100, v0
	v_mov_b32_e32 v101, v0
	v_mov_b32_e32 v102, v0
	v_mov_b32_e32 v103, v0
	v_mov_b32_e32 v112, v0
	v_mov_b32_e32 v113, v0
	v_mov_b32_e32 v114, v0
	v_mov_b32_e32 v115, v0
	v_mov_b32_e32 v124, v0
	v_mov_b32_e32 v125, v0
	v_mov_b32_e32 v126, v0
	v_mov_b32_e32 v127, v0
	v_mov_b32_e32 v72, v0
	v_mov_b32_e32 v73, v0
	v_mov_b32_e32 v74, v0
	v_mov_b32_e32 v75, v0
	v_mov_b32_e32 v76, v0
	v_mov_b32_e32 v77, v0
	v_mov_b32_e32 v78, v0
	v_mov_b32_e32 v79, v0
	v_mov_b32_e32 v88, v0
	v_mov_b32_e32 v89, v0
	v_mov_b32_e32 v90, v0
	v_mov_b32_e32 v91, v0
	v_mov_b32_e32 v92, v0
	v_mov_b32_e32 v93, v0
	v_mov_b32_e32 v94, v0
	v_mov_b32_e32 v95, v0
	v_mov_b32_e32 v104, v0
	v_mov_b32_e32 v105, v0
	v_mov_b32_e32 v106, v0
	v_mov_b32_e32 v107, v0
	v_mov_b32_e32 v108, v0
	v_mov_b32_e32 v109, v0
	v_mov_b32_e32 v110, v0
	v_mov_b32_e32 v111, v0
	v_mov_b32_e32 v148, v0
	v_mov_b32_e32 v149, v0
	v_mov_b32_e32 v150, v0
	v_mov_b32_e32 v151, v0
	v_mov_b32_e32 v152, v0
	v_mov_b32_e32 v153, v0
	v_mov_b32_e32 v154, v0
	v_mov_b32_e32 v155, v0
	.p2align	6
	s_nop 0
	s_nop 0
	s_nop 0
	s_nop 0
	s_nop 0
	s_nop 0

; #define PG8_STAGE(bufoff, gbase, voff) do { _Pragma("unroll") for (int _i = 0; _i < 2; ++_i) \
;         __builtin_amdgcn_global_load_lds((const unsigned*)((const char*)(gbase) + (voff)[_i]), (PG8_LAS unsigned*)(lds + (bufoff) + ldsw + _i * 8192), 16, 0, 0); } while (0)
; #define PG8_LDA(dst, b, h) do { _Pragma("unroll") for (int m = 0; m < 4; ++m) _Pragma("unroll") for (int k = 0; k < 2; ++k) dst[m][k] = *(const PG8_LAS bf16x8*)(lds + PG8_SA(b, h) + aoff + m * 2048 + k * 1024); } while (0)
; #define PG8_LDB(dst, b, h) do { _Pragma("unroll") for (int n = 0; n < 2; ++n) _Pragma("unroll") for (int k = 0; k < 2; ++k) dst[n][k] = *(const PG8_LAS bf16x8*)(lds + PG8_SB(b, h) + boff + n * 2048 + k * 1024); } while (0)
; #define PG8_MMA(ai, bj, At, Bt) do { __builtin_amdgcn_s_setprio(1); _Pragma("unroll") for (int m = 0; m < 4; ++m) _Pragma("unroll") for (int n = 0; n < 2; ++n) _Pragma("unroll") for (int k = 0; k < 2; ++k) \
;         acc[ai][bj][m][n] = __builtin_amdgcn_mfma_f32_16x16x32_bf16(Bt[n][k], At[m][k], acc[ai][bj][m][n], 0, 0, 0); __builtin_amdgcn_s_setprio(0); } while (0)
; #define PG8_WAIT_L(n) asm volatile("s_waitcnt lgkmcnt(" #n ")" ::: "memory")
; #define PG8_WAIT_V8_UNLESS(flag) asm volatile("s_cmp_lg_i32 %0, 0\n\ts_cbranch_scc1 .Lpg8rx%=\n\ts_waitcnt vmcnt(8)\n.Lpg8rx%=:" :: "s"(__builtin_amdgcn_readfirstlane(flag)) : "scc", "memory")
; #define PG8_BAR __builtin_amdgcn_s_barrier()
; #define PG8_SCHED __builtin_amdgcn_sched_barrier(0)
; template <class Epi, class Sched, bool ALIGN_EPI = false, bool SP2 = false>
; __device__ __forceinline__ void gemm_phase(PG8_LAS unsigned char* lds, const Gemm g, const Sched& S, const Epi& E) {
;     ...
;             PG8_STAGE(PG8_SA(1, 1), a1 + hstep, voffA); PG8_SCHED; PG8_LDB(B0, 0, 0); PG8_LDB(B1, 0, 1); PG8_SCHED; PG8_LDA(At, 0, 0);
;             PG8_WAIT_V8_UNLESS(rx); PG8_WAIT_L(0); PG8_BAR; PG8_MMA(0, 0, At, B0); PG8_MMA(0, 1, At, B1); PG8_BAR; PG8_SCHED;
;             PG8_STAGE(PG8_SB(0, 0), b2, voffB); PG8_STAGE(PG8_SB(0, 1), b2 + hstep, voffB); PG8_STAGE(PG8_SA(0, 0), a2, voffA); PG8_SCHED; PG8_LDA(At, 0, 1);
;             PG8_WAIT_V8_UNLESS(rx); PG8_WAIT_L(0); PG8_BAR; PG8_MMA(1, 0, At, B0); PG8_MMA(1, 1, At, B1); PG8_BAR; PG8_SCHED;
.Lpg8rx6:
	s_waitcnt lgkmcnt(0)
	s_setprio 1
	s_barrier
	v_mfma_f32_16x16x32_bf16 v[152:155], v[120:123], v[164:167], v[152:155]
	v_mfma_f32_16x16x32_bf16 v[148:151], v[132:135], v[164:167], v[148:151]
	v_mfma_f32_16x16x32_bf16 v[108:111], v[120:123], v[172:175], v[108:111]
	v_mfma_f32_16x16x32_bf16 v[104:107], v[132:135], v[172:175], v[104:107]
	v_mfma_f32_16x16x32_bf16 v[92:95], v[120:123], v[180:183], v[92:95]
	v_mfma_f32_16x16x32_bf16 v[88:91], v[132:135], v[180:183], v[88:91]
	v_mfma_f32_16x16x32_bf16 v[76:79], v[120:123], v[188:191], v[76:79]
	v_mfma_f32_16x16x32_bf16 v[72:75], v[132:135], v[188:191], v[72:75]
	v_mfma_f32_16x16x32_bf16 v[152:155], v[128:131], v[168:171], v[152:155]
	v_mfma_f32_16x16x32_bf16 v[148:151], v[136:139], v[168:171], v[148:151]
	v_mfma_f32_16x16x32_bf16 v[108:111], v[128:131], v[176:179], v[108:111]
	v_mfma_f32_16x16x32_bf16 v[104:107], v[136:139], v[176:179], v[104:107]
	v_mfma_f32_16x16x32_bf16 v[92:95], v[128:131], v[184:187], v[92:95]
	v_mfma_f32_16x16x32_bf16 v[88:91], v[136:139], v[184:187], v[88:91]
	v_mfma_f32_16x16x32_bf16 v[76:79], v[128:131], v[214:217], v[76:79]
	v_mfma_f32_16x16x32_bf16 v[72:75], v[136:139], v[214:217], v[72:75]
	v_mfma_f32_16x16x32_bf16 v[124:127], v[140:143], v[164:167], v[124:127]
	v_mfma_f32_16x16x32_bf16 v[112:115], v[156:159], v[164:167], v[112:115]
	v_mfma_f32_16x16x32_bf16 v[100:103], v[140:143], v[172:175], v[100:103]
	v_mfma_f32_16x16x32_bf16 v[96:99], v[156:159], v[172:175], v[96:99]
	v_mfma_f32_16x16x32_bf16 v[84:87], v[140:143], v[180:183], v[84:87]
	v_mfma_f32_16x16x32_bf16 v[80:83], v[156:159], v[180:183], v[80:83]
	v_mfma_f32_16x16x32_bf16 v[68:71], v[140:143], v[188:191], v[68:71]
	v_mfma_f32_16x16x32_bf16 v[64:67], v[156:159], v[188:191], v[64:67]
	v_mfma_f32_16x16x32_bf16 v[124:127], v[144:147], v[168:171], v[124:127]
	v_mfma_f32_16x16x32_bf16 v[112:115], v[160:163], v[168:171], v[112:115]
	v_mfma_f32_16x16x32_bf16 v[100:103], v[144:147], v[176:179], v[100:103]
	v_mfma_f32_16x16x32_bf16 v[96:99], v[160:163], v[176:179], v[96:99]
	v_mfma_f32_16x16x32_bf16 v[84:87], v[144:147], v[184:187], v[84:87]
	v_mfma_f32_16x16x32_bf16 v[80:83], v[160:163], v[184:187], v[80:83]
	v_mfma_f32_16x16x32_bf16 v[68:71], v[144:147], v[214:217], v[68:71]
	v_mfma_f32_16x16x32_bf16 v[64:67], v[160:163], v[214:217], v[64:67]
	s_setprio 0
	s_barrier
	ds_read_b128 v[164:167], v248 offset:16384
	ds_read_b128 v[168:171], v248 offset:17408
	ds_read_b128 v[172:175], v248 offset:18432
	ds_read_b128 v[176:179], v248 offset:19456
	ds_read_b128 v[180:183], v248 offset:20480
	ds_read_b128 v[184:187], v248 offset:21504
	ds_read_b128 v[188:191], v248 offset:22528
	ds_read_b128 v[214:217], v248 offset:23552
	s_add_u32 s58, s28, 0x100000
	s_addc_u32 s59, s29, 0
	s_add_i32 m0, s57, s39
	s_nop 0
	global_load_lds_dwordx4 v194, s[28:29]
	s_add_i32 m0, m0, 0x2000
	s_nop 0
	global_load_lds_dwordx4 v208, s[28:29]
	s_add_i32 m0, s60, s39
	s_nop 0
	global_load_lds_dwordx4 v194, s[58:59]
	s_add_i32 m0, m0, 0x2000
	s_nop 0
	global_load_lds_dwordx4 v208, s[58:59]
	s_mov_b32 m0, s25
	s_nop 0
	global_load_lds_dwordx4 v204, s[30:31]
	s_mov_b32 m0, s42
	s_nop 0
	global_load_lds_dwordx4 v206, s[30:31]
	s_cmp_lg_i32 s61, 0
	s_cbranch_scc1 .Lpg8rx7
	s_waitcnt vmcnt(8)
.Lpg8rx7:
	s_waitcnt lgkmcnt(0)
	s_setprio 1
	s_barrier
	v_mfma_f32_16x16x32_bf16 v[60:63], v[120:123], v[164:167], v[60:63]
	v_mfma_f32_16x16x32_bf16 v[56:59], v[132:135], v[164:167], v[56:59]
	v_mfma_f32_16x16x32_bf16 v[44:47], v[120:123], v[172:175], v[44:47]
	v_mfma_f32_16x16x32_bf16 v[40:43], v[132:135], v[172:175], v[40:43]
	v_mfma_f32_16x16x32_bf16 v[28:31], v[120:123], v[180:183], v[28:31]
	v_mfma_f32_16x16x32_bf16 v[24:27], v[132:135], v[180:183], v[24:27]
	v_mfma_f32_16x16x32_bf16 v[12:15], v[120:123], v[188:191], v[12:15]
	v_mfma_f32_16x16x32_bf16 v[8:11], v[132:135], v[188:191], v[8:11]
	v_mfma_f32_16x16x32_bf16 v[60:63], v[128:131], v[168:171], v[60:63]
	v_mfma_f32_16x16x32_bf16 v[56:59], v[136:139], v[168:171], v[56:59]
	v_mfma_f32_16x16x32_bf16 v[44:47], v[128:131], v[176:179], v[44:47]
	v_mfma_f32_16x16x32_bf16 v[40:43], v[136:139], v[176:179], v[40:43]
	v_mfma_f32_16x16x32_bf16 v[28:31], v[128:131], v[184:187], v[28:31]
	v_mfma_f32_16x16x32_bf16 v[24:27], v[136:139], v[184:187], v[24:27]
	v_mfma_f32_16x16x32_bf16 v[12:15], v[128:131], v[214:217], v[12:15]
	v_mfma_f32_16x16x32_bf16 v[8:11], v[136:139], v[214:217], v[8:11]
	v_mfma_f32_16x16x32_bf16 v[52:55], v[140:143], v[164:167], v[52:55]
	v_mfma_f32_16x16x32_bf16 v[48:51], v[156:159], v[164:167], v[48:51]
	v_mfma_f32_16x16x32_bf16 v[36:39], v[140:143], v[172:175], v[36:39]
	v_mfma_f32_16x16x32_bf16 v[32:35], v[156:159], v[172:175], v[32:35]
	v_mfma_f32_16x16x32_bf16 v[20:23], v[140:143], v[180:183], v[20:23]
	v_mfma_f32_16x16x32_bf16 v[16:19], v[156:159], v[180:183], v[16:19]
	v_mfma_f32_16x16x32_bf16 v[4:7], v[140:143], v[188:191], v[4:7]
	v_mfma_f32_16x16x32_bf16 v[0:3], v[156:159], v[188:191], v[0:3]
	v_mfma_f32_16x16x32_bf16 v[52:55], v[144:147], v[168:171], v[52:55]
	v_mfma_f32_16x16x32_bf16 v[48:51], v[160:163], v[168:171], v[48:51]
	v_mfma_f32_16x16x32_bf16 v[36:39], v[144:147], v[176:179], v[36:39]
	v_mfma_f32_16x16x32_bf16 v[32:35], v[160:163], v[176:179], v[32:35]
	v_mfma_f32_16x16x32_bf16 v[20:23], v[144:147], v[184:187], v[20:23]
	v_mfma_f32_16x16x32_bf16 v[16:19], v[160:163], v[184:187], v[16:19]
	v_mfma_f32_16x16x32_bf16 v[4:7], v[144:147], v[214:217], v[4:7]
	v_mfma_f32_16x16x32_bf16 v[0:3], v[160:163], v[214:217], v[0:3]
	s_setprio 0
	s_barrier
; #define PG8_STAGE(bufoff, gbase, voff) do { _Pragma("unroll") for (int _i = 0; _i < 2; ++_i) \
;         __builtin_amdgcn_global_load_lds((const unsigned*)((const char*)(gbase) + (voff)[_i]), (PG8_LAS unsigned*)(lds + (bufoff) + ldsw + _i * 8192), 16, 0, 0); } while (0)
; #define PG8_LDA(dst, b, h) do { _Pragma("unroll") for (int m = 0; m < 4; ++m) _Pragma("unroll") for (int k = 0; k < 2; ++k) dst[m][k] = *(const PG8_LAS bf16x8*)(lds + PG8_SA(b, h) + aoff + m * 2048 + k * 1024); } while (0)
; #define PG8_LDB(dst, b, h) do { _Pragma("unroll") for (int n = 0; n < 2; ++n) _Pragma("unroll") for (int k = 0; k < 2; ++k) dst[n][k] = *(const PG8_LAS bf16x8*)(lds + PG8_SB(b, h) + boff + n * 2048 + k * 1024); } while (0)
; #define PG8_MMA(ai, bj, At, Bt) do { __builtin_amdgcn_s_setprio(1); _Pragma("unroll") for (int m = 0; m < 4; ++m) _Pragma("unroll") for (int n = 0; n < 2; ++n) _Pragma("unroll") for (int k = 0; k < 2; ++k) \
;         acc[ai][bj][m][n] = __builtin_amdgcn_mfma_f32_16x16x32_bf16(Bt[n][k], At[m][k], acc[ai][bj][m][n], 0, 0, 0); __builtin_amdgcn_s_setprio(0); } while (0)
; #define PG8_WAIT_V(n) asm volatile("s_waitcnt vmcnt(" #n ")" ::: "memory")
; #define PG8_WAIT_L(n) asm volatile("s_waitcnt lgkmcnt(" #n ")" ::: "memory")
; #define PG8_BAR __builtin_amdgcn_s_barrier()
; #define PG8_SCHED __builtin_amdgcn_sched_barrier(0)
; template <class Epi, class Sched, bool ALIGN_EPI = false, bool SP2 = false>
; __device__ __forceinline__ void gemm_phase(PG8_LAS unsigned char* lds, const Gemm g, const Sched& S, const Epi& E) {
;     ...
;             PG8_STAGE(PG8_SA(0, 1), a2 + hstep, voffA); PG8_SCHED; PG8_LDB(B0, 1, 0); PG8_LDB(B1, 1, 1); PG8_SCHED; PG8_LDA(At, 1, 0);
;             PG8_WAIT_V(8); PG8_WAIT_L(0); PG8_BAR; PG8_MMA(0, 0, At, B0); PG8_MMA(0, 1, At, B1); PG8_BAR; PG8_SCHED;
;             PG8_STAGE(PG8_SB(1, 0), b3, voffB); PG8_STAGE(PG8_SB(1, 1), b3 + hstep, voffB); PG8_STAGE(PG8_SA(1, 0), a3, voffA); PG8_SCHED; PG8_LDA(At, 1, 1);
;             PG8_WAIT_V(8); PG8_WAIT_L(0); PG8_BAR; PG8_MMA(1, 0, At, B0); PG8_MMA(1, 1, At, B1); PG8_BAR; PG8_SCHED;
;     ...
;         if constexpr (ALIGN_EPI) { if (wr == 0) PG8_BAR; }
	s_mov_b64 s[98:99], s[30:31]
	s_add_u32 s100, s30, 0x100000
	s_addc_u32 s101, s31, 0
	s_add_i32 s30, 0, 0x18000
	s_add_i32 s31, 0, 0x1c000
	v_add_u32_e32 v136, s30, v247
	v_add_u32_e32 v160, s31, v247
	ds_read_b128 v[120:123], v136
	ds_read_b128 v[128:131], v136 offset:1024
	ds_read_b128 v[132:135], v136 offset:2048
	ds_read_b128 v[136:139], v136 offset:3072
	ds_read_b128 v[140:143], v160
	ds_read_b128 v[144:147], v160 offset:1024
	ds_read_b128 v[156:159], v160 offset:2048
	ds_read_b128 v[160:163], v160 offset:3072
	ds_read_b128 v[164:167], v248 offset:32768
	ds_read_b128 v[168:171], v248 offset:33792
	ds_read_b128 v[172:175], v248 offset:34816
	ds_read_b128 v[176:179], v248 offset:35840
	ds_read_b128 v[180:183], v248 offset:36864
	ds_read_b128 v[184:187], v248 offset:37888
	ds_read_b128 v[188:191], v248 offset:38912
	ds_read_b128 v[214:217], v248 offset:39936
	s_mov_b32 m0, s43
	s_nop 0
	global_load_lds_dwordx4 v204, s[100:101]
	s_mov_b32 m0, s44
	s_nop 0
	global_load_lds_dwordx4 v206, s[100:101]
	s_waitcnt vmcnt(8)
	s_waitcnt lgkmcnt(0)
	s_setprio 1
	s_barrier
	v_mfma_f32_16x16x32_bf16 v[152:155], v[120:123], v[164:167], v[152:155]
	v_mfma_f32_16x16x32_bf16 v[148:151], v[132:135], v[164:167], v[148:151]
	v_mfma_f32_16x16x32_bf16 v[108:111], v[120:123], v[172:175], v[108:111]
	v_mfma_f32_16x16x32_bf16 v[104:107], v[132:135], v[172:175], v[104:107]
	v_mfma_f32_16x16x32_bf16 v[92:95], v[120:123], v[180:183], v[92:95]
	v_mfma_f32_16x16x32_bf16 v[88:91], v[132:135], v[180:183], v[88:91]
	v_mfma_f32_16x16x32_bf16 v[76:79], v[120:123], v[188:191], v[76:79]
	v_mfma_f32_16x16x32_bf16 v[72:75], v[132:135], v[188:191], v[72:75]
	v_mfma_f32_16x16x32_bf16 v[152:155], v[128:131], v[168:171], v[152:155]
	v_mfma_f32_16x16x32_bf16 v[148:151], v[136:139], v[168:171], v[148:151]
	v_mfma_f32_16x16x32_bf16 v[108:111], v[128:131], v[176:179], v[108:111]
	v_mfma_f32_16x16x32_bf16 v[104:107], v[136:139], v[176:179], v[104:107]
	v_mfma_f32_16x16x32_bf16 v[92:95], v[128:131], v[184:187], v[92:95]
	v_mfma_f32_16x16x32_bf16 v[88:91], v[136:139], v[184:187], v[88:91]
	v_mfma_f32_16x16x32_bf16 v[76:79], v[128:131], v[214:217], v[76:79]
	v_mfma_f32_16x16x32_bf16 v[72:75], v[136:139], v[214:217], v[72:75]
	v_mfma_f32_16x16x32_bf16 v[124:127], v[140:143], v[164:167], v[124:127]
	v_mfma_f32_16x16x32_bf16 v[112:115], v[156:159], v[164:167], v[112:115]
	v_mfma_f32_16x16x32_bf16 v[100:103], v[140:143], v[172:175], v[100:103]
	v_mfma_f32_16x16x32_bf16 v[96:99], v[156:159], v[172:175], v[96:99]
	v_mfma_f32_16x16x32_bf16 v[84:87], v[140:143], v[180:183], v[84:87]
	v_mfma_f32_16x16x32_bf16 v[80:83], v[156:159], v[180:183], v[80:83]
	v_mfma_f32_16x16x32_bf16 v[68:71], v[140:143], v[188:191], v[68:71]
	v_mfma_f32_16x16x32_bf16 v[64:67], v[156:159], v[188:191], v[64:67]
	v_mfma_f32_16x16x32_bf16 v[124:127], v[144:147], v[168:171], v[124:127]
	v_mfma_f32_16x16x32_bf16 v[112:115], v[160:163], v[168:171], v[112:115]
	v_mfma_f32_16x16x32_bf16 v[100:103], v[144:147], v[176:179], v[100:103]
	v_mfma_f32_16x16x32_bf16 v[96:99], v[160:163], v[176:179], v[96:99]
	v_mfma_f32_16x16x32_bf16 v[84:87], v[144:147], v[184:187], v[84:87]
	v_mfma_f32_16x16x32_bf16 v[80:83], v[160:163], v[184:187], v[80:83]
	v_mfma_f32_16x16x32_bf16 v[68:71], v[144:147], v[214:217], v[68:71]
	v_mfma_f32_16x16x32_bf16 v[64:67], v[160:163], v[214:217], v[64:67]
	s_setprio 0
	s_barrier
	ds_read_b128 v[164:167], v248 offset:49152
	ds_read_b128 v[168:171], v248 offset:50176
	ds_read_b128 v[172:175], v248 offset:51200
	ds_read_b128 v[176:179], v248 offset:52224
	ds_read_b128 v[180:183], v248 offset:53248
	ds_read_b128 v[184:187], v248 offset:54272
	ds_read_b128 v[188:191], v248 offset:55296
	ds_read_b128 v[214:217], v248 offset:56320
	s_add_u32 s100, s28, 0x80
	s_addc_u32 s101, s29, 0
	s_add_u32 s28, s28, 0x100080
	s_addc_u32 s29, s29, 0
	s_add_u32 s98, s98, 0x80
	s_addc_u32 s99, s99, 0
	s_add_i32 m0, s30, s39
	s_nop 0
	global_load_lds_dwordx4 v194, s[100:101]
	s_add_i32 m0, m0, 0x2000
	s_nop 0
	global_load_lds_dwordx4 v208, s[100:101]
	s_add_i32 m0, s31, s39
	s_nop 0
	global_load_lds_dwordx4 v194, s[28:29]
	s_add_i32 m0, m0, 0x2000
	s_nop 0
	global_load_lds_dwordx4 v208, s[28:29]
	s_mov_b32 m0, s46
	s_nop 0
	global_load_lds_dwordx4 v204, s[98:99]
	s_mov_b32 m0, s48
	s_nop 0
	global_load_lds_dwordx4 v206, s[98:99]
	s_waitcnt vmcnt(8)
	s_waitcnt lgkmcnt(0)
	s_setprio 1
	s_barrier
	v_mfma_f32_16x16x32_bf16 v[60:63], v[120:123], v[164:167], v[60:63]
	v_mfma_f32_16x16x32_bf16 v[56:59], v[132:135], v[164:167], v[56:59]
	v_mfma_f32_16x16x32_bf16 v[44:47], v[120:123], v[172:175], v[44:47]
	v_mfma_f32_16x16x32_bf16 v[40:43], v[132:135], v[172:175], v[40:43]
	v_mfma_f32_16x16x32_bf16 v[28:31], v[120:123], v[180:183], v[28:31]
	v_mfma_f32_16x16x32_bf16 v[24:27], v[132:135], v[180:183], v[24:27]
	v_mfma_f32_16x16x32_bf16 v[12:15], v[120:123], v[188:191], v[12:15]
	v_mfma_f32_16x16x32_bf16 v[8:11], v[132:135], v[188:191], v[8:11]
	v_mfma_f32_16x16x32_bf16 v[60:63], v[128:131], v[168:171], v[60:63]
	v_mfma_f32_16x16x32_bf16 v[56:59], v[136:139], v[168:171], v[56:59]
	v_mfma_f32_16x16x32_bf16 v[44:47], v[128:131], v[176:179], v[44:47]
	v_mfma_f32_16x16x32_bf16 v[40:43], v[136:139], v[176:179], v[40:43]
	v_mfma_f32_16x16x32_bf16 v[28:31], v[128:131], v[184:187], v[28:31]
	v_mfma_f32_16x16x32_bf16 v[24:27], v[136:139], v[184:187], v[24:27]
	v_mfma_f32_16x16x32_bf16 v[12:15], v[128:131], v[214:217], v[12:15]
	v_mfma_f32_16x16x32_bf16 v[8:11], v[136:139], v[214:217], v[8:11]
	v_mfma_f32_16x16x32_bf16 v[52:55], v[140:143], v[164:167], v[52:55]
	v_mfma_f32_16x16x32_bf16 v[48:51], v[156:159], v[164:167], v[48:51]
	v_mfma_f32_16x16x32_bf16 v[36:39], v[140:143], v[172:175], v[36:39]
	v_mfma_f32_16x16x32_bf16 v[32:35], v[156:159], v[172:175], v[32:35]
	v_mfma_f32_16x16x32_bf16 v[20:23], v[140:143], v[180:183], v[20:23]
	v_mfma_f32_16x16x32_bf16 v[16:19], v[156:159], v[180:183], v[16:19]
	v_mfma_f32_16x16x32_bf16 v[4:7], v[140:143], v[188:191], v[4:7]
	v_mfma_f32_16x16x32_bf16 v[0:3], v[156:159], v[188:191], v[0:3]
	v_mfma_f32_16x16x32_bf16 v[52:55], v[144:147], v[168:171], v[52:55]
	v_mfma_f32_16x16x32_bf16 v[48:51], v[160:163], v[168:171], v[48:51]
	v_mfma_f32_16x16x32_bf16 v[36:39], v[144:147], v[176:179], v[36:39]
	v_mfma_f32_16x16x32_bf16 v[32:35], v[160:163], v[176:179], v[32:35]
	v_mfma_f32_16x16x32_bf16 v[20:23], v[144:147], v[184:187], v[20:23]
	v_mfma_f32_16x16x32_bf16 v[16:19], v[160:163], v[184:187], v[16:19]
	v_mfma_f32_16x16x32_bf16 v[4:7], v[144:147], v[214:217], v[4:7]
	v_mfma_f32_16x16x32_bf16 v[0:3], v[160:163], v[214:217], v[0:3]
	s_setprio 0
	s_barrier
	s_add_i32 s56, s56, 2
	s_add_u32 s40, s40, 0x100
	s_addc_u32 s41, s41, 0
	s_cmp_gt_u32 s56, 61
	s_cbranch_scc0 .LBB0_965
	.p2align	6
	s_and_b64 vcc, exec, s[10:11]
	s_cbranch_vccz .LBB0_968
	s_barrier

; template <class Epi, class Sched, bool ALIGN_EPI = false, bool SP2 = false>
; __device__ __forceinline__ void gemm_phase(PG8_LAS unsigned char* lds, const Gemm g, const Sched& S, const Epi& E) {
;     ...
;     Unit cur, nxt; int ui = 0; bool relax = false;
;     if (!S.next(0, cur)) return;
;     f32x4 acc[2][2][4][2];
; #pragma unroll
;     for (int a = 0; a < 2; ++a)
; #pragma unroll
;         for (int b = 0; b < 2; ++b)
; #pragma unroll
;             for (int m = 0; m < 4; ++m)
; #pragma unroll
;                 for (int n = 0; n < 2; ++n) acc[a][b][m][n] = (f32x4){0.f, 0.f, 0.f, 0.f};
;     bf16x8 At[4][2], B0[2][2], B1[2][2];
;     const char* cA = (const char*)g.A + (size_t)cur.pm * tstep; const char* cB = (const char*)g.Bt + (size_t)cur.pn * tstep;
;     ...
;         const bool has_next = S.next(ui + 1, nxt);
;         const char* nA = has_next ? (const char*)g.A + (size_t)nxt.pm * tstep : cA; const char* nB = has_next ? (const char*)g.Bt + (size_t)nxt.pn * tstep : cB;
;         for (int t = 0; t < nt; t += 2) {
;             const bool last = (t == nt - 2);
;             const char* a1 = cA + (size_t)(t + 1) * kstep;
;             const char* a2 = last ? nA : cA + (size_t)(t + 2) * kstep; const char* b2 = last ? nB : cB + (size_t)(t + 2) * kstep;
;             const char* a3 = a2 + kstep; const char* b3 = b2 + kstep;
.LBB0_1089:
	v_mov_b32_e32 v123, 0
	s_andn2_b64 vcc, exec, s[14:15]
	v_mov_b32_e32 v122, v123
	v_mov_b32_e32 v121, v123
	v_mov_b32_e32 v120, v123
	v_mov_b32_e32 v127, v123
	v_mov_b32_e32 v126, v123
	v_mov_b32_e32 v125, v123
	v_mov_b32_e32 v124, v123
	v_mov_b32_e32 v111, v123
	v_mov_b32_e32 v110, v123
	v_mov_b32_e32 v109, v123
	v_mov_b32_e32 v108, v123
	v_mov_b32_e32 v107, v123
	v_mov_b32_e32 v106, v123
	v_mov_b32_e32 v105, v123
	v_mov_b32_e32 v104, v123
	v_mov_b32_e32 v95, v123
	v_mov_b32_e32 v94, v123
	v_mov_b32_e32 v93, v123
	v_mov_b32_e32 v92, v123
	v_mov_b32_e32 v91, v123
	v_mov_b32_e32 v90, v123
	v_mov_b32_e32 v89, v123
	v_mov_b32_e32 v88, v123
	v_mov_b32_e32 v79, v123
	v_mov_b32_e32 v78, v123
	v_mov_b32_e32 v77, v123
	v_mov_b32_e32 v76, v123
	v_mov_b32_e32 v75, v123
	v_mov_b32_e32 v74, v123
	v_mov_b32_e32 v73, v123
	v_mov_b32_e32 v72, v123
	v_mov_b32_e32 v119, v123
	v_mov_b32_e32 v118, v123
	v_mov_b32_e32 v117, v123
	v_mov_b32_e32 v116, v123
	v_mov_b32_e32 v115, v123
	v_mov_b32_e32 v114, v123
	v_mov_b32_e32 v113, v123
	v_mov_b32_e32 v112, v123
	v_mov_b32_e32 v103, v123
	v_mov_b32_e32 v102, v123
	v_mov_b32_e32 v101, v123
	v_mov_b32_e32 v100, v123
	v_mov_b32_e32 v99, v123
	v_mov_b32_e32 v98, v123
	v_mov_b32_e32 v97, v123
	v_mov_b32_e32 v96, v123
	v_mov_b32_e32 v87, v123
	v_mov_b32_e32 v86, v123
	v_mov_b32_e32 v85, v123
	v_mov_b32_e32 v84, v123
	v_mov_b32_e32 v83, v123
	v_mov_b32_e32 v82, v123
	v_mov_b32_e32 v81, v123
	v_mov_b32_e32 v80, v123
	v_mov_b32_e32 v71, v123
	v_mov_b32_e32 v70, v123
	v_mov_b32_e32 v69, v123
	v_mov_b32_e32 v68, v123
	v_mov_b32_e32 v67, v123
	v_mov_b32_e32 v66, v123
	v_mov_b32_e32 v65, v123
	v_mov_b32_e32 v64, v123
	v_mov_b32_e32 v63, v123
	v_mov_b32_e32 v62, v123
	v_mov_b32_e32 v61, v123
	v_mov_b32_e32 v60, v123
	v_mov_b32_e32 v59, v123
	v_mov_b32_e32 v58, v123
	v_mov_b32_e32 v57, v123
	v_mov_b32_e32 v56, v123
	v_mov_b32_e32 v47, v123
	v_mov_b32_e32 v46, v123
	v_mov_b32_e32 v45, v123
	v_mov_b32_e32 v44, v123
	v_mov_b32_e32 v43, v123
	v_mov_b32_e32 v42, v123
	v_mov_b32_e32 v41, v123
	v_mov_b32_e32 v40, v123
	v_mov_b32_e32 v31, v123
	v_mov_b32_e32 v30, v123
	v_mov_b32_e32 v29, v123
	v_mov_b32_e32 v28, v123
	v_mov_b32_e32 v27, v123
	v_mov_b32_e32 v26, v123
	v_mov_b32_e32 v25, v123
	v_mov_b32_e32 v24, v123
	v_mov_b32_e32 v15, v123
	v_mov_b32_e32 v14, v123
	v_mov_b32_e32 v13, v123
	v_mov_b32_e32 v12, v123
	v_mov_b32_e32 v11, v123
	v_mov_b32_e32 v10, v123
	v_mov_b32_e32 v9, v123
	v_mov_b32_e32 v8, v123
	v_mov_b32_e32 v55, v123
	v_mov_b32_e32 v54, v123
	v_mov_b32_e32 v53, v123
	v_mov_b32_e32 v52, v123
	v_mov_b32_e32 v51, v123
	v_mov_b32_e32 v50, v123
	v_mov_b32_e32 v49, v123
	v_mov_b32_e32 v48, v123
	v_mov_b32_e32 v39, v123
	v_mov_b32_e32 v38, v123
	v_mov_b32_e32 v37, v123
	v_mov_b32_e32 v36, v123
	v_mov_b32_e32 v35, v123
	v_mov_b32_e32 v34, v123
	v_mov_b32_e32 v33, v123
	v_mov_b32_e32 v32, v123
	v_mov_b32_e32 v23, v123
	v_mov_b32_e32 v22, v123
	v_mov_b32_e32 v21, v123
	v_mov_b32_e32 v20, v123
	v_mov_b32_e32 v19, v123
	v_mov_b32_e32 v18, v123
	v_mov_b32_e32 v17, v123
	v_mov_b32_e32 v16, v123
	v_mov_b32_e32 v7, v123
	v_mov_b32_e32 v6, v123
	v_mov_b32_e32 v5, v123
	v_mov_b32_e32 v4, v123
	v_mov_b32_e32 v3, v123
	v_mov_b32_e32 v2, v123
	v_mov_b32_e32 v1, v123
	v_mov_b32_e32 v0, v123
	s_cbranch_vccnz .LBB0_1092
	s_add_u32 s22, s22, 0x80
	s_addc_u32 s23, s23, 0
	s_add_u32 s60, s24, 0x100
	v_mov_b32_e32 v0, 0
	s_addc_u32 s61, s25, 0
	s_mov_b32 s24, 0
	v_mov_b32_e32 v1, v0
	v_mov_b32_e32 v2, v0
	v_mov_b32_e32 v3, v0
	v_mov_b32_e32 v4, v0
	v_mov_b32_e32 v5, v0
	v_mov_b32_e32 v6, v0
	v_mov_b32_e32 v7, v0
	v_mov_b32_e32 v16, v0
	v_mov_b32_e32 v17, v0
	v_mov_b32_e32 v18, v0
	v_mov_b32_e32 v19, v0
	v_mov_b32_e32 v20, v0
	v_mov_b32_e32 v21, v0
	v_mov_b32_e32 v22, v0
	v_mov_b32_e32 v23, v0
	v_mov_b32_e32 v32, v0
	v_mov_b32_e32 v33, v0
	v_mov_b32_e32 v34, v0
	v_mov_b32_e32 v35, v0
	v_mov_b32_e32 v36, v0
	v_mov_b32_e32 v37, v0
	v_mov_b32_e32 v38, v0
	v_mov_b32_e32 v39, v0
	v_mov_b32_e32 v48, v0
	v_mov_b32_e32 v49, v0
	v_mov_b32_e32 v50, v0
	v_mov_b32_e32 v51, v0
	v_mov_b32_e32 v52, v0
	v_mov_b32_e32 v53, v0
	v_mov_b32_e32 v54, v0
	v_mov_b32_e32 v55, v0
	v_mov_b32_e32 v8, v0
	v_mov_b32_e32 v9, v0
	v_mov_b32_e32 v10, v0
	v_mov_b32_e32 v11, v0
	v_mov_b32_e32 v12, v0
	v_mov_b32_e32 v13, v0
	v_mov_b32_e32 v14, v0
	v_mov_b32_e32 v15, v0
	v_mov_b32_e32 v24, v0
	v_mov_b32_e32 v25, v0
	v_mov_b32_e32 v26, v0
	v_mov_b32_e32 v27, v0
	v_mov_b32_e32 v28, v0
	v_mov_b32_e32 v29, v0
	v_mov_b32_e32 v30, v0
	v_mov_b32_e32 v31, v0
	v_mov_b32_e32 v40, v0
	v_mov_b32_e32 v41, v0
	v_mov_b32_e32 v42, v0
	v_mov_b32_e32 v43, v0
	v_mov_b32_e32 v44, v0
	v_mov_b32_e32 v45, v0
	v_mov_b32_e32 v46, v0
	v_mov_b32_e32 v47, v0
	v_mov_b32_e32 v56, v0
	v_mov_b32_e32 v57, v0
	v_mov_b32_e32 v58, v0
	v_mov_b32_e32 v59, v0
	v_mov_b32_e32 v60, v0
	v_mov_b32_e32 v61, v0
	v_mov_b32_e32 v62, v0
	v_mov_b32_e32 v63, v0
	v_mov_b32_e32 v64, v0
	v_mov_b32_e32 v65, v0
	v_mov_b32_e32 v66, v0
	v_mov_b32_e32 v67, v0
	v_mov_b32_e32 v68, v0
	v_mov_b32_e32 v69, v0
	v_mov_b32_e32 v70, v0
	v_mov_b32_e32 v71, v0
	v_mov_b32_e32 v80, v0
	v_mov_b32_e32 v81, v0
	v_mov_b32_e32 v82, v0
	v_mov_b32_e32 v83, v0
	v_mov_b32_e32 v84, v0
	v_mov_b32_e32 v85, v0
	v_mov_b32_e32 v86, v0
	v_mov_b32_e32 v87, v0
	v_mov_b32_e32 v96, v0
	v_mov_b32_e32 v97, v0
	v_mov_b32_e32 v98, v0
	v_mov_b32_e32 v99, v0
	v_mov_b32_e32 v100, v0
	v_mov_b32_e32 v101, v0
	v_mov_b32_e32 v102, v0
	v_mov_b32_e32 v103, v0
	v_mov_b32_e32 v112, v0
	v_mov_b32_e32 v113, v0
	v_mov_b32_e32 v114, v0
	v_mov_b32_e32 v115, v0
	v_mov_b32_e32 v116, v0
	v_mov_b32_e32 v117, v0
	v_mov_b32_e32 v118, v0
	v_mov_b32_e32 v119, v0
	v_mov_b32_e32 v72, v0
	v_mov_b32_e32 v73, v0
	v_mov_b32_e32 v74, v0
	v_mov_b32_e32 v75, v0
	v_mov_b32_e32 v76, v0
	v_mov_b32_e32 v77, v0
	v_mov_b32_e32 v78, v0
	v_mov_b32_e32 v79, v0
	v_mov_b32_e32 v88, v0
	v_mov_b32_e32 v89, v0
	v_mov_b32_e32 v90, v0
	v_mov_b32_e32 v91, v0
	v_mov_b32_e32 v92, v0
	v_mov_b32_e32 v93, v0
	v_mov_b32_e32 v94, v0
	v_mov_b32_e32 v95, v0
	v_mov_b32_e32 v104, v0
	v_mov_b32_e32 v105, v0
	v_mov_b32_e32 v106, v0
	v_mov_b32_e32 v107, v0
	v_mov_b32_e32 v108, v0
	v_mov_b32_e32 v109, v0
	v_mov_b32_e32 v110, v0
	v_mov_b32_e32 v111, v0
	v_mov_b32_e32 v124, v0
	v_mov_b32_e32 v125, v0
	v_mov_b32_e32 v126, v0
	v_mov_b32_e32 v127, v0
	v_mov_b32_e32 v120, v0
	v_mov_b32_e32 v121, v0
	v_mov_b32_e32 v122, v0
	v_mov_b32_e32 v123, v0
	.p2align	6

; #define PG8_STAGE(bufoff, gbase, voff) do { _Pragma("unroll") for (int _i = 0; _i < 2; ++_i) \
;         __builtin_amdgcn_global_load_lds((const unsigned*)((const char*)(gbase) + (voff)[_i]), (PG8_LAS unsigned*)(lds + (bufoff) + ldsw + _i * 8192), 16, 0, 0); } while (0)
; #define PG8_LDA(dst, b, h) do { _Pragma("unroll") for (int m = 0; m < 4; ++m) _Pragma("unroll") for (int k = 0; k < 2; ++k) dst[m][k] = *(const PG8_LAS bf16x8*)(lds + PG8_SA(b, h) + aoff + m * 2048 + k * 1024); } while (0)
; #define PG8_LDB(dst, b, h) do { _Pragma("unroll") for (int n = 0; n < 2; ++n) _Pragma("unroll") for (int k = 0; k < 2; ++k) dst[n][k] = *(const PG8_LAS bf16x8*)(lds + PG8_SB(b, h) + boff + n * 2048 + k * 1024); } while (0)
; #define PG8_MMA(ai, bj, At, Bt) do { __builtin_amdgcn_s_setprio(1); _Pragma("unroll") for (int m = 0; m < 4; ++m) _Pragma("unroll") for (int n = 0; n < 2; ++n) _Pragma("unroll") for (int k = 0; k < 2; ++k) \
;         acc[ai][bj][m][n] = __builtin_amdgcn_mfma_f32_16x16x32_bf16(Bt[n][k], At[m][k], acc[ai][bj][m][n], 0, 0, 0); __builtin_amdgcn_s_setprio(0); } while (0)
; #define PG8_WAIT_L(n) asm volatile("s_waitcnt lgkmcnt(" #n ")" ::: "memory")
; #define PG8_WAIT_V8_UNLESS(flag) asm volatile("s_cmp_lg_i32 %0, 0\n\ts_cbranch_scc1 .Lpg8rx%=\n\ts_waitcnt vmcnt(8)\n.Lpg8rx%=:" :: "s"(__builtin_amdgcn_readfirstlane(flag)) : "scc", "memory")
; #define PG8_BAR __builtin_amdgcn_s_barrier()
; #define PG8_SCHED __builtin_amdgcn_sched_barrier(0)
; template <class Epi, class Sched, bool ALIGN_EPI = false, bool SP2 = false>
; __device__ __forceinline__ void gemm_phase(PG8_LAS unsigned char* lds, const Gemm g, const Sched& S, const Epi& E) {
;     ...
;             PG8_STAGE(PG8_SA(1, 1), a1 + hstep, voffA); PG8_SCHED; PG8_LDB(B0, 0, 0); PG8_LDB(B1, 0, 1); PG8_SCHED; PG8_LDA(At, 0, 0);
;             PG8_WAIT_V8_UNLESS(rx); PG8_WAIT_L(0); PG8_BAR; PG8_MMA(0, 0, At, B0); PG8_MMA(0, 1, At, B1); PG8_BAR; PG8_SCHED;
;             PG8_STAGE(PG8_SB(0, 0), b2, voffB); PG8_STAGE(PG8_SB(0, 1), b2 + hstep, voffB); PG8_STAGE(PG8_SA(0, 0), a2, voffA); PG8_SCHED; PG8_LDA(At, 0, 1);
;             PG8_WAIT_V8_UNLESS(rx); PG8_WAIT_L(0); PG8_BAR; PG8_MMA(1, 0, At, B0); PG8_MMA(1, 1, At, B1); PG8_BAR; PG8_SCHED;
.Lpg8rx8:
	s_waitcnt lgkmcnt(0)
	s_setprio 1
	s_barrier
	v_mfma_f32_16x16x32_bf16 v[120:123], v[140:143], v[172:175], v[120:123]
	v_mfma_f32_16x16x32_bf16 v[124:127], v[148:151], v[172:175], v[124:127]
	v_mfma_f32_16x16x32_bf16 v[108:111], v[140:143], v[180:183], v[108:111]
	v_mfma_f32_16x16x32_bf16 v[104:107], v[148:151], v[180:183], v[104:107]
	v_mfma_f32_16x16x32_bf16 v[92:95], v[140:143], v[188:191], v[92:95]
	v_mfma_f32_16x16x32_bf16 v[88:91], v[148:151], v[188:191], v[88:91]
	v_mfma_f32_16x16x32_bf16 v[76:79], v[140:143], v[208:211], v[76:79]
	v_mfma_f32_16x16x32_bf16 v[72:75], v[148:151], v[208:211], v[72:75]
	v_mfma_f32_16x16x32_bf16 v[120:123], v[144:147], v[176:179], v[120:123]
	v_mfma_f32_16x16x32_bf16 v[124:127], v[152:155], v[176:179], v[124:127]
	v_mfma_f32_16x16x32_bf16 v[108:111], v[144:147], v[184:187], v[108:111]
	v_mfma_f32_16x16x32_bf16 v[104:107], v[152:155], v[184:187], v[104:107]
	v_mfma_f32_16x16x32_bf16 v[92:95], v[144:147], v[204:207], v[92:95]
	v_mfma_f32_16x16x32_bf16 v[88:91], v[152:155], v[204:207], v[88:91]
	v_mfma_f32_16x16x32_bf16 v[76:79], v[144:147], v[212:215], v[76:79]
	v_mfma_f32_16x16x32_bf16 v[72:75], v[152:155], v[212:215], v[72:75]
	v_mfma_f32_16x16x32_bf16 v[116:119], v[156:159], v[172:175], v[116:119]
	v_mfma_f32_16x16x32_bf16 v[112:115], v[164:167], v[172:175], v[112:115]
	v_mfma_f32_16x16x32_bf16 v[100:103], v[156:159], v[180:183], v[100:103]
	v_mfma_f32_16x16x32_bf16 v[96:99], v[164:167], v[180:183], v[96:99]
	v_mfma_f32_16x16x32_bf16 v[84:87], v[156:159], v[188:191], v[84:87]
	v_mfma_f32_16x16x32_bf16 v[80:83], v[164:167], v[188:191], v[80:83]
	v_mfma_f32_16x16x32_bf16 v[68:71], v[156:159], v[208:211], v[68:71]
	v_mfma_f32_16x16x32_bf16 v[64:67], v[164:167], v[208:211], v[64:67]
	v_mfma_f32_16x16x32_bf16 v[116:119], v[160:163], v[176:179], v[116:119]
	v_mfma_f32_16x16x32_bf16 v[112:115], v[168:171], v[176:179], v[112:115]
	v_mfma_f32_16x16x32_bf16 v[100:103], v[160:163], v[184:187], v[100:103]
	v_mfma_f32_16x16x32_bf16 v[96:99], v[168:171], v[184:187], v[96:99]
	v_mfma_f32_16x16x32_bf16 v[84:87], v[160:163], v[204:207], v[84:87]
	v_mfma_f32_16x16x32_bf16 v[80:83], v[168:171], v[204:207], v[80:83]
	v_mfma_f32_16x16x32_bf16 v[68:71], v[160:163], v[212:215], v[68:71]
	v_mfma_f32_16x16x32_bf16 v[64:67], v[168:171], v[212:215], v[64:67]
	s_setprio 0
	s_barrier
	s_add_i32 s63, s63, s34
	v_lshl_add_u64 v[216:217], s[66:67], 0, v[194:195]
	s_mov_b32 m0, s63
	v_lshl_add_u64 v[218:219], s[66:67], 0, v[132:133]
	global_load_lds_dwordx4 v[216:217], off
	s_add_i32 m0, s63, 0x2000
	s_add_u32 s66, s66, s8
	s_addc_u32 s67, s67, s9
	s_add_i32 s63, s65, s34
	global_load_lds_dwordx4 v[218:219], off
	v_lshl_add_u64 v[220:221], s[66:67], 0, v[194:195]
	s_mov_b32 m0, s63
	v_lshl_add_u64 v[222:223], s[66:67], 0, v[132:133]
	global_load_lds_dwordx4 v[220:221], off
	s_add_i32 m0, s63, 0x2000
	v_lshl_add_u64 v[224:225], s[24:25], 0, v[128:129]
	global_load_lds_dwordx4 v[222:223], off
	s_mov_b32 m0, s43
	v_lshl_add_u64 v[226:227], s[24:25], 0, v[130:131]
	global_load_lds_dwordx4 v[224:225], off
	s_mov_b32 m0, s44
	s_nop 0
	global_load_lds_dwordx4 v[226:227], off
	ds_read_b128 v[172:175], v139 offset:16384
	ds_read_b128 v[176:179], v139 offset:17408
	ds_read_b128 v[180:183], v139 offset:18432
	ds_read_b128 v[184:187], v139 offset:19456
	ds_read_b128 v[188:191], v139 offset:20480
	ds_read_b128 v[204:207], v139 offset:21504
	ds_read_b128 v[208:211], v139 offset:22528
	ds_read_b128 v[212:215], v139 offset:23552
	s_cmp_lg_i32 s73, 0
	s_cbranch_scc1 .Lpg8rx9
	s_waitcnt vmcnt(8)
.Lpg8rx9:
	s_waitcnt lgkmcnt(0)
	s_setprio 1
	s_barrier
	v_mfma_f32_16x16x32_bf16 v[60:63], v[140:143], v[172:175], v[60:63]
	v_mfma_f32_16x16x32_bf16 v[56:59], v[148:151], v[172:175], v[56:59]
	v_mfma_f32_16x16x32_bf16 v[44:47], v[140:143], v[180:183], v[44:47]
	v_mfma_f32_16x16x32_bf16 v[40:43], v[148:151], v[180:183], v[40:43]
	v_mfma_f32_16x16x32_bf16 v[28:31], v[140:143], v[188:191], v[28:31]
	v_mfma_f32_16x16x32_bf16 v[24:27], v[148:151], v[188:191], v[24:27]
	v_mfma_f32_16x16x32_bf16 v[12:15], v[140:143], v[208:211], v[12:15]
	v_mfma_f32_16x16x32_bf16 v[8:11], v[148:151], v[208:211], v[8:11]
	v_mfma_f32_16x16x32_bf16 v[60:63], v[144:147], v[176:179], v[60:63]
	v_mfma_f32_16x16x32_bf16 v[56:59], v[152:155], v[176:179], v[56:59]
	v_mfma_f32_16x16x32_bf16 v[44:47], v[144:147], v[184:187], v[44:47]
	v_mfma_f32_16x16x32_bf16 v[40:43], v[152:155], v[184:187], v[40:43]
	v_mfma_f32_16x16x32_bf16 v[28:31], v[144:147], v[204:207], v[28:31]
	v_mfma_f32_16x16x32_bf16 v[24:27], v[152:155], v[204:207], v[24:27]
	v_mfma_f32_16x16x32_bf16 v[12:15], v[144:147], v[212:215], v[12:15]
	v_mfma_f32_16x16x32_bf16 v[8:11], v[152:155], v[212:215], v[8:11]
	v_mfma_f32_16x16x32_bf16 v[52:55], v[156:159], v[172:175], v[52:55]
	v_mfma_f32_16x16x32_bf16 v[48:51], v[164:167], v[172:175], v[48:51]
	v_mfma_f32_16x16x32_bf16 v[36:39], v[156:159], v[180:183], v[36:39]
	v_mfma_f32_16x16x32_bf16 v[32:35], v[164:167], v[180:183], v[32:35]
	v_mfma_f32_16x16x32_bf16 v[20:23], v[156:159], v[188:191], v[20:23]
	v_mfma_f32_16x16x32_bf16 v[16:19], v[164:167], v[188:191], v[16:19]
	v_mfma_f32_16x16x32_bf16 v[4:7], v[156:159], v[208:211], v[4:7]
	v_mfma_f32_16x16x32_bf16 v[0:3], v[164:167], v[208:211], v[0:3]
	v_mfma_f32_16x16x32_bf16 v[52:55], v[160:163], v[176:179], v[52:55]
	v_mfma_f32_16x16x32_bf16 v[48:51], v[168:171], v[176:179], v[48:51]
	v_mfma_f32_16x16x32_bf16 v[36:39], v[160:163], v[184:187], v[36:39]
	v_mfma_f32_16x16x32_bf16 v[32:35], v[168:171], v[184:187], v[32:35]
	v_mfma_f32_16x16x32_bf16 v[20:23], v[160:163], v[204:207], v[20:23]
	v_mfma_f32_16x16x32_bf16 v[16:19], v[168:171], v[204:207], v[16:19]
	v_mfma_f32_16x16x32_bf16 v[4:7], v[160:163], v[212:215], v[4:7]
	v_mfma_f32_16x16x32_bf16 v[0:3], v[168:171], v[212:215], v[0:3]
	s_setprio 0
	s_barrier
; #define PG8_STAGE(bufoff, gbase, voff) do { _Pragma("unroll") for (int _i = 0; _i < 2; ++_i) \
;         __builtin_amdgcn_global_load_lds((const unsigned*)((const char*)(gbase) + (voff)[_i]), (PG8_LAS unsigned*)(lds + (bufoff) + ldsw + _i * 8192), 16, 0, 0); } while (0)
; #define PG8_LDA(dst, b, h) do { _Pragma("unroll") for (int m = 0; m < 4; ++m) _Pragma("unroll") for (int k = 0; k < 2; ++k) dst[m][k] = *(const PG8_LAS bf16x8*)(lds + PG8_SA(b, h) + aoff + m * 2048 + k * 1024); } while (0)
; #define PG8_LDB(dst, b, h) do { _Pragma("unroll") for (int n = 0; n < 2; ++n) _Pragma("unroll") for (int k = 0; k < 2; ++k) dst[n][k] = *(const PG8_LAS bf16x8*)(lds + PG8_SB(b, h) + boff + n * 2048 + k * 1024); } while (0)
; #define PG8_MMA(ai, bj, At, Bt) do { __builtin_amdgcn_s_setprio(1); _Pragma("unroll") for (int m = 0; m < 4; ++m) _Pragma("unroll") for (int n = 0; n < 2; ++n) _Pragma("unroll") for (int k = 0; k < 2; ++k) \
;         acc[ai][bj][m][n] = __builtin_amdgcn_mfma_f32_16x16x32_bf16(Bt[n][k], At[m][k], acc[ai][bj][m][n], 0, 0, 0); __builtin_amdgcn_s_setprio(0); } while (0)
; #define PG8_WAIT_V(n) asm volatile("s_waitcnt vmcnt(" #n ")" ::: "memory")
; #define PG8_WAIT_L(n) asm volatile("s_waitcnt lgkmcnt(" #n ")" ::: "memory")
; #define PG8_BAR __builtin_amdgcn_s_barrier()
; #define PG8_SCHED __builtin_amdgcn_sched_barrier(0)
; template <class Epi, class Sched, bool ALIGN_EPI = false, bool SP2 = false>
; __device__ __forceinline__ void gemm_phase(PG8_LAS unsigned char* lds, const Gemm g, const Sched& S, const Epi& E) {
;     ...
;             PG8_STAGE(PG8_SA(0, 1), a2 + hstep, voffA); PG8_SCHED; PG8_LDB(B0, 1, 0); PG8_LDB(B1, 1, 1); PG8_SCHED; PG8_LDA(At, 1, 0);
;             PG8_WAIT_V(8); PG8_WAIT_L(0); PG8_BAR; PG8_MMA(0, 0, At, B0); PG8_MMA(0, 1, At, B1); PG8_BAR; PG8_SCHED;
;             PG8_STAGE(PG8_SB(1, 0), b3, voffB); PG8_STAGE(PG8_SB(1, 1), b3 + hstep, voffB); PG8_STAGE(PG8_SA(1, 0), a3, voffA); PG8_SCHED; PG8_LDA(At, 1, 1);
;             PG8_WAIT_V(8); PG8_WAIT_L(0); PG8_BAR; PG8_MMA(1, 0, At, B0); PG8_MMA(1, 1, At, B1); PG8_BAR; PG8_SCHED;
	s_add_u32 s24, s24, s8
	s_addc_u32 s25, s25, s9
	s_mov_b32 m0, s46
	v_lshl_add_u64 v[140:141], s[24:25], 0, v[128:129]
	global_load_lds_dwordx4 v[140:141], off
	v_lshl_add_u64 v[140:141], s[24:25], 0, v[130:131]
	s_mov_b32 m0, s48
	s_nop 0
	global_load_lds_dwordx4 v[140:141], off
	s_add_i32 s24, 0, 0x18000
	s_add_i32 s25, 0, 0x1c000
	v_add_u32_e32 v152, s24, v138
	v_add_u32_e32 v168, s25, v138
	ds_read_b128 v[140:143], v152
	ds_read_b128 v[144:147], v152 offset:1024
	ds_read_b128 v[148:151], v152 offset:2048
	ds_read_b128 v[152:155], v152 offset:3072
	ds_read_b128 v[156:159], v168
	ds_read_b128 v[160:163], v168 offset:1024
	ds_read_b128 v[164:167], v168 offset:2048
	ds_read_b128 v[168:171], v168 offset:3072
	ds_read_b128 v[172:175], v139 offset:32768
	ds_read_b128 v[176:179], v139 offset:33792
	ds_read_b128 v[180:183], v139 offset:34816
	ds_read_b128 v[184:187], v139 offset:35840
	ds_read_b128 v[188:191], v139 offset:36864
	ds_read_b128 v[204:207], v139 offset:37888
	ds_read_b128 v[208:211], v139 offset:38912
	ds_read_b128 v[212:215], v139 offset:39936
	s_waitcnt vmcnt(8)
	s_waitcnt lgkmcnt(0)
	s_setprio 1
	s_barrier
	v_mfma_f32_16x16x32_bf16 v[120:123], v[140:143], v[172:175], v[120:123]
	v_mfma_f32_16x16x32_bf16 v[124:127], v[148:151], v[172:175], v[124:127]
	v_mfma_f32_16x16x32_bf16 v[108:111], v[140:143], v[180:183], v[108:111]
	v_mfma_f32_16x16x32_bf16 v[104:107], v[148:151], v[180:183], v[104:107]
	v_mfma_f32_16x16x32_bf16 v[92:95], v[140:143], v[188:191], v[92:95]
	v_mfma_f32_16x16x32_bf16 v[88:91], v[148:151], v[188:191], v[88:91]
	v_mfma_f32_16x16x32_bf16 v[76:79], v[140:143], v[208:211], v[76:79]
	v_mfma_f32_16x16x32_bf16 v[72:75], v[148:151], v[208:211], v[72:75]
	v_mfma_f32_16x16x32_bf16 v[120:123], v[144:147], v[176:179], v[120:123]
	v_mfma_f32_16x16x32_bf16 v[124:127], v[152:155], v[176:179], v[124:127]
	v_mfma_f32_16x16x32_bf16 v[108:111], v[144:147], v[184:187], v[108:111]
	v_mfma_f32_16x16x32_bf16 v[104:107], v[152:155], v[184:187], v[104:107]
	v_mfma_f32_16x16x32_bf16 v[92:95], v[144:147], v[204:207], v[92:95]
	v_mfma_f32_16x16x32_bf16 v[88:91], v[152:155], v[204:207], v[88:91]
	v_mfma_f32_16x16x32_bf16 v[76:79], v[144:147], v[212:215], v[76:79]
	v_mfma_f32_16x16x32_bf16 v[72:75], v[152:155], v[212:215], v[72:75]
	v_mfma_f32_16x16x32_bf16 v[116:119], v[156:159], v[172:175], v[116:119]
	v_mfma_f32_16x16x32_bf16 v[112:115], v[164:167], v[172:175], v[112:115]
	v_mfma_f32_16x16x32_bf16 v[100:103], v[156:159], v[180:183], v[100:103]
	v_mfma_f32_16x16x32_bf16 v[96:99], v[164:167], v[180:183], v[96:99]
	v_mfma_f32_16x16x32_bf16 v[84:87], v[156:159], v[188:191], v[84:87]
	v_mfma_f32_16x16x32_bf16 v[80:83], v[164:167], v[188:191], v[80:83]
	v_mfma_f32_16x16x32_bf16 v[68:71], v[156:159], v[208:211], v[68:71]
	v_mfma_f32_16x16x32_bf16 v[64:67], v[164:167], v[208:211], v[64:67]
	v_mfma_f32_16x16x32_bf16 v[116:119], v[160:163], v[176:179], v[116:119]
	v_mfma_f32_16x16x32_bf16 v[112:115], v[168:171], v[176:179], v[112:115]
	v_mfma_f32_16x16x32_bf16 v[100:103], v[160:163], v[184:187], v[100:103]
	v_mfma_f32_16x16x32_bf16 v[96:99], v[168:171], v[184:187], v[96:99]
	v_mfma_f32_16x16x32_bf16 v[84:87], v[160:163], v[204:207], v[84:87]
	v_mfma_f32_16x16x32_bf16 v[80:83], v[168:171], v[204:207], v[80:83]
	v_mfma_f32_16x16x32_bf16 v[68:71], v[160:163], v[212:215], v[68:71]
	v_mfma_f32_16x16x32_bf16 v[64:67], v[168:171], v[212:215], v[64:67]
	s_setprio 0
	s_barrier
	s_add_i32 s24, s24, s34
	v_lshl_add_u64 v[172:173], v[216:217], 0, s[74:75]
	s_mov_b32 m0, s24
	s_nop 0
	global_load_lds_dwordx4 v[172:173], off
	v_lshl_add_u64 v[172:173], v[218:219], 0, s[74:75]
	s_add_i32 m0, s24, 0x2000
	s_add_i32 s24, s25, s34
	global_load_lds_dwordx4 v[172:173], off
	v_lshl_add_u64 v[172:173], v[220:221], 0, s[74:75]
	s_mov_b32 m0, s24
	s_nop 0
	global_load_lds_dwordx4 v[172:173], off
	v_lshl_add_u64 v[172:173], v[222:223], 0, s[74:75]
	s_add_i32 m0, s24, 0x2000
	s_nop 0
	global_load_lds_dwordx4 v[172:173], off
	v_lshl_add_u64 v[172:173], v[224:225], 0, s[74:75]
	s_mov_b32 m0, s53
	s_nop 0
	global_load_lds_dwordx4 v[172:173], off
	v_lshl_add_u64 v[172:173], v[226:227], 0, s[74:75]
	s_mov_b32 m0, s54
	s_nop 0
	global_load_lds_dwordx4 v[172:173], off
	ds_read_b128 v[172:175], v139 offset:49152
	ds_read_b128 v[176:179], v139 offset:50176
	ds_read_b128 v[180:183], v139 offset:51200
	ds_read_b128 v[184:187], v139 offset:52224
	ds_read_b128 v[188:191], v139 offset:53248
	ds_read_b128 v[204:207], v139 offset:54272
	ds_read_b128 v[208:211], v139 offset:55296
	ds_read_b128 v[212:215], v139 offset:56320
	s_waitcnt vmcnt(8)
	s_waitcnt lgkmcnt(0)
	s_setprio 1
	s_barrier
	v_mfma_f32_16x16x32_bf16 v[60:63], v[140:143], v[172:175], v[60:63]
	v_mfma_f32_16x16x32_bf16 v[56:59], v[148:151], v[172:175], v[56:59]
	v_mfma_f32_16x16x32_bf16 v[44:47], v[140:143], v[180:183], v[44:47]
	v_mfma_f32_16x16x32_bf16 v[40:43], v[148:151], v[180:183], v[40:43]
	v_mfma_f32_16x16x32_bf16 v[28:31], v[140:143], v[188:191], v[28:31]
	v_mfma_f32_16x16x32_bf16 v[24:27], v[148:151], v[188:191], v[24:27]
	v_mfma_f32_16x16x32_bf16 v[12:15], v[140:143], v[208:211], v[12:15]
	v_mfma_f32_16x16x32_bf16 v[8:11], v[148:151], v[208:211], v[8:11]
	v_mfma_f32_16x16x32_bf16 v[60:63], v[144:147], v[176:179], v[60:63]
	v_mfma_f32_16x16x32_bf16 v[56:59], v[152:155], v[176:179], v[56:59]
	v_mfma_f32_16x16x32_bf16 v[44:47], v[144:147], v[184:187], v[44:47]
	v_mfma_f32_16x16x32_bf16 v[40:43], v[152:155], v[184:187], v[40:43]
	v_mfma_f32_16x16x32_bf16 v[28:31], v[144:147], v[204:207], v[28:31]
	v_mfma_f32_16x16x32_bf16 v[24:27], v[152:155], v[204:207], v[24:27]
	v_mfma_f32_16x16x32_bf16 v[12:15], v[144:147], v[212:215], v[12:15]
	v_mfma_f32_16x16x32_bf16 v[8:11], v[152:155], v[212:215], v[8:11]
	v_mfma_f32_16x16x32_bf16 v[52:55], v[156:159], v[172:175], v[52:55]
	v_mfma_f32_16x16x32_bf16 v[48:51], v[164:167], v[172:175], v[48:51]
	v_mfma_f32_16x16x32_bf16 v[36:39], v[156:159], v[180:183], v[36:39]
	v_mfma_f32_16x16x32_bf16 v[32:35], v[164:167], v[180:183], v[32:35]
	v_mfma_f32_16x16x32_bf16 v[20:23], v[156:159], v[188:191], v[20:23]
	v_mfma_f32_16x16x32_bf16 v[16:19], v[164:167], v[188:191], v[16:19]
	v_mfma_f32_16x16x32_bf16 v[4:7], v[156:159], v[208:211], v[4:7]
	v_mfma_f32_16x16x32_bf16 v[0:3], v[164:167], v[208:211], v[0:3]
	v_mfma_f32_16x16x32_bf16 v[52:55], v[160:163], v[176:179], v[52:55]
	v_mfma_f32_16x16x32_bf16 v[48:51], v[168:171], v[176:179], v[48:51]
	v_mfma_f32_16x16x32_bf16 v[36:39], v[160:163], v[184:187], v[36:39]
	v_mfma_f32_16x16x32_bf16 v[32:35], v[168:171], v[184:187], v[32:35]
	v_mfma_f32_16x16x32_bf16 v[20:23], v[160:163], v[204:207], v[20:23]
	v_mfma_f32_16x16x32_bf16 v[16:19], v[168:171], v[204:207], v[16:19]
	v_mfma_f32_16x16x32_bf16 v[4:7], v[160:163], v[212:215], v[4:7]
	v_mfma_f32_16x16x32_bf16 v[0:3], v[168:171], v[212:215], v[0:3]
	s_setprio 0
	s_barrier
	s_add_u32 s22, s22, 0x100
	s_addc_u32 s23, s23, 0
	s_add_u32 s60, s60, 0x100
	s_addc_u32 s61, s61, 0
	s_cmp_ge_i32 s62, s51
	s_mov_b32 s24, s62
	s_cbranch_scc0 .LBB0_1091
	.p2align	6

; template <class Epi, class Sched, bool ALIGN_EPI = false, bool SP2 = false>
; __device__ __forceinline__ void gemm_phase(PG8_LAS unsigned char* lds, const Gemm g, const Sched& S, const Epi& E) {
;     ...
;         const bool has_next = S.next(ui + 1, nxt);
;         const char* nA = has_next ? (const char*)g.A + (size_t)nxt.pm * tstep : cA; const char* nB = has_next ? (const char*)g.Bt + (size_t)nxt.pn * tstep : cB;
;         for (int t = 0; t < nt; t += 2) {
;             const bool last = (t == nt - 2);
;             const char* a1 = cA + (size_t)(t + 1) * kstep;
;             const char* a2 = last ? nA : cA + (size_t)(t + 2) * kstep; const char* b2 = last ? nB : cB + (size_t)(t + 2) * kstep;
;             const char* a3 = a2 + kstep; const char* b3 = b2 + kstep;
;     ...
; #pragma unroll
;         for (int a = 0; a < 2; ++a)
; #pragma unroll
;             for (int b = 0; b < 2; ++b)
; #pragma unroll
;                 for (int m = 0; m < 4; ++m)
; #pragma unroll
;                     for (int n = 0; n < 2; ++n) acc[a][b][m][n] = (f32x4){0.f, 0.f, 0.f, 0.f};
;         cur = nxt; cA = nA; cB = nB; ++ui; relax = Epi::LOADS_BEFORE_STORES && !Epi::AFTER_DRAIN && SP2;
.LBB0_1132:
	s_ashr_i32 s19, s18, 31
	s_lshl_b64 s[22:23], s[18:19], 19
	s_add_u32 s22, s6, s22
	s_addc_u32 s23, s7, s23
	s_and_b64 s[24:25], s[20:21], exec
	s_cselect_b32 s19, s23, s43
	s_cselect_b32 s27, s22, s42
	s_ashr_i32 s17, s16, 31
	s_lshl_b64 s[24:25], s[16:17], 19
	s_add_u32 s24, s44, s24
	s_addc_u32 s25, s46, s25
	s_and_b64 s[30:31], s[20:21], exec
	s_cselect_b32 s17, s25, s29
	s_cselect_b32 s34, s24, s28
	s_add_u32 s30, s42, 0x40080
	s_addc_u32 s31, s43, 0
	s_add_u32 s57, s28, 0x100
	v_mov_b32_e32 v0, 0
	v_lshl_add_u64 v[128:129], s[30:31], 0, v[156:157]
	v_lshl_add_u64 v[130:131], s[30:31], 0, v[158:159]
	s_addc_u32 s58, s29, 0
	s_mov_b32 s59, -2
	s_mov_b64 vcc, 0
	s_waitcnt lgkmcnt(0)
	v_mov_b32_e32 v1, v0
	v_mov_b32_e32 v2, v0
	v_mov_b32_e32 v3, v0
	v_mov_b32_e32 v4, v0
	v_mov_b32_e32 v5, v0
	v_mov_b32_e32 v6, v0
	v_mov_b32_e32 v7, v0
	v_mov_b32_e32 v16, v0
	v_mov_b32_e32 v17, v0
	v_mov_b32_e32 v18, v0
	v_mov_b32_e32 v19, v0
	v_mov_b32_e32 v20, v0
	v_mov_b32_e32 v21, v0
	v_mov_b32_e32 v22, v0
	v_mov_b32_e32 v23, v0
	v_mov_b32_e32 v32, v0
	v_mov_b32_e32 v33, v0
	v_mov_b32_e32 v34, v0
	v_mov_b32_e32 v35, v0
	v_mov_b32_e32 v36, v0
	v_mov_b32_e32 v37, v0
	v_mov_b32_e32 v38, v0
	v_mov_b32_e32 v39, v0
	v_mov_b32_e32 v48, v0
	v_mov_b32_e32 v49, v0
	v_mov_b32_e32 v50, v0
	v_mov_b32_e32 v51, v0
	v_mov_b32_e32 v52, v0
	v_mov_b32_e32 v53, v0
	v_mov_b32_e32 v54, v0
	v_mov_b32_e32 v55, v0
	v_mov_b32_e32 v8, v0
	v_mov_b32_e32 v9, v0
	v_mov_b32_e32 v10, v0
	v_mov_b32_e32 v11, v0
	v_mov_b32_e32 v12, v0
	v_mov_b32_e32 v13, v0
	v_mov_b32_e32 v14, v0
	v_mov_b32_e32 v15, v0
	v_mov_b32_e32 v24, v0
	v_mov_b32_e32 v25, v0
	v_mov_b32_e32 v26, v0
	v_mov_b32_e32 v27, v0
	v_mov_b32_e32 v28, v0
	v_mov_b32_e32 v29, v0
	v_mov_b32_e32 v30, v0
	v_mov_b32_e32 v31, v0
	v_mov_b32_e32 v40, v0
	v_mov_b32_e32 v41, v0
	v_mov_b32_e32 v42, v0
	v_mov_b32_e32 v43, v0
	v_mov_b32_e32 v44, v0
	v_mov_b32_e32 v45, v0
	v_mov_b32_e32 v46, v0
	v_mov_b32_e32 v47, v0
	v_mov_b32_e32 v56, v0
	v_mov_b32_e32 v57, v0
	v_mov_b32_e32 v58, v0
	v_mov_b32_e32 v59, v0
	v_mov_b32_e32 v60, v0
	v_mov_b32_e32 v61, v0
	v_mov_b32_e32 v62, v0
	v_mov_b32_e32 v63, v0
	v_mov_b32_e32 v64, v0
	v_mov_b32_e32 v65, v0
	v_mov_b32_e32 v66, v0
	v_mov_b32_e32 v67, v0
	v_mov_b32_e32 v68, v0
	v_mov_b32_e32 v69, v0
	v_mov_b32_e32 v70, v0
	v_mov_b32_e32 v71, v0
	v_mov_b32_e32 v80, v0
	v_mov_b32_e32 v81, v0
	v_mov_b32_e32 v82, v0
	v_mov_b32_e32 v83, v0
	v_mov_b32_e32 v84, v0
	v_mov_b32_e32 v85, v0
	v_mov_b32_e32 v86, v0
	v_mov_b32_e32 v87, v0
	v_mov_b32_e32 v96, v0
	v_mov_b32_e32 v97, v0
	v_mov_b32_e32 v98, v0
	v_mov_b32_e32 v99, v0
	v_mov_b32_e32 v100, v0
	v_mov_b32_e32 v101, v0
	v_mov_b32_e32 v102, v0
	v_mov_b32_e32 v103, v0
	v_mov_b32_e32 v112, v0
	v_mov_b32_e32 v113, v0
	v_mov_b32_e32 v114, v0
	v_mov_b32_e32 v115, v0
	v_mov_b32_e32 v116, v0
	v_mov_b32_e32 v117, v0
	v_mov_b32_e32 v118, v0
	v_mov_b32_e32 v119, v0
	v_mov_b32_e32 v72, v0
	v_mov_b32_e32 v73, v0
	v_mov_b32_e32 v74, v0
	v_mov_b32_e32 v75, v0
	v_mov_b32_e32 v76, v0
	v_mov_b32_e32 v77, v0
	v_mov_b32_e32 v78, v0
	v_mov_b32_e32 v79, v0
	v_mov_b32_e32 v88, v0
	v_mov_b32_e32 v89, v0
	v_mov_b32_e32 v90, v0
	v_mov_b32_e32 v91, v0
	v_mov_b32_e32 v92, v0
	v_mov_b32_e32 v93, v0
	v_mov_b32_e32 v94, v0
	v_mov_b32_e32 v95, v0
	v_mov_b32_e32 v104, v0
	v_mov_b32_e32 v105, v0
	v_mov_b32_e32 v106, v0
	v_mov_b32_e32 v107, v0
	v_mov_b32_e32 v108, v0
	v_mov_b32_e32 v109, v0
	v_mov_b32_e32 v110, v0
	v_mov_b32_e32 v111, v0
	v_mov_b32_e32 v120, v0
	v_mov_b32_e32 v121, v0
	v_mov_b32_e32 v122, v0
	v_mov_b32_e32 v123, v0
	v_mov_b32_e32 v124, v0
	v_mov_b32_e32 v125, v0
	v_mov_b32_e32 v126, v0
	v_mov_b32_e32 v127, v0
	.p2align	6

; #define PG8_STAGE(bufoff, gbase, voff) do { _Pragma("unroll") for (int _i = 0; _i < 2; ++_i) \
;         __builtin_amdgcn_global_load_lds((const unsigned*)((const char*)(gbase) + (voff)[_i]), (PG8_LAS unsigned*)(lds + (bufoff) + ldsw + _i * 8192), 16, 0, 0); } while (0)
; #define PG8_LDA(dst, b, h) do { _Pragma("unroll") for (int m = 0; m < 4; ++m) _Pragma("unroll") for (int k = 0; k < 2; ++k) dst[m][k] = *(const PG8_LAS bf16x8*)(lds + PG8_SA(b, h) + aoff + m * 2048 + k * 1024); } while (0)
; #define PG8_LDB(dst, b, h) do { _Pragma("unroll") for (int n = 0; n < 2; ++n) _Pragma("unroll") for (int k = 0; k < 2; ++k) dst[n][k] = *(const PG8_LAS bf16x8*)(lds + PG8_SB(b, h) + boff + n * 2048 + k * 1024); } while (0)
; #define PG8_MMA(ai, bj, At, Bt) do { __builtin_amdgcn_s_setprio(1); _Pragma("unroll") for (int m = 0; m < 4; ++m) _Pragma("unroll") for (int n = 0; n < 2; ++n) _Pragma("unroll") for (int k = 0; k < 2; ++k) \
;         acc[ai][bj][m][n] = __builtin_amdgcn_mfma_f32_16x16x32_bf16(Bt[n][k], At[m][k], acc[ai][bj][m][n], 0, 0, 0); __builtin_amdgcn_s_setprio(0); } while (0)
; #define PG8_WAIT_L(n) asm volatile("s_waitcnt lgkmcnt(" #n ")" ::: "memory")
; #define PG8_WAIT_V8_UNLESS(flag) asm volatile("s_cmp_lg_i32 %0, 0\n\ts_cbranch_scc1 .Lpg8rx%=\n\ts_waitcnt vmcnt(8)\n.Lpg8rx%=:" :: "s"(__builtin_amdgcn_readfirstlane(flag)) : "scc", "memory")
; #define PG8_BAR __builtin_amdgcn_s_barrier()
; #define PG8_SCHED __builtin_amdgcn_sched_barrier(0)
; template <class Epi, class Sched, bool ALIGN_EPI = false, bool SP2 = false>
; __device__ __forceinline__ void gemm_phase(PG8_LAS unsigned char* lds, const Gemm g, const Sched& S, const Epi& E) {
;     ...
;             PG8_STAGE(PG8_SA(1, 1), a1 + hstep, voffA); PG8_SCHED; PG8_LDB(B0, 0, 0); PG8_LDB(B1, 0, 1); PG8_SCHED; PG8_LDA(At, 0, 0);
;             PG8_WAIT_V8_UNLESS(rx); PG8_WAIT_L(0); PG8_BAR; PG8_MMA(0, 0, At, B0); PG8_MMA(0, 1, At, B1); PG8_BAR; PG8_SCHED;
;             PG8_STAGE(PG8_SB(0, 0), b2, voffB); PG8_STAGE(PG8_SB(0, 1), b2 + hstep, voffB); PG8_STAGE(PG8_SA(0, 0), a2, voffA); PG8_SCHED; PG8_LDA(At, 0, 1);
;             PG8_WAIT_V8_UNLESS(rx); PG8_WAIT_L(0); PG8_BAR; PG8_MMA(1, 0, At, B0); PG8_MMA(1, 1, At, B1); PG8_BAR; PG8_SCHED;
.Lpg8rx10:
	s_waitcnt lgkmcnt(0)
	s_setprio 1
	s_barrier
	v_mfma_f32_16x16x32_bf16 v[124:127], v[132:135], v[180:183], v[124:127]
	v_mfma_f32_16x16x32_bf16 v[120:123], v[140:143], v[180:183], v[120:123]
	v_mfma_f32_16x16x32_bf16 v[108:111], v[132:135], v[188:191], v[108:111]
	v_mfma_f32_16x16x32_bf16 v[104:107], v[140:143], v[188:191], v[104:107]
	v_mfma_f32_16x16x32_bf16 v[92:95], v[132:135], v[208:211], v[92:95]
	v_mfma_f32_16x16x32_bf16 v[88:91], v[140:143], v[208:211], v[88:91]
	v_mfma_f32_16x16x32_bf16 v[76:79], v[132:135], v[216:219], v[76:79]
	v_mfma_f32_16x16x32_bf16 v[72:75], v[140:143], v[216:219], v[72:75]
	v_mfma_f32_16x16x32_bf16 v[124:127], v[136:139], v[184:187], v[124:127]
	v_mfma_f32_16x16x32_bf16 v[120:123], v[144:147], v[184:187], v[120:123]
	v_mfma_f32_16x16x32_bf16 v[108:111], v[136:139], v[204:207], v[108:111]
	v_mfma_f32_16x16x32_bf16 v[104:107], v[144:147], v[204:207], v[104:107]
	v_mfma_f32_16x16x32_bf16 v[92:95], v[136:139], v[212:215], v[92:95]
	v_mfma_f32_16x16x32_bf16 v[88:91], v[144:147], v[212:215], v[88:91]
	v_mfma_f32_16x16x32_bf16 v[76:79], v[136:139], v[220:223], v[76:79]
	v_mfma_f32_16x16x32_bf16 v[72:75], v[144:147], v[220:223], v[72:75]
	v_mfma_f32_16x16x32_bf16 v[116:119], v[160:163], v[180:183], v[116:119]
	v_mfma_f32_16x16x32_bf16 v[112:115], v[168:171], v[180:183], v[112:115]
	v_mfma_f32_16x16x32_bf16 v[100:103], v[160:163], v[188:191], v[100:103]
	v_mfma_f32_16x16x32_bf16 v[96:99], v[168:171], v[188:191], v[96:99]
	v_mfma_f32_16x16x32_bf16 v[84:87], v[160:163], v[208:211], v[84:87]
	v_mfma_f32_16x16x32_bf16 v[80:83], v[168:171], v[208:211], v[80:83]
	v_mfma_f32_16x16x32_bf16 v[68:71], v[160:163], v[216:219], v[68:71]
	v_mfma_f32_16x16x32_bf16 v[64:67], v[168:171], v[216:219], v[64:67]
	v_mfma_f32_16x16x32_bf16 v[116:119], v[164:167], v[184:187], v[116:119]
	v_mfma_f32_16x16x32_bf16 v[112:115], v[176:179], v[184:187], v[112:115]
	v_mfma_f32_16x16x32_bf16 v[100:103], v[164:167], v[204:207], v[100:103]
	v_mfma_f32_16x16x32_bf16 v[96:99], v[176:179], v[204:207], v[96:99]
	v_mfma_f32_16x16x32_bf16 v[84:87], v[164:167], v[212:215], v[84:87]
	v_mfma_f32_16x16x32_bf16 v[80:83], v[176:179], v[212:215], v[80:83]
	v_mfma_f32_16x16x32_bf16 v[68:71], v[164:167], v[220:223], v[68:71]
	v_mfma_f32_16x16x32_bf16 v[64:67], v[176:179], v[220:223], v[64:67]
	s_setprio 0
	s_barrier
	ds_read_b128 v[180:183], v175 offset:16384
	ds_read_b128 v[184:187], v175 offset:17408
	ds_read_b128 v[188:191], v175 offset:18432
	ds_read_b128 v[204:207], v175 offset:19456
	ds_read_b128 v[208:211], v175 offset:20480
	ds_read_b128 v[212:215], v175 offset:21504
	ds_read_b128 v[216:219], v175 offset:22528
	ds_read_b128 v[220:223], v175 offset:23552
	s_add_u32 s60, s28, 0x40000
	s_addc_u32 s61, s29, 0
	s_add_i32 m0, s65, s35
	s_nop 0
	global_load_lds_dwordx4 v150, s[28:29]
	s_add_i32 m0, m0, 0x2000
	s_nop 0
	global_load_lds_dwordx4 v154, s[28:29]
	s_add_i32 m0, s66, s35
	s_nop 0
	global_load_lds_dwordx4 v150, s[60:61]
	s_add_i32 m0, m0, 0x2000
	s_nop 0
	global_load_lds_dwordx4 v154, s[60:61]
	s_mov_b32 m0, s41
	s_nop 0
	global_load_lds_dwordx4 v148, s[30:31]
	s_mov_b32 m0, s48
	s_nop 0
	global_load_lds_dwordx4 v152, s[30:31]
	s_cmp_lg_i32 s67, 0
	s_cbranch_scc1 .Lpg8rx11
	s_waitcnt vmcnt(8)
.Lpg8rx11:
	s_waitcnt lgkmcnt(0)
	s_setprio 1
	s_barrier
	v_mfma_f32_16x16x32_bf16 v[60:63], v[132:135], v[180:183], v[60:63]
	v_mfma_f32_16x16x32_bf16 v[56:59], v[140:143], v[180:183], v[56:59]
	v_mfma_f32_16x16x32_bf16 v[44:47], v[132:135], v[188:191], v[44:47]
	v_mfma_f32_16x16x32_bf16 v[40:43], v[140:143], v[188:191], v[40:43]
	v_mfma_f32_16x16x32_bf16 v[28:31], v[132:135], v[208:211], v[28:31]
	v_mfma_f32_16x16x32_bf16 v[24:27], v[140:143], v[208:211], v[24:27]
	v_mfma_f32_16x16x32_bf16 v[12:15], v[132:135], v[216:219], v[12:15]
	v_mfma_f32_16x16x32_bf16 v[8:11], v[140:143], v[216:219], v[8:11]
	v_mfma_f32_16x16x32_bf16 v[60:63], v[136:139], v[184:187], v[60:63]
	v_mfma_f32_16x16x32_bf16 v[56:59], v[144:147], v[184:187], v[56:59]
	v_mfma_f32_16x16x32_bf16 v[44:47], v[136:139], v[204:207], v[44:47]
	v_mfma_f32_16x16x32_bf16 v[40:43], v[144:147], v[204:207], v[40:43]
	v_mfma_f32_16x16x32_bf16 v[28:31], v[136:139], v[212:215], v[28:31]
	v_mfma_f32_16x16x32_bf16 v[24:27], v[144:147], v[212:215], v[24:27]
	v_mfma_f32_16x16x32_bf16 v[12:15], v[136:139], v[220:223], v[12:15]
	v_mfma_f32_16x16x32_bf16 v[8:11], v[144:147], v[220:223], v[8:11]
	v_mfma_f32_16x16x32_bf16 v[52:55], v[160:163], v[180:183], v[52:55]
	v_mfma_f32_16x16x32_bf16 v[48:51], v[168:171], v[180:183], v[48:51]
	v_mfma_f32_16x16x32_bf16 v[36:39], v[160:163], v[188:191], v[36:39]
	v_mfma_f32_16x16x32_bf16 v[32:35], v[168:171], v[188:191], v[32:35]
	v_mfma_f32_16x16x32_bf16 v[20:23], v[160:163], v[208:211], v[20:23]
	v_mfma_f32_16x16x32_bf16 v[16:19], v[168:171], v[208:211], v[16:19]
	v_mfma_f32_16x16x32_bf16 v[4:7], v[160:163], v[216:219], v[4:7]
	v_mfma_f32_16x16x32_bf16 v[0:3], v[168:171], v[216:219], v[0:3]
	v_mfma_f32_16x16x32_bf16 v[52:55], v[164:167], v[184:187], v[52:55]
	v_mfma_f32_16x16x32_bf16 v[48:51], v[176:179], v[184:187], v[48:51]
	v_mfma_f32_16x16x32_bf16 v[36:39], v[164:167], v[204:207], v[36:39]
	v_mfma_f32_16x16x32_bf16 v[32:35], v[176:179], v[204:207], v[32:35]
	v_mfma_f32_16x16x32_bf16 v[20:23], v[164:167], v[212:215], v[20:23]
	v_mfma_f32_16x16x32_bf16 v[16:19], v[176:179], v[212:215], v[16:19]
	v_mfma_f32_16x16x32_bf16 v[4:7], v[164:167], v[220:223], v[4:7]
	v_mfma_f32_16x16x32_bf16 v[0:3], v[176:179], v[220:223], v[0:3]
	s_setprio 0
	s_barrier
; #define PG8_STAGE(bufoff, gbase, voff) do { _Pragma("unroll") for (int _i = 0; _i < 2; ++_i) \
;         __builtin_amdgcn_global_load_lds((const unsigned*)((const char*)(gbase) + (voff)[_i]), (PG8_LAS unsigned*)(lds + (bufoff) + ldsw + _i * 8192), 16, 0, 0); } while (0)
; #define PG8_LDA(dst, b, h) do { _Pragma("unroll") for (int m = 0; m < 4; ++m) _Pragma("unroll") for (int k = 0; k < 2; ++k) dst[m][k] = *(const PG8_LAS bf16x8*)(lds + PG8_SA(b, h) + aoff + m * 2048 + k * 1024); } while (0)
; #define PG8_LDB(dst, b, h) do { _Pragma("unroll") for (int n = 0; n < 2; ++n) _Pragma("unroll") for (int k = 0; k < 2; ++k) dst[n][k] = *(const PG8_LAS bf16x8*)(lds + PG8_SB(b, h) + boff + n * 2048 + k * 1024); } while (0)
; #define PG8_MMA(ai, bj, At, Bt) do { __builtin_amdgcn_s_setprio(1); _Pragma("unroll") for (int m = 0; m < 4; ++m) _Pragma("unroll") for (int n = 0; n < 2; ++n) _Pragma("unroll") for (int k = 0; k < 2; ++k) \
;         acc[ai][bj][m][n] = __builtin_amdgcn_mfma_f32_16x16x32_bf16(Bt[n][k], At[m][k], acc[ai][bj][m][n], 0, 0, 0); __builtin_amdgcn_s_setprio(0); } while (0)
; #define PG8_WAIT_V(n) asm volatile("s_waitcnt vmcnt(" #n ")" ::: "memory")
; #define PG8_WAIT_L(n) asm volatile("s_waitcnt lgkmcnt(" #n ")" ::: "memory")
; #define PG8_BAR __builtin_amdgcn_s_barrier()
; #define PG8_SCHED __builtin_amdgcn_sched_barrier(0)
; template <class Epi, class Sched, bool ALIGN_EPI = false, bool SP2 = false>
; __device__ __forceinline__ void gemm_phase(PG8_LAS unsigned char* lds, const Gemm g, const Sched& S, const Epi& E) {
;     ...
;             PG8_STAGE(PG8_SA(0, 1), a2 + hstep, voffA); PG8_SCHED; PG8_LDB(B0, 1, 0); PG8_LDB(B1, 1, 1); PG8_SCHED; PG8_LDA(At, 1, 0);
;             PG8_WAIT_V(8); PG8_WAIT_L(0); PG8_BAR; PG8_MMA(0, 0, At, B0); PG8_MMA(0, 1, At, B1); PG8_BAR; PG8_SCHED;
;             PG8_STAGE(PG8_SB(1, 0), b3, voffB); PG8_STAGE(PG8_SB(1, 1), b3 + hstep, voffB); PG8_STAGE(PG8_SA(1, 0), a3, voffA); PG8_SCHED; PG8_LDA(At, 1, 1);
;             PG8_WAIT_V(8); PG8_WAIT_L(0); PG8_BAR; PG8_MMA(1, 0, At, B0); PG8_MMA(1, 1, At, B1); PG8_BAR; PG8_SCHED;
;     ...
;         if constexpr (ALIGN_EPI) { if (wr == 0) PG8_BAR; }
	s_mov_b64 s[98:99], s[30:31]
	s_add_u32 s100, s30, 0x40000
	s_addc_u32 s101, s31, 0
	s_add_i32 s30, 0, 0x18000
	s_add_i32 s31, 0, 0x1c000
	v_add_u32_e32 v144, s30, v174
	v_add_u32_e32 v176, s31, v174
	ds_read_b128 v[132:135], v144
	ds_read_b128 v[136:139], v144 offset:1024
	ds_read_b128 v[140:143], v144 offset:2048
	ds_read_b128 v[144:147], v144 offset:3072
	ds_read_b128 v[160:163], v176
	ds_read_b128 v[164:167], v176 offset:1024
	ds_read_b128 v[168:171], v176 offset:2048
	ds_read_b128 v[176:179], v176 offset:3072
	ds_read_b128 v[180:183], v175 offset:32768
	ds_read_b128 v[184:187], v175 offset:33792
	ds_read_b128 v[188:191], v175 offset:34816
	ds_read_b128 v[204:207], v175 offset:35840
	ds_read_b128 v[208:211], v175 offset:36864
	ds_read_b128 v[212:215], v175 offset:37888
	ds_read_b128 v[216:219], v175 offset:38912
	ds_read_b128 v[220:223], v175 offset:39936
	s_mov_b32 m0, s50
	s_nop 0
	global_load_lds_dwordx4 v148, s[100:101]
	s_mov_b32 m0, s51
	s_nop 0
	global_load_lds_dwordx4 v152, s[100:101]
	s_waitcnt vmcnt(8)
	s_waitcnt lgkmcnt(0)
	s_setprio 1
	s_barrier
	v_mfma_f32_16x16x32_bf16 v[124:127], v[132:135], v[180:183], v[124:127]
	v_mfma_f32_16x16x32_bf16 v[120:123], v[140:143], v[180:183], v[120:123]
	v_mfma_f32_16x16x32_bf16 v[108:111], v[132:135], v[188:191], v[108:111]
	v_mfma_f32_16x16x32_bf16 v[104:107], v[140:143], v[188:191], v[104:107]
	v_mfma_f32_16x16x32_bf16 v[92:95], v[132:135], v[208:211], v[92:95]
	v_mfma_f32_16x16x32_bf16 v[88:91], v[140:143], v[208:211], v[88:91]
	v_mfma_f32_16x16x32_bf16 v[76:79], v[132:135], v[216:219], v[76:79]
	v_mfma_f32_16x16x32_bf16 v[72:75], v[140:143], v[216:219], v[72:75]
	v_mfma_f32_16x16x32_bf16 v[124:127], v[136:139], v[184:187], v[124:127]
	v_mfma_f32_16x16x32_bf16 v[120:123], v[144:147], v[184:187], v[120:123]
	v_mfma_f32_16x16x32_bf16 v[108:111], v[136:139], v[204:207], v[108:111]
	v_mfma_f32_16x16x32_bf16 v[104:107], v[144:147], v[204:207], v[104:107]
	v_mfma_f32_16x16x32_bf16 v[92:95], v[136:139], v[212:215], v[92:95]
	v_mfma_f32_16x16x32_bf16 v[88:91], v[144:147], v[212:215], v[88:91]
	v_mfma_f32_16x16x32_bf16 v[76:79], v[136:139], v[220:223], v[76:79]
	v_mfma_f32_16x16x32_bf16 v[72:75], v[144:147], v[220:223], v[72:75]
	v_mfma_f32_16x16x32_bf16 v[116:119], v[160:163], v[180:183], v[116:119]
	v_mfma_f32_16x16x32_bf16 v[112:115], v[168:171], v[180:183], v[112:115]
	v_mfma_f32_16x16x32_bf16 v[100:103], v[160:163], v[188:191], v[100:103]
	v_mfma_f32_16x16x32_bf16 v[96:99], v[168:171], v[188:191], v[96:99]
	v_mfma_f32_16x16x32_bf16 v[84:87], v[160:163], v[208:211], v[84:87]
	v_mfma_f32_16x16x32_bf16 v[80:83], v[168:171], v[208:211], v[80:83]
	v_mfma_f32_16x16x32_bf16 v[68:71], v[160:163], v[216:219], v[68:71]
	v_mfma_f32_16x16x32_bf16 v[64:67], v[168:171], v[216:219], v[64:67]
	v_mfma_f32_16x16x32_bf16 v[116:119], v[164:167], v[184:187], v[116:119]
	v_mfma_f32_16x16x32_bf16 v[112:115], v[176:179], v[184:187], v[112:115]
	v_mfma_f32_16x16x32_bf16 v[100:103], v[164:167], v[204:207], v[100:103]
	v_mfma_f32_16x16x32_bf16 v[96:99], v[176:179], v[204:207], v[96:99]
	v_mfma_f32_16x16x32_bf16 v[84:87], v[164:167], v[212:215], v[84:87]
	v_mfma_f32_16x16x32_bf16 v[80:83], v[176:179], v[212:215], v[80:83]
	v_mfma_f32_16x16x32_bf16 v[68:71], v[164:167], v[220:223], v[68:71]
	v_mfma_f32_16x16x32_bf16 v[64:67], v[176:179], v[220:223], v[64:67]
	s_setprio 0
	s_barrier
	ds_read_b128 v[180:183], v175 offset:49152
	ds_read_b128 v[184:187], v175 offset:50176
	ds_read_b128 v[188:191], v175 offset:51200
	ds_read_b128 v[204:207], v175 offset:52224
	ds_read_b128 v[208:211], v175 offset:53248
	ds_read_b128 v[212:215], v175 offset:54272
	ds_read_b128 v[216:219], v175 offset:55296
	ds_read_b128 v[220:223], v175 offset:56320
	s_add_u32 s100, s28, 0x80
	s_addc_u32 s101, s29, 0
	s_add_u32 s28, s28, 0x40080
	s_addc_u32 s29, s29, 0
	s_add_u32 s98, s98, 0x80
	s_addc_u32 s99, s99, 0
	s_add_i32 m0, s30, s35
	s_nop 0
	global_load_lds_dwordx4 v150, s[100:101]
	s_add_i32 m0, m0, 0x2000
	s_nop 0
	global_load_lds_dwordx4 v154, s[100:101]
	s_add_i32 m0, s31, s35
	s_nop 0
	global_load_lds_dwordx4 v150, s[28:29]
	s_add_i32 m0, m0, 0x2000
	s_nop 0
	global_load_lds_dwordx4 v154, s[28:29]
	s_mov_b32 m0, s52
	s_nop 0
	global_load_lds_dwordx4 v148, s[98:99]
	s_mov_b32 m0, s53
	s_nop 0
	global_load_lds_dwordx4 v152, s[98:99]
	s_waitcnt vmcnt(8)
	s_waitcnt lgkmcnt(0)
	s_setprio 1
	s_barrier
	v_mfma_f32_16x16x32_bf16 v[60:63], v[132:135], v[180:183], v[60:63]
	v_mfma_f32_16x16x32_bf16 v[56:59], v[140:143], v[180:183], v[56:59]
	v_mfma_f32_16x16x32_bf16 v[44:47], v[132:135], v[188:191], v[44:47]
	v_mfma_f32_16x16x32_bf16 v[40:43], v[140:143], v[188:191], v[40:43]
	v_mfma_f32_16x16x32_bf16 v[28:31], v[132:135], v[208:211], v[28:31]
	v_mfma_f32_16x16x32_bf16 v[24:27], v[140:143], v[208:211], v[24:27]
	v_mfma_f32_16x16x32_bf16 v[12:15], v[132:135], v[216:219], v[12:15]
	v_mfma_f32_16x16x32_bf16 v[8:11], v[140:143], v[216:219], v[8:11]
	v_mfma_f32_16x16x32_bf16 v[60:63], v[136:139], v[184:187], v[60:63]
	v_mfma_f32_16x16x32_bf16 v[56:59], v[144:147], v[184:187], v[56:59]
	v_mfma_f32_16x16x32_bf16 v[44:47], v[136:139], v[204:207], v[44:47]
	v_mfma_f32_16x16x32_bf16 v[40:43], v[144:147], v[204:207], v[40:43]
	v_mfma_f32_16x16x32_bf16 v[28:31], v[136:139], v[212:215], v[28:31]
	v_mfma_f32_16x16x32_bf16 v[24:27], v[144:147], v[212:215], v[24:27]
	v_mfma_f32_16x16x32_bf16 v[12:15], v[136:139], v[220:223], v[12:15]
	v_mfma_f32_16x16x32_bf16 v[8:11], v[144:147], v[220:223], v[8:11]
	v_mfma_f32_16x16x32_bf16 v[52:55], v[160:163], v[180:183], v[52:55]
	v_mfma_f32_16x16x32_bf16 v[48:51], v[168:171], v[180:183], v[48:51]
	v_mfma_f32_16x16x32_bf16 v[36:39], v[160:163], v[188:191], v[36:39]
	v_mfma_f32_16x16x32_bf16 v[32:35], v[168:171], v[188:191], v[32:35]
	v_mfma_f32_16x16x32_bf16 v[20:23], v[160:163], v[208:211], v[20:23]
	v_mfma_f32_16x16x32_bf16 v[16:19], v[168:171], v[208:211], v[16:19]
	v_mfma_f32_16x16x32_bf16 v[4:7], v[160:163], v[216:219], v[4:7]
	v_mfma_f32_16x16x32_bf16 v[0:3], v[168:171], v[216:219], v[0:3]
	v_mfma_f32_16x16x32_bf16 v[52:55], v[164:167], v[184:187], v[52:55]
	v_mfma_f32_16x16x32_bf16 v[48:51], v[176:179], v[184:187], v[48:51]
	v_mfma_f32_16x16x32_bf16 v[36:39], v[164:167], v[204:207], v[36:39]
	v_mfma_f32_16x16x32_bf16 v[32:35], v[176:179], v[204:207], v[32:35]
	v_mfma_f32_16x16x32_bf16 v[20:23], v[164:167], v[212:215], v[20:23]
	v_mfma_f32_16x16x32_bf16 v[16:19], v[176:179], v[212:215], v[16:19]
	v_mfma_f32_16x16x32_bf16 v[4:7], v[164:167], v[220:223], v[4:7]
	v_mfma_f32_16x16x32_bf16 v[0:3], v[176:179], v[220:223], v[0:3]
	s_setprio 0
	s_barrier
	s_add_i32 s59, s59, 2
	s_add_u32 vcc_lo, vcc_lo, 0x100
	s_addc_u32 vcc_hi, vcc_hi, 0
	s_cmp_gt_u32 s59, 13
	s_cbranch_scc0 .LBB0_1133
	.p2align	6
	s_and_b64 vcc, exec, s[14:15]
	s_cbranch_vccz .LBB0_1136
	s_barrier
